# all peeled GEMM K-loops: LDS-DMA loads use SGPR base + 32-bit VGPR offset instead of per-load 64-bit VALU address adds
# speedup vs baseline: 1.0087x; 1.0032x over previous
.LBB0_318:
	s_ashr_i32 s15, s14, 31
	s_lshl_b64 s[16:17], s[14:15], 19
	s_add_u32 s16, s37, s16
	s_addc_u32 s17, s42, s17
	s_and_b64 s[18:19], s[6:7], exec
	s_cselect_b32 s9, s17, s25
	s_cselect_b32 s15, s16, s24
	s_ashr_i32 s13, s12, 31
	s_lshl_b64 s[18:19], s[12:13], 19
	s_add_u32 s18, s38, s18
	s_addc_u32 s19, s39, s19
	s_and_b64 s[26:27], s[6:7], exec
	s_cselect_b32 s13, s19, s23
	s_cselect_b32 s21, s18, s22
	s_add_u32 s44, s22, 0x100
	s_addc_u32 s62, s23, 0
	s_add_u32 s22, s24, 0x40080
	s_addc_u32 s23, s25, 0
	s_mov_b32 s63, -2
	s_add_u32 s24, s22, 0xfffc0080
	s_addc_u32 s25, s23, -1
	s_add_i32 s64, 0, 0x10000
	s_cmp_eq_u32 s63, 12
	s_cselect_b32 s27, s9, s25
	s_cselect_b32 s26, s15, s24
	s_cselect_b32 s25, s13, s62
	s_cselect_b32 s24, s21, s44
	s_add_i32 s68, 0, 0x14000
	v_add_u32_e32 v112, s64, v159
	v_add_u32_e32 v165, s68, v159
	ds_read_b128 v[96:99], v112
	ds_read_b128 v[100:103], v112 offset:1024
	ds_read_b128 v[108:111], v112 offset:2048
	ds_read_b128 v[112:115], v112 offset:3072
	ds_read_b128 v[154:157], v165
	ds_read_b128 v[166:169], v165 offset:1024
	ds_read_b128 v[170:173], v165 offset:2048
	ds_read_b128 v[182:185], v165 offset:3072
	s_add_i32 m0, s50, 0xc000
	ds_read_b128 v[186:189], v164
	ds_read_b128 v[190:193], v164 offset:1024
	ds_read_b128 v[194:197], v164 offset:2048
	ds_read_b128 v[198:201], v164 offset:3072
	ds_read_b128 v[202:205], v164 offset:4096
	ds_read_b128 v[206:209], v164 offset:5120
	ds_read_b128 v[210:213], v164 offset:6144
	ds_read_b128 v[228:231], v164 offset:7168
	global_load_lds_dwordx4 v152, s[22:23]
	s_add_i32 m0, s50, 0xe000
	s_nop 0
	global_load_lds_dwordx4 v150, s[22:23]
	s_waitcnt vmcnt(8)
	s_waitcnt lgkmcnt(0)
	s_barrier
	s_setprio 1
	v_mfma_f32_16x16x32_bf16 v[140:143], v[96:99], v[186:189], 0
	v_mfma_f32_16x16x32_bf16 v[136:139], v[108:111], v[186:189], 0
	v_mfma_f32_16x16x32_bf16 v[124:127], v[96:99], v[194:197], 0
	v_mfma_f32_16x16x32_bf16 v[120:123], v[108:111], v[194:197], 0
	v_mfma_f32_16x16x32_bf16 v[92:95], v[96:99], v[202:205], 0
	v_mfma_f32_16x16x32_bf16 v[88:91], v[108:111], v[202:205], 0
	v_mfma_f32_16x16x32_bf16 v[76:79], v[96:99], v[210:213], 0
	v_mfma_f32_16x16x32_bf16 v[72:75], v[108:111], v[210:213], 0
	v_mfma_f32_16x16x32_bf16 v[140:143], v[100:103], v[190:193], v[140:143]
	v_mfma_f32_16x16x32_bf16 v[136:139], v[112:115], v[190:193], v[136:139]
	v_mfma_f32_16x16x32_bf16 v[124:127], v[100:103], v[198:201], v[124:127]
	v_mfma_f32_16x16x32_bf16 v[120:123], v[112:115], v[198:201], v[120:123]
	v_mfma_f32_16x16x32_bf16 v[92:95], v[100:103], v[206:209], v[92:95]
	v_mfma_f32_16x16x32_bf16 v[88:91], v[112:115], v[206:209], v[88:91]
	v_mfma_f32_16x16x32_bf16 v[76:79], v[100:103], v[228:231], v[76:79]
	v_mfma_f32_16x16x32_bf16 v[72:75], v[112:115], v[228:231], v[72:75]
	v_mfma_f32_16x16x32_bf16 v[132:135], v[154:157], v[186:189], 0
	v_mfma_f32_16x16x32_bf16 v[128:131], v[170:173], v[186:189], 0
	v_mfma_f32_16x16x32_bf16 v[116:119], v[154:157], v[194:197], 0
	v_mfma_f32_16x16x32_bf16 v[104:107], v[170:173], v[194:197], 0
	v_mfma_f32_16x16x32_bf16 v[84:87], v[154:157], v[202:205], 0
	v_mfma_f32_16x16x32_bf16 v[80:83], v[170:173], v[202:205], 0
	v_mfma_f32_16x16x32_bf16 v[68:71], v[154:157], v[210:213], 0
	v_mfma_f32_16x16x32_bf16 v[64:67], v[170:173], v[210:213], 0
	v_mfma_f32_16x16x32_bf16 v[132:135], v[166:169], v[190:193], v[132:135]
	v_mfma_f32_16x16x32_bf16 v[128:131], v[182:185], v[190:193], v[128:131]
	v_mfma_f32_16x16x32_bf16 v[116:119], v[166:169], v[198:201], v[116:119]
	v_mfma_f32_16x16x32_bf16 v[104:107], v[182:185], v[198:201], v[104:107]
	s_setprio 2
	s_barrier
	v_mfma_f32_16x16x32_bf16 v[84:87], v[166:169], v[206:209], v[84:87]
	v_mfma_f32_16x16x32_bf16 v[80:83], v[182:185], v[206:209], v[80:83]
	v_mfma_f32_16x16x32_bf16 v[68:71], v[166:169], v[228:231], v[68:71]
	v_mfma_f32_16x16x32_bf16 v[64:67], v[182:185], v[228:231], v[64:67]
	s_setprio 0
	s_add_i32 s64, s64, s43
	s_add_u32 s94, s24, s34
	s_addc_u32 s95, s25, s35
	s_mov_b32 m0, s64
	ds_read_b128 v[186:189], v164 offset:16384
	ds_read_b128 v[190:193], v164 offset:17408
	ds_read_b128 v[194:197], v164 offset:18432
	ds_read_b128 v[198:201], v164 offset:19456
	ds_read_b128 v[202:205], v164 offset:20480
	ds_read_b128 v[206:209], v164 offset:21504
	ds_read_b128 v[210:213], v164 offset:22528
	ds_read_b128 v[228:231], v164 offset:23552
	global_load_lds_dwordx4 v176, s[24:25]
	s_add_i32 m0, s64, 0x2000
	s_add_u32 s64, s24, 0x40000
	s_addc_u32 s65, s25, 0
	s_add_i32 s68, s68, s43
	global_load_lds_dwordx4 v148, s[24:25]
	s_mov_b32 m0, s68
	s_nop 0
	global_load_lds_dwordx4 v176, s[64:65]
	s_add_i32 m0, s68, 0x2000
	s_nop 0
	global_load_lds_dwordx4 v148, s[64:65]
	s_add_u32 s98, s26, s34
	s_addc_u32 s99, s27, s35
	s_mov_b32 m0, s50
	s_nop 0
	global_load_lds_dwordx4 v144, s[26:27]
	s_mov_b32 m0, s51
	s_nop 0
	global_load_lds_dwordx4 v146, s[26:27]
	s_waitcnt vmcnt(8)
	s_waitcnt lgkmcnt(0)
	s_barrier
	s_setprio 1
	v_mfma_f32_16x16x32_bf16 v[60:63], v[96:99], v[186:189], 0
	v_mfma_f32_16x16x32_bf16 v[56:59], v[108:111], v[186:189], 0
	v_mfma_f32_16x16x32_bf16 v[44:47], v[96:99], v[194:197], 0
	v_mfma_f32_16x16x32_bf16 v[40:43], v[108:111], v[194:197], 0
	v_mfma_f32_16x16x32_bf16 v[28:31], v[96:99], v[202:205], 0
	v_mfma_f32_16x16x32_bf16 v[24:27], v[108:111], v[202:205], 0
	v_mfma_f32_16x16x32_bf16 v[12:15], v[96:99], v[210:213], 0
	v_mfma_f32_16x16x32_bf16 v[8:11], v[108:111], v[210:213], 0
	v_mfma_f32_16x16x32_bf16 v[60:63], v[100:103], v[190:193], v[60:63]
	v_mfma_f32_16x16x32_bf16 v[56:59], v[112:115], v[190:193], v[56:59]
	v_mfma_f32_16x16x32_bf16 v[44:47], v[100:103], v[198:201], v[44:47]
	v_mfma_f32_16x16x32_bf16 v[40:43], v[112:115], v[198:201], v[40:43]
	v_mfma_f32_16x16x32_bf16 v[28:31], v[100:103], v[206:209], v[28:31]
	v_mfma_f32_16x16x32_bf16 v[24:27], v[112:115], v[206:209], v[24:27]
	v_mfma_f32_16x16x32_bf16 v[12:15], v[100:103], v[228:231], v[12:15]
	v_mfma_f32_16x16x32_bf16 v[8:11], v[112:115], v[228:231], v[8:11]
	v_mfma_f32_16x16x32_bf16 v[52:55], v[154:157], v[186:189], 0
	v_mfma_f32_16x16x32_bf16 v[48:51], v[170:173], v[186:189], 0
	v_mfma_f32_16x16x32_bf16 v[36:39], v[154:157], v[194:197], 0
	v_mfma_f32_16x16x32_bf16 v[32:35], v[170:173], v[194:197], 0
	v_mfma_f32_16x16x32_bf16 v[20:23], v[154:157], v[202:205], 0
	v_mfma_f32_16x16x32_bf16 v[16:19], v[170:173], v[202:205], 0
	v_mfma_f32_16x16x32_bf16 v[4:7], v[154:157], v[210:213], 0
	v_mfma_f32_16x16x32_bf16 v[0:3], v[170:173], v[210:213], 0
	v_mfma_f32_16x16x32_bf16 v[52:55], v[166:169], v[190:193], v[52:55]
	v_mfma_f32_16x16x32_bf16 v[48:51], v[182:185], v[190:193], v[48:51]
	v_mfma_f32_16x16x32_bf16 v[36:39], v[166:169], v[198:201], v[36:39]
	v_mfma_f32_16x16x32_bf16 v[32:35], v[182:185], v[198:201], v[32:35]
	s_setprio 2
	s_barrier
	v_mfma_f32_16x16x32_bf16 v[20:23], v[166:169], v[206:209], v[20:23]
	v_mfma_f32_16x16x32_bf16 v[16:19], v[182:185], v[206:209], v[16:19]
	v_mfma_f32_16x16x32_bf16 v[4:7], v[166:169], v[228:231], v[4:7]
	v_mfma_f32_16x16x32_bf16 v[0:3], v[182:185], v[228:231], v[0:3]
	s_setprio 0
	s_add_i32 s64, 0, 0x18000
	s_add_i32 s65, 0, 0x1c000
	v_add_u32_e32 v112, s64, v159
	v_add_u32_e32 v165, s65, v159
	ds_read_b128 v[96:99], v112
	ds_read_b128 v[100:103], v112 offset:1024
	ds_read_b128 v[108:111], v112 offset:2048
	ds_read_b128 v[112:115], v112 offset:3072
	ds_read_b128 v[154:157], v165
	ds_read_b128 v[166:169], v165 offset:1024
	ds_read_b128 v[170:173], v165 offset:2048
	ds_read_b128 v[182:185], v165 offset:3072
	s_add_u32 s26, s26, 0x40000
	s_addc_u32 s27, s27, 0
	s_mov_b32 m0, s52
	ds_read_b128 v[186:189], v164 offset:32768
	ds_read_b128 v[190:193], v164 offset:33792
	ds_read_b128 v[194:197], v164 offset:34816
	ds_read_b128 v[198:201], v164 offset:35840
	ds_read_b128 v[202:205], v164 offset:36864
	ds_read_b128 v[206:209], v164 offset:37888
	ds_read_b128 v[210:213], v164 offset:38912
	ds_read_b128 v[228:231], v164 offset:39936
	global_load_lds_dwordx4 v144, s[26:27]
	s_mov_b32 m0, s53
	s_nop 0
	global_load_lds_dwordx4 v146, s[26:27]
	s_waitcnt vmcnt(8)
	s_waitcnt lgkmcnt(0)
	s_barrier
	s_setprio 1
	v_mfma_f32_16x16x32_bf16 v[140:143], v[96:99], v[186:189], v[140:143]
	v_mfma_f32_16x16x32_bf16 v[136:139], v[108:111], v[186:189], v[136:139]
	v_mfma_f32_16x16x32_bf16 v[124:127], v[96:99], v[194:197], v[124:127]
	v_mfma_f32_16x16x32_bf16 v[120:123], v[108:111], v[194:197], v[120:123]
	v_mfma_f32_16x16x32_bf16 v[92:95], v[96:99], v[202:205], v[92:95]
	v_mfma_f32_16x16x32_bf16 v[88:91], v[108:111], v[202:205], v[88:91]
	v_mfma_f32_16x16x32_bf16 v[76:79], v[96:99], v[210:213], v[76:79]
	v_mfma_f32_16x16x32_bf16 v[72:75], v[108:111], v[210:213], v[72:75]
	v_mfma_f32_16x16x32_bf16 v[140:143], v[100:103], v[190:193], v[140:143]
	v_mfma_f32_16x16x32_bf16 v[136:139], v[112:115], v[190:193], v[136:139]
	v_mfma_f32_16x16x32_bf16 v[124:127], v[100:103], v[198:201], v[124:127]
	v_mfma_f32_16x16x32_bf16 v[120:123], v[112:115], v[198:201], v[120:123]
	v_mfma_f32_16x16x32_bf16 v[92:95], v[100:103], v[206:209], v[92:95]
	v_mfma_f32_16x16x32_bf16 v[88:91], v[112:115], v[206:209], v[88:91]
	v_mfma_f32_16x16x32_bf16 v[76:79], v[100:103], v[228:231], v[76:79]
	v_mfma_f32_16x16x32_bf16 v[72:75], v[112:115], v[228:231], v[72:75]
	v_mfma_f32_16x16x32_bf16 v[132:135], v[154:157], v[186:189], v[132:135]
	v_mfma_f32_16x16x32_bf16 v[128:131], v[170:173], v[186:189], v[128:131]
	v_mfma_f32_16x16x32_bf16 v[116:119], v[154:157], v[194:197], v[116:119]
	v_mfma_f32_16x16x32_bf16 v[104:107], v[170:173], v[194:197], v[104:107]
	v_mfma_f32_16x16x32_bf16 v[84:87], v[154:157], v[202:205], v[84:87]
	v_mfma_f32_16x16x32_bf16 v[80:83], v[170:173], v[202:205], v[80:83]
	v_mfma_f32_16x16x32_bf16 v[68:71], v[154:157], v[210:213], v[68:71]
	v_mfma_f32_16x16x32_bf16 v[64:67], v[170:173], v[210:213], v[64:67]
	v_mfma_f32_16x16x32_bf16 v[132:135], v[166:169], v[190:193], v[132:135]
	v_mfma_f32_16x16x32_bf16 v[128:131], v[182:185], v[190:193], v[128:131]
	v_mfma_f32_16x16x32_bf16 v[116:119], v[166:169], v[198:201], v[116:119]
	v_mfma_f32_16x16x32_bf16 v[104:107], v[182:185], v[198:201], v[104:107]
	s_setprio 2
	s_barrier
	v_mfma_f32_16x16x32_bf16 v[84:87], v[166:169], v[206:209], v[84:87]
	v_mfma_f32_16x16x32_bf16 v[80:83], v[182:185], v[206:209], v[80:83]
	v_mfma_f32_16x16x32_bf16 v[68:71], v[166:169], v[228:231], v[68:71]
	v_mfma_f32_16x16x32_bf16 v[64:67], v[182:185], v[228:231], v[64:67]
	s_setprio 0
	s_add_i32 s26, s64, s43
	s_mov_b32 m0, s26
	ds_read_b128 v[186:189], v164 offset:49152
	ds_read_b128 v[190:193], v164 offset:50176
	ds_read_b128 v[194:197], v164 offset:51200
	ds_read_b128 v[198:201], v164 offset:52224
	ds_read_b128 v[202:205], v164 offset:53248
	ds_read_b128 v[206:209], v164 offset:54272
	ds_read_b128 v[210:213], v164 offset:55296
	ds_read_b128 v[228:231], v164 offset:56320
	global_load_lds_dwordx4 v176, s[94:95]
	s_add_i32 m0, s26, 0x2000
	s_add_u32 s24, s24, 0x40080
	s_addc_u32 s25, s25, 0
	s_add_i32 s26, s65, s43
	global_load_lds_dwordx4 v148, s[94:95]
	s_mov_b32 m0, s26
	s_nop 0
	global_load_lds_dwordx4 v176, s[24:25]
	s_add_i32 m0, s26, 0x2000
	s_nop 0
	global_load_lds_dwordx4 v148, s[24:25]
	s_mov_b32 m0, s57
	s_nop 0
	global_load_lds_dwordx4 v144, s[98:99]
	s_mov_b32 m0, s58
	s_nop 0
	global_load_lds_dwordx4 v146, s[98:99]
	s_waitcnt vmcnt(8)
	s_waitcnt lgkmcnt(0)
	s_barrier
	s_setprio 1
	v_mfma_f32_16x16x32_bf16 v[60:63], v[96:99], v[186:189], v[60:63]
	v_mfma_f32_16x16x32_bf16 v[56:59], v[108:111], v[186:189], v[56:59]
	v_mfma_f32_16x16x32_bf16 v[44:47], v[96:99], v[194:197], v[44:47]
	v_mfma_f32_16x16x32_bf16 v[40:43], v[108:111], v[194:197], v[40:43]
	v_mfma_f32_16x16x32_bf16 v[28:31], v[96:99], v[202:205], v[28:31]
	v_mfma_f32_16x16x32_bf16 v[24:27], v[108:111], v[202:205], v[24:27]
	v_mfma_f32_16x16x32_bf16 v[12:15], v[96:99], v[210:213], v[12:15]
	v_mfma_f32_16x16x32_bf16 v[8:11], v[108:111], v[210:213], v[8:11]
	v_mfma_f32_16x16x32_bf16 v[60:63], v[100:103], v[190:193], v[60:63]
	v_mfma_f32_16x16x32_bf16 v[56:59], v[112:115], v[190:193], v[56:59]
	v_mfma_f32_16x16x32_bf16 v[44:47], v[100:103], v[198:201], v[44:47]
	v_mfma_f32_16x16x32_bf16 v[40:43], v[112:115], v[198:201], v[40:43]
	v_mfma_f32_16x16x32_bf16 v[28:31], v[100:103], v[206:209], v[28:31]
	v_mfma_f32_16x16x32_bf16 v[24:27], v[112:115], v[206:209], v[24:27]
	v_mfma_f32_16x16x32_bf16 v[12:15], v[100:103], v[228:231], v[12:15]
	v_mfma_f32_16x16x32_bf16 v[8:11], v[112:115], v[228:231], v[8:11]
	v_mfma_f32_16x16x32_bf16 v[52:55], v[154:157], v[186:189], v[52:55]
	v_mfma_f32_16x16x32_bf16 v[48:51], v[170:173], v[186:189], v[48:51]
	v_mfma_f32_16x16x32_bf16 v[36:39], v[154:157], v[194:197], v[36:39]
	v_mfma_f32_16x16x32_bf16 v[32:35], v[170:173], v[194:197], v[32:35]
	v_mfma_f32_16x16x32_bf16 v[20:23], v[154:157], v[202:205], v[20:23]
	v_mfma_f32_16x16x32_bf16 v[16:19], v[170:173], v[202:205], v[16:19]
	v_mfma_f32_16x16x32_bf16 v[4:7], v[154:157], v[210:213], v[4:7]
	v_mfma_f32_16x16x32_bf16 v[0:3], v[170:173], v[210:213], v[0:3]
	v_mfma_f32_16x16x32_bf16 v[52:55], v[166:169], v[190:193], v[52:55]
	v_mfma_f32_16x16x32_bf16 v[48:51], v[182:185], v[190:193], v[48:51]
	v_mfma_f32_16x16x32_bf16 v[36:39], v[166:169], v[198:201], v[36:39]
	v_mfma_f32_16x16x32_bf16 v[32:35], v[182:185], v[198:201], v[32:35]
	s_setprio 2
	s_barrier
	v_mfma_f32_16x16x32_bf16 v[20:23], v[166:169], v[206:209], v[20:23]
	v_mfma_f32_16x16x32_bf16 v[16:19], v[182:185], v[206:209], v[16:19]
	v_mfma_f32_16x16x32_bf16 v[4:7], v[166:169], v[228:231], v[4:7]
	v_mfma_f32_16x16x32_bf16 v[0:3], v[182:185], v[228:231], v[0:3]
	s_setprio 0
	s_add_i32 s63, s63, 2
	s_add_u32 s44, s44, 0x100
	s_addc_u32 s62, s62, 0
	s_add_u32 s22, s22, 0x100
	s_addc_u32 s23, s23, 0
	s_cmp_gt_u32 s63, 13
	s_cbranch_scc1 .Lpeel_exit_0
.LBB0_319:
	s_add_u32 s24, s22, 0xfffc0080
	s_addc_u32 s25, s23, -1
	s_add_i32 s64, 0, 0x10000
	s_cmp_eq_u32 s63, 12
	s_cselect_b32 s27, s9, s25
	s_cselect_b32 s26, s15, s24
	s_cselect_b32 s25, s13, s62
	s_cselect_b32 s24, s21, s44
	s_add_i32 s68, 0, 0x14000
	v_add_u32_e32 v112, s64, v159
	v_add_u32_e32 v165, s68, v159
	ds_read_b128 v[96:99], v112
	ds_read_b128 v[100:103], v112 offset:1024
	ds_read_b128 v[108:111], v112 offset:2048
	ds_read_b128 v[112:115], v112 offset:3072
	ds_read_b128 v[154:157], v165
	ds_read_b128 v[166:169], v165 offset:1024
	ds_read_b128 v[170:173], v165 offset:2048
	ds_read_b128 v[182:185], v165 offset:3072
	s_add_i32 m0, s50, 0xc000
	ds_read_b128 v[186:189], v164
	ds_read_b128 v[190:193], v164 offset:1024
	ds_read_b128 v[194:197], v164 offset:2048
	ds_read_b128 v[198:201], v164 offset:3072
	ds_read_b128 v[202:205], v164 offset:4096
	ds_read_b128 v[206:209], v164 offset:5120
	ds_read_b128 v[210:213], v164 offset:6144
	ds_read_b128 v[228:231], v164 offset:7168
	global_load_lds_dwordx4 v152, s[22:23]
	s_add_i32 m0, s50, 0xe000
	s_nop 0
	global_load_lds_dwordx4 v150, s[22:23]
	s_waitcnt vmcnt(8)
	s_waitcnt lgkmcnt(0)
	s_barrier
	s_setprio 1
	v_mfma_f32_16x16x32_bf16 v[140:143], v[96:99], v[186:189], v[140:143]
	v_mfma_f32_16x16x32_bf16 v[136:139], v[108:111], v[186:189], v[136:139]
	v_mfma_f32_16x16x32_bf16 v[124:127], v[96:99], v[194:197], v[124:127]
	v_mfma_f32_16x16x32_bf16 v[120:123], v[108:111], v[194:197], v[120:123]
	v_mfma_f32_16x16x32_bf16 v[92:95], v[96:99], v[202:205], v[92:95]
	v_mfma_f32_16x16x32_bf16 v[88:91], v[108:111], v[202:205], v[88:91]
	v_mfma_f32_16x16x32_bf16 v[76:79], v[96:99], v[210:213], v[76:79]
	v_mfma_f32_16x16x32_bf16 v[72:75], v[108:111], v[210:213], v[72:75]
	v_mfma_f32_16x16x32_bf16 v[140:143], v[100:103], v[190:193], v[140:143]
	v_mfma_f32_16x16x32_bf16 v[136:139], v[112:115], v[190:193], v[136:139]
	v_mfma_f32_16x16x32_bf16 v[124:127], v[100:103], v[198:201], v[124:127]
	v_mfma_f32_16x16x32_bf16 v[120:123], v[112:115], v[198:201], v[120:123]
	v_mfma_f32_16x16x32_bf16 v[92:95], v[100:103], v[206:209], v[92:95]
	v_mfma_f32_16x16x32_bf16 v[88:91], v[112:115], v[206:209], v[88:91]
	v_mfma_f32_16x16x32_bf16 v[76:79], v[100:103], v[228:231], v[76:79]
	v_mfma_f32_16x16x32_bf16 v[72:75], v[112:115], v[228:231], v[72:75]
	v_mfma_f32_16x16x32_bf16 v[132:135], v[154:157], v[186:189], v[132:135]
	v_mfma_f32_16x16x32_bf16 v[128:131], v[170:173], v[186:189], v[128:131]
	v_mfma_f32_16x16x32_bf16 v[116:119], v[154:157], v[194:197], v[116:119]
	v_mfma_f32_16x16x32_bf16 v[104:107], v[170:173], v[194:197], v[104:107]
	v_mfma_f32_16x16x32_bf16 v[84:87], v[154:157], v[202:205], v[84:87]
	v_mfma_f32_16x16x32_bf16 v[80:83], v[170:173], v[202:205], v[80:83]
	v_mfma_f32_16x16x32_bf16 v[68:71], v[154:157], v[210:213], v[68:71]
	v_mfma_f32_16x16x32_bf16 v[64:67], v[170:173], v[210:213], v[64:67]
	v_mfma_f32_16x16x32_bf16 v[132:135], v[166:169], v[190:193], v[132:135]
	v_mfma_f32_16x16x32_bf16 v[128:131], v[182:185], v[190:193], v[128:131]
	v_mfma_f32_16x16x32_bf16 v[116:119], v[166:169], v[198:201], v[116:119]
	v_mfma_f32_16x16x32_bf16 v[104:107], v[182:185], v[198:201], v[104:107]
	s_setprio 2
	s_barrier
	v_mfma_f32_16x16x32_bf16 v[84:87], v[166:169], v[206:209], v[84:87]
	v_mfma_f32_16x16x32_bf16 v[80:83], v[182:185], v[206:209], v[80:83]
	v_mfma_f32_16x16x32_bf16 v[68:71], v[166:169], v[228:231], v[68:71]
	v_mfma_f32_16x16x32_bf16 v[64:67], v[182:185], v[228:231], v[64:67]
	s_setprio 0
	s_add_i32 s64, s64, s43
	s_add_u32 s94, s24, s34
	s_addc_u32 s95, s25, s35
	s_mov_b32 m0, s64
	ds_read_b128 v[186:189], v164 offset:16384
	ds_read_b128 v[190:193], v164 offset:17408
	ds_read_b128 v[194:197], v164 offset:18432
	ds_read_b128 v[198:201], v164 offset:19456
	ds_read_b128 v[202:205], v164 offset:20480
	ds_read_b128 v[206:209], v164 offset:21504
	ds_read_b128 v[210:213], v164 offset:22528
	ds_read_b128 v[228:231], v164 offset:23552
	global_load_lds_dwordx4 v176, s[24:25]
	s_add_i32 m0, s64, 0x2000
	s_add_u32 s64, s24, 0x40000
	s_addc_u32 s65, s25, 0
	s_add_i32 s68, s68, s43
	global_load_lds_dwordx4 v148, s[24:25]
	s_mov_b32 m0, s68
	s_nop 0
	global_load_lds_dwordx4 v176, s[64:65]
	s_add_i32 m0, s68, 0x2000
	s_nop 0
	global_load_lds_dwordx4 v148, s[64:65]
	s_add_u32 s98, s26, s34
	s_addc_u32 s99, s27, s35
	s_mov_b32 m0, s50
	s_nop 0
	global_load_lds_dwordx4 v144, s[26:27]
	s_mov_b32 m0, s51
	s_nop 0
	global_load_lds_dwordx4 v146, s[26:27]
	s_waitcnt vmcnt(8)
	s_waitcnt lgkmcnt(0)
	s_barrier
	s_setprio 1
	v_mfma_f32_16x16x32_bf16 v[60:63], v[96:99], v[186:189], v[60:63]
	v_mfma_f32_16x16x32_bf16 v[56:59], v[108:111], v[186:189], v[56:59]
	v_mfma_f32_16x16x32_bf16 v[44:47], v[96:99], v[194:197], v[44:47]
	v_mfma_f32_16x16x32_bf16 v[40:43], v[108:111], v[194:197], v[40:43]
	v_mfma_f32_16x16x32_bf16 v[28:31], v[96:99], v[202:205], v[28:31]
	v_mfma_f32_16x16x32_bf16 v[24:27], v[108:111], v[202:205], v[24:27]
	v_mfma_f32_16x16x32_bf16 v[12:15], v[96:99], v[210:213], v[12:15]
	v_mfma_f32_16x16x32_bf16 v[8:11], v[108:111], v[210:213], v[8:11]
	v_mfma_f32_16x16x32_bf16 v[60:63], v[100:103], v[190:193], v[60:63]
	v_mfma_f32_16x16x32_bf16 v[56:59], v[112:115], v[190:193], v[56:59]
	v_mfma_f32_16x16x32_bf16 v[44:47], v[100:103], v[198:201], v[44:47]
	v_mfma_f32_16x16x32_bf16 v[40:43], v[112:115], v[198:201], v[40:43]
	v_mfma_f32_16x16x32_bf16 v[28:31], v[100:103], v[206:209], v[28:31]
	v_mfma_f32_16x16x32_bf16 v[24:27], v[112:115], v[206:209], v[24:27]
	v_mfma_f32_16x16x32_bf16 v[12:15], v[100:103], v[228:231], v[12:15]
	v_mfma_f32_16x16x32_bf16 v[8:11], v[112:115], v[228:231], v[8:11]
	v_mfma_f32_16x16x32_bf16 v[52:55], v[154:157], v[186:189], v[52:55]
	v_mfma_f32_16x16x32_bf16 v[48:51], v[170:173], v[186:189], v[48:51]
	v_mfma_f32_16x16x32_bf16 v[36:39], v[154:157], v[194:197], v[36:39]
	v_mfma_f32_16x16x32_bf16 v[32:35], v[170:173], v[194:197], v[32:35]
	v_mfma_f32_16x16x32_bf16 v[20:23], v[154:157], v[202:205], v[20:23]
	v_mfma_f32_16x16x32_bf16 v[16:19], v[170:173], v[202:205], v[16:19]
	v_mfma_f32_16x16x32_bf16 v[4:7], v[154:157], v[210:213], v[4:7]
	v_mfma_f32_16x16x32_bf16 v[0:3], v[170:173], v[210:213], v[0:3]
	v_mfma_f32_16x16x32_bf16 v[52:55], v[166:169], v[190:193], v[52:55]
	v_mfma_f32_16x16x32_bf16 v[48:51], v[182:185], v[190:193], v[48:51]
	v_mfma_f32_16x16x32_bf16 v[36:39], v[166:169], v[198:201], v[36:39]
	v_mfma_f32_16x16x32_bf16 v[32:35], v[182:185], v[198:201], v[32:35]
	s_setprio 2
	s_barrier
	v_mfma_f32_16x16x32_bf16 v[20:23], v[166:169], v[206:209], v[20:23]
	v_mfma_f32_16x16x32_bf16 v[16:19], v[182:185], v[206:209], v[16:19]
	v_mfma_f32_16x16x32_bf16 v[4:7], v[166:169], v[228:231], v[4:7]
	v_mfma_f32_16x16x32_bf16 v[0:3], v[182:185], v[228:231], v[0:3]
	s_setprio 0
	s_add_i32 s64, 0, 0x18000
	s_add_i32 s65, 0, 0x1c000
	v_add_u32_e32 v112, s64, v159
	v_add_u32_e32 v165, s65, v159
	ds_read_b128 v[96:99], v112
	ds_read_b128 v[100:103], v112 offset:1024
	ds_read_b128 v[108:111], v112 offset:2048
	ds_read_b128 v[112:115], v112 offset:3072
	ds_read_b128 v[154:157], v165
	ds_read_b128 v[166:169], v165 offset:1024
	ds_read_b128 v[170:173], v165 offset:2048
	ds_read_b128 v[182:185], v165 offset:3072
	s_add_u32 s26, s26, 0x40000
	s_addc_u32 s27, s27, 0
	s_mov_b32 m0, s52
	ds_read_b128 v[186:189], v164 offset:32768
	ds_read_b128 v[190:193], v164 offset:33792
	ds_read_b128 v[194:197], v164 offset:34816
	ds_read_b128 v[198:201], v164 offset:35840
	ds_read_b128 v[202:205], v164 offset:36864
	ds_read_b128 v[206:209], v164 offset:37888
	ds_read_b128 v[210:213], v164 offset:38912
	ds_read_b128 v[228:231], v164 offset:39936
	global_load_lds_dwordx4 v144, s[26:27]
	s_mov_b32 m0, s53
	s_nop 0
	global_load_lds_dwordx4 v146, s[26:27]
	s_waitcnt vmcnt(8)
	s_waitcnt lgkmcnt(0)
	s_barrier
	s_setprio 1
	v_mfma_f32_16x16x32_bf16 v[140:143], v[96:99], v[186:189], v[140:143]
	v_mfma_f32_16x16x32_bf16 v[136:139], v[108:111], v[186:189], v[136:139]
	v_mfma_f32_16x16x32_bf16 v[124:127], v[96:99], v[194:197], v[124:127]
	v_mfma_f32_16x16x32_bf16 v[120:123], v[108:111], v[194:197], v[120:123]
	v_mfma_f32_16x16x32_bf16 v[92:95], v[96:99], v[202:205], v[92:95]
	v_mfma_f32_16x16x32_bf16 v[88:91], v[108:111], v[202:205], v[88:91]
	v_mfma_f32_16x16x32_bf16 v[76:79], v[96:99], v[210:213], v[76:79]
	v_mfma_f32_16x16x32_bf16 v[72:75], v[108:111], v[210:213], v[72:75]
	v_mfma_f32_16x16x32_bf16 v[140:143], v[100:103], v[190:193], v[140:143]
	v_mfma_f32_16x16x32_bf16 v[136:139], v[112:115], v[190:193], v[136:139]
	v_mfma_f32_16x16x32_bf16 v[124:127], v[100:103], v[198:201], v[124:127]
	v_mfma_f32_16x16x32_bf16 v[120:123], v[112:115], v[198:201], v[120:123]
	v_mfma_f32_16x16x32_bf16 v[92:95], v[100:103], v[206:209], v[92:95]
	v_mfma_f32_16x16x32_bf16 v[88:91], v[112:115], v[206:209], v[88:91]
	v_mfma_f32_16x16x32_bf16 v[76:79], v[100:103], v[228:231], v[76:79]
	v_mfma_f32_16x16x32_bf16 v[72:75], v[112:115], v[228:231], v[72:75]
	v_mfma_f32_16x16x32_bf16 v[132:135], v[154:157], v[186:189], v[132:135]
	v_mfma_f32_16x16x32_bf16 v[128:131], v[170:173], v[186:189], v[128:131]
	v_mfma_f32_16x16x32_bf16 v[116:119], v[154:157], v[194:197], v[116:119]
	v_mfma_f32_16x16x32_bf16 v[104:107], v[170:173], v[194:197], v[104:107]
	v_mfma_f32_16x16x32_bf16 v[84:87], v[154:157], v[202:205], v[84:87]
	v_mfma_f32_16x16x32_bf16 v[80:83], v[170:173], v[202:205], v[80:83]
	v_mfma_f32_16x16x32_bf16 v[68:71], v[154:157], v[210:213], v[68:71]
	v_mfma_f32_16x16x32_bf16 v[64:67], v[170:173], v[210:213], v[64:67]
	v_mfma_f32_16x16x32_bf16 v[132:135], v[166:169], v[190:193], v[132:135]
	v_mfma_f32_16x16x32_bf16 v[128:131], v[182:185], v[190:193], v[128:131]
	v_mfma_f32_16x16x32_bf16 v[116:119], v[166:169], v[198:201], v[116:119]
	v_mfma_f32_16x16x32_bf16 v[104:107], v[182:185], v[198:201], v[104:107]
	s_setprio 2
	s_barrier
	v_mfma_f32_16x16x32_bf16 v[84:87], v[166:169], v[206:209], v[84:87]
	v_mfma_f32_16x16x32_bf16 v[80:83], v[182:185], v[206:209], v[80:83]
	v_mfma_f32_16x16x32_bf16 v[68:71], v[166:169], v[228:231], v[68:71]
	v_mfma_f32_16x16x32_bf16 v[64:67], v[182:185], v[228:231], v[64:67]
	s_setprio 0
	s_add_i32 s26, s64, s43
	s_mov_b32 m0, s26
	ds_read_b128 v[186:189], v164 offset:49152
	ds_read_b128 v[190:193], v164 offset:50176
	ds_read_b128 v[194:197], v164 offset:51200
	ds_read_b128 v[198:201], v164 offset:52224
	ds_read_b128 v[202:205], v164 offset:53248
	ds_read_b128 v[206:209], v164 offset:54272
	ds_read_b128 v[210:213], v164 offset:55296
	ds_read_b128 v[228:231], v164 offset:56320
	global_load_lds_dwordx4 v176, s[94:95]
	s_add_i32 m0, s26, 0x2000
	s_add_u32 s24, s24, 0x40080
	s_addc_u32 s25, s25, 0
	s_add_i32 s26, s65, s43
	global_load_lds_dwordx4 v148, s[94:95]
	s_mov_b32 m0, s26
	s_nop 0
	global_load_lds_dwordx4 v176, s[24:25]
	s_add_i32 m0, s26, 0x2000
	s_nop 0
	global_load_lds_dwordx4 v148, s[24:25]
	s_mov_b32 m0, s57
	s_nop 0
	global_load_lds_dwordx4 v144, s[98:99]
	s_mov_b32 m0, s58
	s_nop 0
	global_load_lds_dwordx4 v146, s[98:99]
	s_waitcnt vmcnt(8)
	s_waitcnt lgkmcnt(0)
	s_barrier
	s_setprio 1
	v_mfma_f32_16x16x32_bf16 v[60:63], v[96:99], v[186:189], v[60:63]
	v_mfma_f32_16x16x32_bf16 v[56:59], v[108:111], v[186:189], v[56:59]
	v_mfma_f32_16x16x32_bf16 v[44:47], v[96:99], v[194:197], v[44:47]
	v_mfma_f32_16x16x32_bf16 v[40:43], v[108:111], v[194:197], v[40:43]
	v_mfma_f32_16x16x32_bf16 v[28:31], v[96:99], v[202:205], v[28:31]
	v_mfma_f32_16x16x32_bf16 v[24:27], v[108:111], v[202:205], v[24:27]
	v_mfma_f32_16x16x32_bf16 v[12:15], v[96:99], v[210:213], v[12:15]
	v_mfma_f32_16x16x32_bf16 v[8:11], v[108:111], v[210:213], v[8:11]
	v_mfma_f32_16x16x32_bf16 v[60:63], v[100:103], v[190:193], v[60:63]
	v_mfma_f32_16x16x32_bf16 v[56:59], v[112:115], v[190:193], v[56:59]
	v_mfma_f32_16x16x32_bf16 v[44:47], v[100:103], v[198:201], v[44:47]
	v_mfma_f32_16x16x32_bf16 v[40:43], v[112:115], v[198:201], v[40:43]
	v_mfma_f32_16x16x32_bf16 v[28:31], v[100:103], v[206:209], v[28:31]
	v_mfma_f32_16x16x32_bf16 v[24:27], v[112:115], v[206:209], v[24:27]
	v_mfma_f32_16x16x32_bf16 v[12:15], v[100:103], v[228:231], v[12:15]
	v_mfma_f32_16x16x32_bf16 v[8:11], v[112:115], v[228:231], v[8:11]
	v_mfma_f32_16x16x32_bf16 v[52:55], v[154:157], v[186:189], v[52:55]
	v_mfma_f32_16x16x32_bf16 v[48:51], v[170:173], v[186:189], v[48:51]
	v_mfma_f32_16x16x32_bf16 v[36:39], v[154:157], v[194:197], v[36:39]
	v_mfma_f32_16x16x32_bf16 v[32:35], v[170:173], v[194:197], v[32:35]
	v_mfma_f32_16x16x32_bf16 v[20:23], v[154:157], v[202:205], v[20:23]
	v_mfma_f32_16x16x32_bf16 v[16:19], v[170:173], v[202:205], v[16:19]
	v_mfma_f32_16x16x32_bf16 v[4:7], v[154:157], v[210:213], v[4:7]
	v_mfma_f32_16x16x32_bf16 v[0:3], v[170:173], v[210:213], v[0:3]
	v_mfma_f32_16x16x32_bf16 v[52:55], v[166:169], v[190:193], v[52:55]
	v_mfma_f32_16x16x32_bf16 v[48:51], v[182:185], v[190:193], v[48:51]
	v_mfma_f32_16x16x32_bf16 v[36:39], v[166:169], v[198:201], v[36:39]
	v_mfma_f32_16x16x32_bf16 v[32:35], v[182:185], v[198:201], v[32:35]
	s_setprio 2
	s_barrier
	v_mfma_f32_16x16x32_bf16 v[20:23], v[166:169], v[206:209], v[20:23]
	v_mfma_f32_16x16x32_bf16 v[16:19], v[182:185], v[206:209], v[16:19]
	v_mfma_f32_16x16x32_bf16 v[4:7], v[166:169], v[228:231], v[4:7]
	v_mfma_f32_16x16x32_bf16 v[0:3], v[182:185], v[228:231], v[0:3]
	s_setprio 0
	s_add_i32 s63, s63, 2
	s_add_u32 s44, s44, 0x100
	s_addc_u32 s62, s62, 0
	s_add_u32 s22, s22, 0x100
	s_addc_u32 s23, s23, 0
	s_cmp_gt_u32 s63, 13
	s_cbranch_scc0 .LBB0_319

.LBB0_633:
	s_ashr_i32 s13, s12, 31
	s_lshl_b64 s[14:15], s[12:13], 19
	s_add_u32 s14, s37, s14
	s_addc_u32 s15, s42, s15
	s_and_b64 s[16:17], s[4:5], exec
	s_cselect_b32 s13, s15, s23
	s_cselect_b32 s19, s14, s22
	s_ashr_i32 s11, s10, 31
	s_lshl_b64 s[16:17], s[10:11], 19
	s_add_u32 s16, s29, s16
	s_addc_u32 s17, s43, s17
	s_and_b64 s[24:25], s[4:5], exec
	s_cselect_b32 s11, s17, s21
	s_cselect_b32 s60, s16, s20
	s_add_u32 s61, s20, 0x100
	s_addc_u32 s62, s21, 0
	s_add_u32 s20, s22, 0x40080
	s_addc_u32 s21, s23, 0
	s_mov_b32 s63, -2
	s_add_u32 s22, s20, 0xfffc0080
	s_addc_u32 s23, s21, -1
	s_add_i32 s64, 0, 0x10000
	s_cmp_eq_u32 s63, 12
	s_cselect_b32 s25, s13, s23
	s_cselect_b32 s24, s19, s22
	s_cselect_b32 s23, s11, s62
	s_cselect_b32 s22, s60, s61
	s_add_i32 s68, 0, 0x14000
	s_waitcnt lgkmcnt(0)
	s_lshl_b32 s74, s18, 8
	v_add_u32_e32 v178, s74, v182
	v_ashrrev_i32_e32 v179, 31, v178
	v_lshlrev_b64 v[178:179], 6, v[178:179]
	v_lshl_add_u64 v[178:179], s[70:71], 0, v[178:179]
	s_and_saveexec_b64 s[78:79], s[2:3]
	global_load_dwordx4 v[238:241], v[178:179], off
	global_load_dwordx4 v[242:245], v[178:179], off offset:16
	global_load_dwordx4 v[246:249], v[178:179], off offset:32
	global_load_dwordx4 v[250:253], v[178:179], off offset:48
	s_mov_b64 exec, s[78:79]
	v_add_u32_e32 v140, s64, v175
	v_add_u32_e32 v170, s68, v175
	ds_read_b128 v[128:131], v140
	ds_read_b128 v[132:135], v140 offset:1024
	ds_read_b128 v[136:139], v140 offset:2048
	ds_read_b128 v[140:143], v140 offset:3072
	ds_read_b128 v[144:147], v170
	ds_read_b128 v[162:165], v170 offset:1024
	ds_read_b128 v[166:169], v170 offset:2048
	ds_read_b128 v[170:173], v170 offset:3072
	s_add_i32 m0, s50, 0xc000
	ds_read_b128 v[186:189], v185
	ds_read_b128 v[190:193], v185 offset:1024
	ds_read_b128 v[194:197], v185 offset:2048
	ds_read_b128 v[198:201], v185 offset:3072
	ds_read_b128 v[202:205], v185 offset:4096
	ds_read_b128 v[206:209], v185 offset:5120
	ds_read_b128 v[210:213], v185 offset:6144
	ds_read_b128 v[228:231], v185 offset:7168
	global_load_lds_dwordx4 v160, s[20:21]
	s_add_i32 m0, s50, 0xe000
	s_nop 0
	global_load_lds_dwordx4 v158, s[20:21]
	s_waitcnt vmcnt(16)
	s_waitcnt lgkmcnt(0)
	s_barrier
	s_setprio 1
	v_mfma_f32_16x16x32_bf16 v[124:127], v[128:131], v[186:189], 0
	v_mfma_f32_16x16x32_bf16 v[120:123], v[136:139], v[186:189], 0
	v_mfma_f32_16x16x32_bf16 v[108:111], v[128:131], v[194:197], 0
	v_mfma_f32_16x16x32_bf16 v[104:107], v[136:139], v[194:197], 0
	v_mfma_f32_16x16x32_bf16 v[92:95], v[128:131], v[202:205], 0
	v_mfma_f32_16x16x32_bf16 v[88:91], v[136:139], v[202:205], 0
	v_mfma_f32_16x16x32_bf16 v[76:79], v[128:131], v[210:213], 0
	v_mfma_f32_16x16x32_bf16 v[72:75], v[136:139], v[210:213], 0
	v_mfma_f32_16x16x32_bf16 v[124:127], v[132:135], v[190:193], v[124:127]
	v_mfma_f32_16x16x32_bf16 v[120:123], v[140:143], v[190:193], v[120:123]
	v_mfma_f32_16x16x32_bf16 v[108:111], v[132:135], v[198:201], v[108:111]
	v_mfma_f32_16x16x32_bf16 v[104:107], v[140:143], v[198:201], v[104:107]
	v_mfma_f32_16x16x32_bf16 v[92:95], v[132:135], v[206:209], v[92:95]
	v_mfma_f32_16x16x32_bf16 v[88:91], v[140:143], v[206:209], v[88:91]
	v_mfma_f32_16x16x32_bf16 v[76:79], v[132:135], v[228:231], v[76:79]
	v_mfma_f32_16x16x32_bf16 v[72:75], v[140:143], v[228:231], v[72:75]
	v_mfma_f32_16x16x32_bf16 v[116:119], v[144:147], v[186:189], 0
	v_mfma_f32_16x16x32_bf16 v[112:115], v[166:169], v[186:189], 0
	v_mfma_f32_16x16x32_bf16 v[100:103], v[144:147], v[194:197], 0
	v_mfma_f32_16x16x32_bf16 v[96:99], v[166:169], v[194:197], 0
	v_mfma_f32_16x16x32_bf16 v[84:87], v[144:147], v[202:205], 0
	v_mfma_f32_16x16x32_bf16 v[80:83], v[166:169], v[202:205], 0
	v_mfma_f32_16x16x32_bf16 v[68:71], v[144:147], v[210:213], 0
	v_mfma_f32_16x16x32_bf16 v[64:67], v[166:169], v[210:213], 0
	v_mfma_f32_16x16x32_bf16 v[116:119], v[162:165], v[190:193], v[116:119]
	v_mfma_f32_16x16x32_bf16 v[112:115], v[170:173], v[190:193], v[112:115]
	v_mfma_f32_16x16x32_bf16 v[100:103], v[162:165], v[198:201], v[100:103]
	v_mfma_f32_16x16x32_bf16 v[96:99], v[170:173], v[198:201], v[96:99]
	s_setprio 2
	s_barrier
	v_mfma_f32_16x16x32_bf16 v[84:87], v[162:165], v[206:209], v[84:87]
	v_mfma_f32_16x16x32_bf16 v[80:83], v[170:173], v[206:209], v[80:83]
	v_mfma_f32_16x16x32_bf16 v[68:71], v[162:165], v[228:231], v[68:71]
	v_mfma_f32_16x16x32_bf16 v[64:67], v[170:173], v[228:231], v[64:67]
	s_setprio 0
	s_add_i32 s64, s64, s46
	s_add_u32 s94, s22, s34
	s_addc_u32 s95, s23, s35
	s_mov_b32 m0, s64
	ds_read_b128 v[186:189], v185 offset:16384
	ds_read_b128 v[190:193], v185 offset:17408
	ds_read_b128 v[194:197], v185 offset:18432
	ds_read_b128 v[198:201], v185 offset:19456
	ds_read_b128 v[202:205], v185 offset:20480
	ds_read_b128 v[206:209], v185 offset:21504
	ds_read_b128 v[210:213], v185 offset:22528
	ds_read_b128 v[228:231], v185 offset:23552
	global_load_lds_dwordx4 v152, s[22:23]
	s_add_i32 m0, s64, 0x2000
	s_add_u32 s64, s22, 0x40000
	s_addc_u32 s65, s23, 0
	s_add_i32 s68, s68, s46
	global_load_lds_dwordx4 v148, s[22:23]
	s_mov_b32 m0, s68
	s_nop 0
	global_load_lds_dwordx4 v152, s[64:65]
	s_add_i32 m0, s68, 0x2000
	s_nop 0
	global_load_lds_dwordx4 v148, s[64:65]
	s_add_u32 s98, s24, s34
	s_addc_u32 s99, s25, s35
	s_mov_b32 m0, s50
	s_nop 0
	global_load_lds_dwordx4 v154, s[24:25]
	s_mov_b32 m0, s51
	s_nop 0
	global_load_lds_dwordx4 v150, s[24:25]
	s_waitcnt vmcnt(8)
	s_waitcnt lgkmcnt(0)
	s_barrier
	s_setprio 1
	v_mfma_f32_16x16x32_bf16 v[60:63], v[128:131], v[186:189], 0
	v_mfma_f32_16x16x32_bf16 v[56:59], v[136:139], v[186:189], 0
	v_mfma_f32_16x16x32_bf16 v[48:51], v[128:131], v[194:197], 0
	v_mfma_f32_16x16x32_bf16 v[40:43], v[136:139], v[194:197], 0
	v_mfma_f32_16x16x32_bf16 v[32:35], v[128:131], v[202:205], 0
	v_mfma_f32_16x16x32_bf16 v[24:27], v[136:139], v[202:205], 0
	v_mfma_f32_16x16x32_bf16 v[16:19], v[128:131], v[210:213], 0
	v_mfma_f32_16x16x32_bf16 v[8:11], v[136:139], v[210:213], 0
	v_mfma_f32_16x16x32_bf16 v[60:63], v[132:135], v[190:193], v[60:63]
	v_mfma_f32_16x16x32_bf16 v[56:59], v[140:143], v[190:193], v[56:59]
	v_mfma_f32_16x16x32_bf16 v[48:51], v[132:135], v[198:201], v[48:51]
	v_mfma_f32_16x16x32_bf16 v[40:43], v[140:143], v[198:201], v[40:43]
	v_mfma_f32_16x16x32_bf16 v[32:35], v[132:135], v[206:209], v[32:35]
	v_mfma_f32_16x16x32_bf16 v[24:27], v[140:143], v[206:209], v[24:27]
	v_mfma_f32_16x16x32_bf16 v[16:19], v[132:135], v[228:231], v[16:19]
	v_mfma_f32_16x16x32_bf16 v[8:11], v[140:143], v[228:231], v[8:11]
	v_mfma_f32_16x16x32_bf16 v[52:55], v[144:147], v[186:189], 0
	v_mfma_f32_16x16x32_bf16 v[44:47], v[166:169], v[186:189], 0
	v_mfma_f32_16x16x32_bf16 v[36:39], v[144:147], v[194:197], 0
	v_mfma_f32_16x16x32_bf16 v[28:31], v[166:169], v[194:197], 0
	v_mfma_f32_16x16x32_bf16 v[20:23], v[144:147], v[202:205], 0
	v_mfma_f32_16x16x32_bf16 v[12:15], v[166:169], v[202:205], 0
	v_mfma_f32_16x16x32_bf16 v[4:7], v[144:147], v[210:213], 0
	v_mfma_f32_16x16x32_bf16 v[0:3], v[166:169], v[210:213], 0
	v_mfma_f32_16x16x32_bf16 v[52:55], v[162:165], v[190:193], v[52:55]
	v_mfma_f32_16x16x32_bf16 v[44:47], v[170:173], v[190:193], v[44:47]
	v_mfma_f32_16x16x32_bf16 v[36:39], v[162:165], v[198:201], v[36:39]
	v_mfma_f32_16x16x32_bf16 v[28:31], v[170:173], v[198:201], v[28:31]
	s_setprio 2
	s_barrier
	v_mfma_f32_16x16x32_bf16 v[20:23], v[162:165], v[206:209], v[20:23]
	v_mfma_f32_16x16x32_bf16 v[12:15], v[170:173], v[206:209], v[12:15]
	v_mfma_f32_16x16x32_bf16 v[4:7], v[162:165], v[228:231], v[4:7]
	v_mfma_f32_16x16x32_bf16 v[0:3], v[170:173], v[228:231], v[0:3]
	s_setprio 0
	s_and_saveexec_b64 s[78:79], s[2:3]
	v_add_f32_e32 v238, v238, v239
	v_add_f32_e32 v240, v240, v241
	v_add_f32_e32 v242, v242, v243
	v_add_f32_e32 v244, v244, v245
	v_add_f32_e32 v246, v246, v247
	v_add_f32_e32 v248, v248, v249
	v_add_f32_e32 v250, v250, v251
	v_add_f32_e32 v252, v252, v253
	v_add_f32_e32 v238, v238, v240
	v_add_f32_e32 v242, v242, v244
	v_add_f32_e32 v246, v246, v248
	v_add_f32_e32 v250, v250, v252
	v_add_f32_e32 v238, v238, v242
	v_add_f32_e32 v246, v246, v250
	v_add_f32_e32 v238, v238, v246
	v_fmamk_f32 v238, v238, 0x3a800000, v216
	v_rsq_f32_e32 v238, v238
	s_nop 0
	ds_write_b32 v183, v238
	s_mov_b64 exec, s[78:79]
	s_add_i32 s64, 0, 0x18000
	s_add_i32 s65, 0, 0x1c000
	v_add_u32_e32 v140, s64, v175
	v_add_u32_e32 v170, s65, v175
	ds_read_b128 v[128:131], v140
	ds_read_b128 v[132:135], v140 offset:1024
	ds_read_b128 v[136:139], v140 offset:2048
	ds_read_b128 v[140:143], v140 offset:3072
	ds_read_b128 v[144:147], v170
	ds_read_b128 v[162:165], v170 offset:1024
	ds_read_b128 v[166:169], v170 offset:2048
	ds_read_b128 v[170:173], v170 offset:3072
	s_add_u32 s24, s24, 0x40000
	s_addc_u32 s25, s25, 0
	s_mov_b32 m0, s52
	ds_read_b128 v[186:189], v185 offset:32768
	ds_read_b128 v[190:193], v185 offset:33792
	ds_read_b128 v[194:197], v185 offset:34816
	ds_read_b128 v[198:201], v185 offset:35840
	ds_read_b128 v[202:205], v185 offset:36864
	ds_read_b128 v[206:209], v185 offset:37888
	ds_read_b128 v[210:213], v185 offset:38912
	ds_read_b128 v[228:231], v185 offset:39936
	global_load_lds_dwordx4 v154, s[24:25]
	s_mov_b32 m0, s53
	s_nop 0
	global_load_lds_dwordx4 v150, s[24:25]
	s_waitcnt vmcnt(8)
	s_waitcnt lgkmcnt(0)
	s_barrier
	s_setprio 1
	v_mfma_f32_16x16x32_bf16 v[124:127], v[128:131], v[186:189], v[124:127]
	v_mfma_f32_16x16x32_bf16 v[120:123], v[136:139], v[186:189], v[120:123]
	v_mfma_f32_16x16x32_bf16 v[108:111], v[128:131], v[194:197], v[108:111]
	v_mfma_f32_16x16x32_bf16 v[104:107], v[136:139], v[194:197], v[104:107]
	v_mfma_f32_16x16x32_bf16 v[92:95], v[128:131], v[202:205], v[92:95]
	v_mfma_f32_16x16x32_bf16 v[88:91], v[136:139], v[202:205], v[88:91]
	v_mfma_f32_16x16x32_bf16 v[76:79], v[128:131], v[210:213], v[76:79]
	v_mfma_f32_16x16x32_bf16 v[72:75], v[136:139], v[210:213], v[72:75]
	v_mfma_f32_16x16x32_bf16 v[124:127], v[132:135], v[190:193], v[124:127]
	v_mfma_f32_16x16x32_bf16 v[120:123], v[140:143], v[190:193], v[120:123]
	v_mfma_f32_16x16x32_bf16 v[108:111], v[132:135], v[198:201], v[108:111]
	v_mfma_f32_16x16x32_bf16 v[104:107], v[140:143], v[198:201], v[104:107]
	v_mfma_f32_16x16x32_bf16 v[92:95], v[132:135], v[206:209], v[92:95]
	v_mfma_f32_16x16x32_bf16 v[88:91], v[140:143], v[206:209], v[88:91]
	v_mfma_f32_16x16x32_bf16 v[76:79], v[132:135], v[228:231], v[76:79]
	v_mfma_f32_16x16x32_bf16 v[72:75], v[140:143], v[228:231], v[72:75]
	v_mfma_f32_16x16x32_bf16 v[116:119], v[144:147], v[186:189], v[116:119]
	v_mfma_f32_16x16x32_bf16 v[112:115], v[166:169], v[186:189], v[112:115]
	v_mfma_f32_16x16x32_bf16 v[100:103], v[144:147], v[194:197], v[100:103]
	v_mfma_f32_16x16x32_bf16 v[96:99], v[166:169], v[194:197], v[96:99]
	v_mfma_f32_16x16x32_bf16 v[84:87], v[144:147], v[202:205], v[84:87]
	v_mfma_f32_16x16x32_bf16 v[80:83], v[166:169], v[202:205], v[80:83]
	v_mfma_f32_16x16x32_bf16 v[68:71], v[144:147], v[210:213], v[68:71]
	v_mfma_f32_16x16x32_bf16 v[64:67], v[166:169], v[210:213], v[64:67]
	v_mfma_f32_16x16x32_bf16 v[116:119], v[162:165], v[190:193], v[116:119]
	v_mfma_f32_16x16x32_bf16 v[112:115], v[170:173], v[190:193], v[112:115]
	v_mfma_f32_16x16x32_bf16 v[100:103], v[162:165], v[198:201], v[100:103]
	v_mfma_f32_16x16x32_bf16 v[96:99], v[170:173], v[198:201], v[96:99]
	s_setprio 2
	s_barrier
	v_mfma_f32_16x16x32_bf16 v[84:87], v[162:165], v[206:209], v[84:87]
	v_mfma_f32_16x16x32_bf16 v[80:83], v[170:173], v[206:209], v[80:83]
	v_mfma_f32_16x16x32_bf16 v[68:71], v[162:165], v[228:231], v[68:71]
	v_mfma_f32_16x16x32_bf16 v[64:67], v[170:173], v[228:231], v[64:67]
	s_setprio 0
	s_min_i32 s74, s18, 0x80
	s_ashr_i32 s74, s74, 3
	s_mul_hi_i32 s75, s74, 0x3000
	s_mulk_i32 s74, 0x3000
	s_add_u32 s74, s54, s74
	s_addc_u32 s75, s55, s75
	s_lshl_b32 s76, s44, 8
	s_ashr_i32 s77, s76, 31
	s_lshl_b64 s[76:77], s[76:77], 2
	s_add_u32 s74, s74, s76
	s_addc_u32 s75, s75, s77
	v_lshl_add_u64 v[178:179], s[74:75], 0, v[176:177]
	global_load_dwordx4 v[238:241], v[178:179], off
	global_load_dwordx4 v[242:245], v[178:179], off offset:16
	global_load_dwordx4 v[246:249], v[178:179], off offset:512
	global_load_dwordx4 v[250:253], v[178:179], off offset:528
	s_add_i32 s24, s64, s46
	s_mov_b32 m0, s24
	ds_read_b128 v[186:189], v185 offset:49152
	ds_read_b128 v[190:193], v185 offset:50176
	ds_read_b128 v[194:197], v185 offset:51200
	ds_read_b128 v[198:201], v185 offset:52224
	ds_read_b128 v[202:205], v185 offset:53248
	ds_read_b128 v[206:209], v185 offset:54272
	ds_read_b128 v[210:213], v185 offset:55296
	ds_read_b128 v[228:231], v185 offset:56320
	global_load_lds_dwordx4 v152, s[94:95]
	s_add_i32 m0, s24, 0x2000
	s_add_u32 s22, s22, 0x40080
	s_addc_u32 s23, s23, 0
	s_add_i32 s24, s65, s46
	global_load_lds_dwordx4 v148, s[94:95]
	s_mov_b32 m0, s24
	s_nop 0
	global_load_lds_dwordx4 v152, s[22:23]
	s_add_i32 m0, s24, 0x2000
	s_nop 0
	global_load_lds_dwordx4 v148, s[22:23]
	s_mov_b32 m0, s56
	s_nop 0
	global_load_lds_dwordx4 v154, s[98:99]
	s_mov_b32 m0, s57
	s_nop 0
	global_load_lds_dwordx4 v150, s[98:99]
	s_waitcnt vmcnt(12)
	s_waitcnt lgkmcnt(0)
	s_barrier
	s_setprio 1
	v_mfma_f32_16x16x32_bf16 v[60:63], v[128:131], v[186:189], v[60:63]
	v_mfma_f32_16x16x32_bf16 v[56:59], v[136:139], v[186:189], v[56:59]
	v_mfma_f32_16x16x32_bf16 v[48:51], v[128:131], v[194:197], v[48:51]
	v_mfma_f32_16x16x32_bf16 v[40:43], v[136:139], v[194:197], v[40:43]
	v_mfma_f32_16x16x32_bf16 v[32:35], v[128:131], v[202:205], v[32:35]
	v_mfma_f32_16x16x32_bf16 v[24:27], v[136:139], v[202:205], v[24:27]
	v_mfma_f32_16x16x32_bf16 v[16:19], v[128:131], v[210:213], v[16:19]
	v_mfma_f32_16x16x32_bf16 v[8:11], v[136:139], v[210:213], v[8:11]
	v_mfma_f32_16x16x32_bf16 v[60:63], v[132:135], v[190:193], v[60:63]
	v_mfma_f32_16x16x32_bf16 v[56:59], v[140:143], v[190:193], v[56:59]
	v_mfma_f32_16x16x32_bf16 v[48:51], v[132:135], v[198:201], v[48:51]
	v_mfma_f32_16x16x32_bf16 v[40:43], v[140:143], v[198:201], v[40:43]
	v_mfma_f32_16x16x32_bf16 v[32:35], v[132:135], v[206:209], v[32:35]
	v_mfma_f32_16x16x32_bf16 v[24:27], v[140:143], v[206:209], v[24:27]
	v_mfma_f32_16x16x32_bf16 v[16:19], v[132:135], v[228:231], v[16:19]
	v_mfma_f32_16x16x32_bf16 v[8:11], v[140:143], v[228:231], v[8:11]
	v_mfma_f32_16x16x32_bf16 v[52:55], v[144:147], v[186:189], v[52:55]
	v_mfma_f32_16x16x32_bf16 v[44:47], v[166:169], v[186:189], v[44:47]
	v_mfma_f32_16x16x32_bf16 v[36:39], v[144:147], v[194:197], v[36:39]
	v_mfma_f32_16x16x32_bf16 v[28:31], v[166:169], v[194:197], v[28:31]
	v_mfma_f32_16x16x32_bf16 v[20:23], v[144:147], v[202:205], v[20:23]
	v_mfma_f32_16x16x32_bf16 v[12:15], v[166:169], v[202:205], v[12:15]
	v_mfma_f32_16x16x32_bf16 v[4:7], v[144:147], v[210:213], v[4:7]
	v_mfma_f32_16x16x32_bf16 v[0:3], v[166:169], v[210:213], v[0:3]
	v_mfma_f32_16x16x32_bf16 v[52:55], v[162:165], v[190:193], v[52:55]
	v_mfma_f32_16x16x32_bf16 v[44:47], v[170:173], v[190:193], v[44:47]
	v_mfma_f32_16x16x32_bf16 v[36:39], v[162:165], v[198:201], v[36:39]
	v_mfma_f32_16x16x32_bf16 v[28:31], v[170:173], v[198:201], v[28:31]
	s_setprio 2
	s_barrier
	v_mfma_f32_16x16x32_bf16 v[20:23], v[162:165], v[206:209], v[20:23]
	v_mfma_f32_16x16x32_bf16 v[12:15], v[170:173], v[206:209], v[12:15]
	v_mfma_f32_16x16x32_bf16 v[4:7], v[162:165], v[228:231], v[4:7]
	v_mfma_f32_16x16x32_bf16 v[0:3], v[170:173], v[228:231], v[0:3]
	s_setprio 0
	s_add_i32 s63, s63, 2
	s_add_u32 s61, s61, 0x100
	s_addc_u32 s62, s62, 0
	s_add_u32 s20, s20, 0x100
	s_addc_u32 s21, s21, 0
	s_cmp_gt_u32 s63, 13
	s_cbranch_scc1 .Lpeel_exit_1
.LBB0_634:
	s_add_u32 s22, s20, 0xfffc0080
	s_addc_u32 s23, s21, -1
	s_add_i32 s64, 0, 0x10000
	s_cmp_eq_u32 s63, 12
	s_cselect_b32 s25, s13, s23
	s_cselect_b32 s24, s19, s22
	s_cselect_b32 s23, s11, s62
	s_cselect_b32 s22, s60, s61
	s_add_i32 s68, 0, 0x14000
	s_waitcnt lgkmcnt(0)
	v_add_u32_e32 v140, s64, v175
	v_add_u32_e32 v170, s68, v175
	ds_read_b128 v[128:131], v140
	ds_read_b128 v[132:135], v140 offset:1024
	ds_read_b128 v[136:139], v140 offset:2048
	ds_read_b128 v[140:143], v140 offset:3072
	ds_read_b128 v[144:147], v170
	ds_read_b128 v[162:165], v170 offset:1024
	ds_read_b128 v[166:169], v170 offset:2048
	ds_read_b128 v[170:173], v170 offset:3072
	s_add_i32 m0, s50, 0xc000
	ds_read_b128 v[186:189], v185
	ds_read_b128 v[190:193], v185 offset:1024
	ds_read_b128 v[194:197], v185 offset:2048
	ds_read_b128 v[198:201], v185 offset:3072
	ds_read_b128 v[202:205], v185 offset:4096
	ds_read_b128 v[206:209], v185 offset:5120
	ds_read_b128 v[210:213], v185 offset:6144
	ds_read_b128 v[228:231], v185 offset:7168
	global_load_lds_dwordx4 v160, s[20:21]
	s_add_i32 m0, s50, 0xe000
	s_nop 0
	global_load_lds_dwordx4 v158, s[20:21]
	s_waitcnt vmcnt(8)
	s_waitcnt lgkmcnt(0)
	s_barrier
	s_setprio 1
	v_mfma_f32_16x16x32_bf16 v[124:127], v[128:131], v[186:189], v[124:127]
	v_mfma_f32_16x16x32_bf16 v[120:123], v[136:139], v[186:189], v[120:123]
	v_mfma_f32_16x16x32_bf16 v[108:111], v[128:131], v[194:197], v[108:111]
	v_mfma_f32_16x16x32_bf16 v[104:107], v[136:139], v[194:197], v[104:107]
	v_mfma_f32_16x16x32_bf16 v[92:95], v[128:131], v[202:205], v[92:95]
	v_mfma_f32_16x16x32_bf16 v[88:91], v[136:139], v[202:205], v[88:91]
	v_mfma_f32_16x16x32_bf16 v[76:79], v[128:131], v[210:213], v[76:79]
	v_mfma_f32_16x16x32_bf16 v[72:75], v[136:139], v[210:213], v[72:75]
	v_mfma_f32_16x16x32_bf16 v[124:127], v[132:135], v[190:193], v[124:127]
	v_mfma_f32_16x16x32_bf16 v[120:123], v[140:143], v[190:193], v[120:123]
	v_mfma_f32_16x16x32_bf16 v[108:111], v[132:135], v[198:201], v[108:111]
	v_mfma_f32_16x16x32_bf16 v[104:107], v[140:143], v[198:201], v[104:107]
	v_mfma_f32_16x16x32_bf16 v[92:95], v[132:135], v[206:209], v[92:95]
	v_mfma_f32_16x16x32_bf16 v[88:91], v[140:143], v[206:209], v[88:91]
	v_mfma_f32_16x16x32_bf16 v[76:79], v[132:135], v[228:231], v[76:79]
	v_mfma_f32_16x16x32_bf16 v[72:75], v[140:143], v[228:231], v[72:75]
	v_mfma_f32_16x16x32_bf16 v[116:119], v[144:147], v[186:189], v[116:119]
	v_mfma_f32_16x16x32_bf16 v[112:115], v[166:169], v[186:189], v[112:115]
	v_mfma_f32_16x16x32_bf16 v[100:103], v[144:147], v[194:197], v[100:103]
	v_mfma_f32_16x16x32_bf16 v[96:99], v[166:169], v[194:197], v[96:99]
	v_mfma_f32_16x16x32_bf16 v[84:87], v[144:147], v[202:205], v[84:87]
	v_mfma_f32_16x16x32_bf16 v[80:83], v[166:169], v[202:205], v[80:83]
	v_mfma_f32_16x16x32_bf16 v[68:71], v[144:147], v[210:213], v[68:71]
	v_mfma_f32_16x16x32_bf16 v[64:67], v[166:169], v[210:213], v[64:67]
	v_mfma_f32_16x16x32_bf16 v[116:119], v[162:165], v[190:193], v[116:119]
	v_mfma_f32_16x16x32_bf16 v[112:115], v[170:173], v[190:193], v[112:115]
	v_mfma_f32_16x16x32_bf16 v[100:103], v[162:165], v[198:201], v[100:103]
	v_mfma_f32_16x16x32_bf16 v[96:99], v[170:173], v[198:201], v[96:99]
	s_setprio 2
	s_barrier
	v_mfma_f32_16x16x32_bf16 v[84:87], v[162:165], v[206:209], v[84:87]
	v_mfma_f32_16x16x32_bf16 v[80:83], v[170:173], v[206:209], v[80:83]
	v_mfma_f32_16x16x32_bf16 v[68:71], v[162:165], v[228:231], v[68:71]
	v_mfma_f32_16x16x32_bf16 v[64:67], v[170:173], v[228:231], v[64:67]
	s_setprio 0
	s_add_i32 s64, s64, s46
	s_add_u32 s94, s22, s34
	s_addc_u32 s95, s23, s35
	s_mov_b32 m0, s64
	ds_read_b128 v[186:189], v185 offset:16384
	ds_read_b128 v[190:193], v185 offset:17408
	ds_read_b128 v[194:197], v185 offset:18432
	ds_read_b128 v[198:201], v185 offset:19456
	ds_read_b128 v[202:205], v185 offset:20480
	ds_read_b128 v[206:209], v185 offset:21504
	ds_read_b128 v[210:213], v185 offset:22528
	ds_read_b128 v[228:231], v185 offset:23552
	global_load_lds_dwordx4 v152, s[22:23]
	s_add_i32 m0, s64, 0x2000
	s_add_u32 s64, s22, 0x40000
	s_addc_u32 s65, s23, 0
	s_add_i32 s68, s68, s46
	global_load_lds_dwordx4 v148, s[22:23]
	s_mov_b32 m0, s68
	s_nop 0
	global_load_lds_dwordx4 v152, s[64:65]
	s_add_i32 m0, s68, 0x2000
	s_nop 0
	global_load_lds_dwordx4 v148, s[64:65]
	s_add_u32 s98, s24, s34
	s_addc_u32 s99, s25, s35
	s_mov_b32 m0, s50
	s_nop 0
	global_load_lds_dwordx4 v154, s[24:25]
	s_mov_b32 m0, s51
	s_nop 0
	global_load_lds_dwordx4 v150, s[24:25]
	s_waitcnt vmcnt(8)
	s_waitcnt lgkmcnt(0)
	s_barrier
	s_setprio 1
	v_mfma_f32_16x16x32_bf16 v[60:63], v[128:131], v[186:189], v[60:63]
	v_mfma_f32_16x16x32_bf16 v[56:59], v[136:139], v[186:189], v[56:59]
	v_mfma_f32_16x16x32_bf16 v[48:51], v[128:131], v[194:197], v[48:51]
	v_mfma_f32_16x16x32_bf16 v[40:43], v[136:139], v[194:197], v[40:43]
	v_mfma_f32_16x16x32_bf16 v[32:35], v[128:131], v[202:205], v[32:35]
	v_mfma_f32_16x16x32_bf16 v[24:27], v[136:139], v[202:205], v[24:27]
	v_mfma_f32_16x16x32_bf16 v[16:19], v[128:131], v[210:213], v[16:19]
	v_mfma_f32_16x16x32_bf16 v[8:11], v[136:139], v[210:213], v[8:11]
	v_mfma_f32_16x16x32_bf16 v[60:63], v[132:135], v[190:193], v[60:63]
	v_mfma_f32_16x16x32_bf16 v[56:59], v[140:143], v[190:193], v[56:59]
	v_mfma_f32_16x16x32_bf16 v[48:51], v[132:135], v[198:201], v[48:51]
	v_mfma_f32_16x16x32_bf16 v[40:43], v[140:143], v[198:201], v[40:43]
	v_mfma_f32_16x16x32_bf16 v[32:35], v[132:135], v[206:209], v[32:35]
	v_mfma_f32_16x16x32_bf16 v[24:27], v[140:143], v[206:209], v[24:27]
	v_mfma_f32_16x16x32_bf16 v[16:19], v[132:135], v[228:231], v[16:19]
	v_mfma_f32_16x16x32_bf16 v[8:11], v[140:143], v[228:231], v[8:11]
	v_mfma_f32_16x16x32_bf16 v[52:55], v[144:147], v[186:189], v[52:55]
	v_mfma_f32_16x16x32_bf16 v[44:47], v[166:169], v[186:189], v[44:47]
	v_mfma_f32_16x16x32_bf16 v[36:39], v[144:147], v[194:197], v[36:39]
	v_mfma_f32_16x16x32_bf16 v[28:31], v[166:169], v[194:197], v[28:31]
	v_mfma_f32_16x16x32_bf16 v[20:23], v[144:147], v[202:205], v[20:23]
	v_mfma_f32_16x16x32_bf16 v[12:15], v[166:169], v[202:205], v[12:15]
	v_mfma_f32_16x16x32_bf16 v[4:7], v[144:147], v[210:213], v[4:7]
	v_mfma_f32_16x16x32_bf16 v[0:3], v[166:169], v[210:213], v[0:3]
	v_mfma_f32_16x16x32_bf16 v[52:55], v[162:165], v[190:193], v[52:55]
	v_mfma_f32_16x16x32_bf16 v[44:47], v[170:173], v[190:193], v[44:47]
	v_mfma_f32_16x16x32_bf16 v[36:39], v[162:165], v[198:201], v[36:39]
	v_mfma_f32_16x16x32_bf16 v[28:31], v[170:173], v[198:201], v[28:31]
	s_setprio 2
	s_barrier
	v_mfma_f32_16x16x32_bf16 v[20:23], v[162:165], v[206:209], v[20:23]
	v_mfma_f32_16x16x32_bf16 v[12:15], v[170:173], v[206:209], v[12:15]
	v_mfma_f32_16x16x32_bf16 v[4:7], v[162:165], v[228:231], v[4:7]
	v_mfma_f32_16x16x32_bf16 v[0:3], v[170:173], v[228:231], v[0:3]
	s_setprio 0
	s_add_i32 s64, 0, 0x18000
	s_add_i32 s65, 0, 0x1c000
	v_add_u32_e32 v140, s64, v175
	v_add_u32_e32 v170, s65, v175
	ds_read_b128 v[128:131], v140
	ds_read_b128 v[132:135], v140 offset:1024
	ds_read_b128 v[136:139], v140 offset:2048
	ds_read_b128 v[140:143], v140 offset:3072
	ds_read_b128 v[144:147], v170
	ds_read_b128 v[162:165], v170 offset:1024
	ds_read_b128 v[166:169], v170 offset:2048
	ds_read_b128 v[170:173], v170 offset:3072
	s_add_u32 s24, s24, 0x40000
	s_addc_u32 s25, s25, 0
	s_mov_b32 m0, s52
	ds_read_b128 v[186:189], v185 offset:32768
	ds_read_b128 v[190:193], v185 offset:33792
	ds_read_b128 v[194:197], v185 offset:34816
	ds_read_b128 v[198:201], v185 offset:35840
	ds_read_b128 v[202:205], v185 offset:36864
	ds_read_b128 v[206:209], v185 offset:37888
	ds_read_b128 v[210:213], v185 offset:38912
	ds_read_b128 v[228:231], v185 offset:39936
	global_load_lds_dwordx4 v154, s[24:25]
	s_mov_b32 m0, s53
	s_nop 0
	global_load_lds_dwordx4 v150, s[24:25]
	s_waitcnt vmcnt(8)
	s_waitcnt lgkmcnt(0)
	s_barrier
	s_setprio 1
	v_mfma_f32_16x16x32_bf16 v[124:127], v[128:131], v[186:189], v[124:127]
	v_mfma_f32_16x16x32_bf16 v[120:123], v[136:139], v[186:189], v[120:123]
	v_mfma_f32_16x16x32_bf16 v[108:111], v[128:131], v[194:197], v[108:111]
	v_mfma_f32_16x16x32_bf16 v[104:107], v[136:139], v[194:197], v[104:107]
	v_mfma_f32_16x16x32_bf16 v[92:95], v[128:131], v[202:205], v[92:95]
	v_mfma_f32_16x16x32_bf16 v[88:91], v[136:139], v[202:205], v[88:91]
	v_mfma_f32_16x16x32_bf16 v[76:79], v[128:131], v[210:213], v[76:79]
	v_mfma_f32_16x16x32_bf16 v[72:75], v[136:139], v[210:213], v[72:75]
	v_mfma_f32_16x16x32_bf16 v[124:127], v[132:135], v[190:193], v[124:127]
	v_mfma_f32_16x16x32_bf16 v[120:123], v[140:143], v[190:193], v[120:123]
	v_mfma_f32_16x16x32_bf16 v[108:111], v[132:135], v[198:201], v[108:111]
	v_mfma_f32_16x16x32_bf16 v[104:107], v[140:143], v[198:201], v[104:107]
	v_mfma_f32_16x16x32_bf16 v[92:95], v[132:135], v[206:209], v[92:95]
	v_mfma_f32_16x16x32_bf16 v[88:91], v[140:143], v[206:209], v[88:91]
	v_mfma_f32_16x16x32_bf16 v[76:79], v[132:135], v[228:231], v[76:79]
	v_mfma_f32_16x16x32_bf16 v[72:75], v[140:143], v[228:231], v[72:75]
	v_mfma_f32_16x16x32_bf16 v[116:119], v[144:147], v[186:189], v[116:119]
	v_mfma_f32_16x16x32_bf16 v[112:115], v[166:169], v[186:189], v[112:115]
	v_mfma_f32_16x16x32_bf16 v[100:103], v[144:147], v[194:197], v[100:103]
	v_mfma_f32_16x16x32_bf16 v[96:99], v[166:169], v[194:197], v[96:99]
	v_mfma_f32_16x16x32_bf16 v[84:87], v[144:147], v[202:205], v[84:87]
	v_mfma_f32_16x16x32_bf16 v[80:83], v[166:169], v[202:205], v[80:83]
	v_mfma_f32_16x16x32_bf16 v[68:71], v[144:147], v[210:213], v[68:71]
	v_mfma_f32_16x16x32_bf16 v[64:67], v[166:169], v[210:213], v[64:67]
	v_mfma_f32_16x16x32_bf16 v[116:119], v[162:165], v[190:193], v[116:119]
	v_mfma_f32_16x16x32_bf16 v[112:115], v[170:173], v[190:193], v[112:115]
	v_mfma_f32_16x16x32_bf16 v[100:103], v[162:165], v[198:201], v[100:103]
	v_mfma_f32_16x16x32_bf16 v[96:99], v[170:173], v[198:201], v[96:99]
	s_setprio 2
	s_barrier
	v_mfma_f32_16x16x32_bf16 v[84:87], v[162:165], v[206:209], v[84:87]
	v_mfma_f32_16x16x32_bf16 v[80:83], v[170:173], v[206:209], v[80:83]
	v_mfma_f32_16x16x32_bf16 v[68:71], v[162:165], v[228:231], v[68:71]
	v_mfma_f32_16x16x32_bf16 v[64:67], v[170:173], v[228:231], v[64:67]
	s_setprio 0
	s_add_i32 s24, s64, s46
	s_mov_b32 m0, s24
	ds_read_b128 v[186:189], v185 offset:49152
	ds_read_b128 v[190:193], v185 offset:50176
	ds_read_b128 v[194:197], v185 offset:51200
	ds_read_b128 v[198:201], v185 offset:52224
	ds_read_b128 v[202:205], v185 offset:53248
	ds_read_b128 v[206:209], v185 offset:54272
	ds_read_b128 v[210:213], v185 offset:55296
	ds_read_b128 v[228:231], v185 offset:56320
	global_load_lds_dwordx4 v152, s[94:95]
	s_add_i32 m0, s24, 0x2000
	s_add_u32 s22, s22, 0x40080
	s_addc_u32 s23, s23, 0
	s_add_i32 s24, s65, s46
	global_load_lds_dwordx4 v148, s[94:95]
	s_mov_b32 m0, s24
	s_nop 0
	global_load_lds_dwordx4 v152, s[22:23]
	s_add_i32 m0, s24, 0x2000
	s_nop 0
	global_load_lds_dwordx4 v148, s[22:23]
	s_mov_b32 m0, s56
	s_nop 0
	global_load_lds_dwordx4 v154, s[98:99]
	s_mov_b32 m0, s57
	s_nop 0
	global_load_lds_dwordx4 v150, s[98:99]
	s_waitcnt vmcnt(8)
	s_waitcnt lgkmcnt(0)
	s_barrier
	s_setprio 1
	v_mfma_f32_16x16x32_bf16 v[60:63], v[128:131], v[186:189], v[60:63]
	v_mfma_f32_16x16x32_bf16 v[56:59], v[136:139], v[186:189], v[56:59]
	v_mfma_f32_16x16x32_bf16 v[48:51], v[128:131], v[194:197], v[48:51]
	v_mfma_f32_16x16x32_bf16 v[40:43], v[136:139], v[194:197], v[40:43]
	v_mfma_f32_16x16x32_bf16 v[32:35], v[128:131], v[202:205], v[32:35]
	v_mfma_f32_16x16x32_bf16 v[24:27], v[136:139], v[202:205], v[24:27]
	v_mfma_f32_16x16x32_bf16 v[16:19], v[128:131], v[210:213], v[16:19]
	v_mfma_f32_16x16x32_bf16 v[8:11], v[136:139], v[210:213], v[8:11]
	v_mfma_f32_16x16x32_bf16 v[60:63], v[132:135], v[190:193], v[60:63]
	v_mfma_f32_16x16x32_bf16 v[56:59], v[140:143], v[190:193], v[56:59]
	v_mfma_f32_16x16x32_bf16 v[48:51], v[132:135], v[198:201], v[48:51]
	v_mfma_f32_16x16x32_bf16 v[40:43], v[140:143], v[198:201], v[40:43]
	v_mfma_f32_16x16x32_bf16 v[32:35], v[132:135], v[206:209], v[32:35]
	v_mfma_f32_16x16x32_bf16 v[24:27], v[140:143], v[206:209], v[24:27]
	v_mfma_f32_16x16x32_bf16 v[16:19], v[132:135], v[228:231], v[16:19]
	v_mfma_f32_16x16x32_bf16 v[8:11], v[140:143], v[228:231], v[8:11]
	v_mfma_f32_16x16x32_bf16 v[52:55], v[144:147], v[186:189], v[52:55]
	v_mfma_f32_16x16x32_bf16 v[44:47], v[166:169], v[186:189], v[44:47]
	v_mfma_f32_16x16x32_bf16 v[36:39], v[144:147], v[194:197], v[36:39]
	v_mfma_f32_16x16x32_bf16 v[28:31], v[166:169], v[194:197], v[28:31]
	v_mfma_f32_16x16x32_bf16 v[20:23], v[144:147], v[202:205], v[20:23]
	v_mfma_f32_16x16x32_bf16 v[12:15], v[166:169], v[202:205], v[12:15]
	v_mfma_f32_16x16x32_bf16 v[4:7], v[144:147], v[210:213], v[4:7]
	v_mfma_f32_16x16x32_bf16 v[0:3], v[166:169], v[210:213], v[0:3]
	v_mfma_f32_16x16x32_bf16 v[52:55], v[162:165], v[190:193], v[52:55]
	v_mfma_f32_16x16x32_bf16 v[44:47], v[170:173], v[190:193], v[44:47]
	v_mfma_f32_16x16x32_bf16 v[36:39], v[162:165], v[198:201], v[36:39]
	v_mfma_f32_16x16x32_bf16 v[28:31], v[170:173], v[198:201], v[28:31]
	s_setprio 2
	s_barrier
	v_mfma_f32_16x16x32_bf16 v[20:23], v[162:165], v[206:209], v[20:23]
	v_mfma_f32_16x16x32_bf16 v[12:15], v[170:173], v[206:209], v[12:15]
	v_mfma_f32_16x16x32_bf16 v[4:7], v[162:165], v[228:231], v[4:7]
	v_mfma_f32_16x16x32_bf16 v[0:3], v[170:173], v[228:231], v[0:3]
	s_setprio 0
	s_add_i32 s63, s63, 2
	s_add_u32 s61, s61, 0x100
	s_addc_u32 s62, s62, 0
	s_add_u32 s20, s20, 0x100
	s_addc_u32 s21, s21, 0
	s_cmp_gt_u32 s63, 13
	s_cbranch_scc0 .LBB0_634

.LBB0_768:
	s_add_u32 s44, s40, 0x100
	s_addc_u32 s55, s41, 0
	s_mov_b32 s92, -2
	s_add_u32 s40, s8, 0x100
	s_addc_u32 s41, s9, 0
	s_add_i32 s64, 0, 0x10000
	s_cmp_eq_u32 s92, 40
	s_cselect_b32 s53, s1, s41
	s_cselect_b32 s52, s0, s40
	s_cselect_b32 s51, s39, s55
	s_cselect_b32 s50, s38, s44
	s_add_i32 s65, 0, 0x14000
	v_add_u32_e32 v140, s64, v228
	v_add_u32_e32 v156, s65, v228
	ds_read_b128 v[128:131], v140
	ds_read_b128 v[132:135], v140 offset:1024
	ds_read_b128 v[136:139], v140 offset:2048
	ds_read_b128 v[140:143], v140 offset:3072
	ds_read_b128 v[144:147], v156
	ds_read_b128 v[148:151], v156 offset:1024
	ds_read_b128 v[152:155], v156 offset:2048
	ds_read_b128 v[156:159], v156 offset:3072
	s_add_i32 m0, s62, 0xc000
	ds_read_b128 v[160:163], v231
	ds_read_b128 v[164:167], v231 offset:1024
	ds_read_b128 v[186:189], v231 offset:2048
	ds_read_b128 v[190:193], v231 offset:3072
	ds_read_b128 v[194:197], v231 offset:4096
	ds_read_b128 v[198:201], v231 offset:5120
	ds_read_b128 v[202:205], v231 offset:6144
	ds_read_b128 v[206:209], v231 offset:7168
	global_load_lds_dwordx4 v184, s[8:9]
	s_add_i32 m0, s62, 0xe000
	s_nop 0
	global_load_lds_dwordx4 v182, s[8:9]
	s_waitcnt vmcnt(24)
	s_waitcnt lgkmcnt(0)
	s_barrier
	s_setprio 1
	v_mfma_f32_16x16x32_bf16 v[124:127], v[128:131], v[160:163], 0
	v_mfma_f32_16x16x32_bf16 v[120:123], v[136:139], v[160:163], 0
	v_mfma_f32_16x16x32_bf16 v[108:111], v[128:131], v[186:189], 0
	v_mfma_f32_16x16x32_bf16 v[104:107], v[136:139], v[186:189], 0
	v_mfma_f32_16x16x32_bf16 v[92:95], v[128:131], v[194:197], 0
	v_mfma_f32_16x16x32_bf16 v[88:91], v[136:139], v[194:197], 0
	v_mfma_f32_16x16x32_bf16 v[76:79], v[128:131], v[202:205], 0
	v_mfma_f32_16x16x32_bf16 v[72:75], v[136:139], v[202:205], 0
	v_mfma_f32_16x16x32_bf16 v[124:127], v[132:135], v[164:167], v[124:127]
	v_mfma_f32_16x16x32_bf16 v[120:123], v[140:143], v[164:167], v[120:123]
	v_mfma_f32_16x16x32_bf16 v[108:111], v[132:135], v[190:193], v[108:111]
	v_mfma_f32_16x16x32_bf16 v[104:107], v[140:143], v[190:193], v[104:107]
	v_mfma_f32_16x16x32_bf16 v[92:95], v[132:135], v[198:201], v[92:95]
	v_mfma_f32_16x16x32_bf16 v[88:91], v[140:143], v[198:201], v[88:91]
	v_mfma_f32_16x16x32_bf16 v[76:79], v[132:135], v[206:209], v[76:79]
	v_mfma_f32_16x16x32_bf16 v[72:75], v[140:143], v[206:209], v[72:75]
	v_mfma_f32_16x16x32_bf16 v[116:119], v[144:147], v[160:163], 0
	v_mfma_f32_16x16x32_bf16 v[112:115], v[152:155], v[160:163], 0
	v_mfma_f32_16x16x32_bf16 v[100:103], v[144:147], v[186:189], 0
	v_mfma_f32_16x16x32_bf16 v[96:99], v[152:155], v[186:189], 0
	v_mfma_f32_16x16x32_bf16 v[84:87], v[144:147], v[194:197], 0
	v_mfma_f32_16x16x32_bf16 v[80:83], v[152:155], v[194:197], 0
	v_mfma_f32_16x16x32_bf16 v[68:71], v[144:147], v[202:205], 0
	v_mfma_f32_16x16x32_bf16 v[64:67], v[152:155], v[202:205], 0
	v_mfma_f32_16x16x32_bf16 v[116:119], v[148:151], v[164:167], v[116:119]
	v_mfma_f32_16x16x32_bf16 v[112:115], v[156:159], v[164:167], v[112:115]
	v_mfma_f32_16x16x32_bf16 v[100:103], v[148:151], v[190:193], v[100:103]
	v_mfma_f32_16x16x32_bf16 v[96:99], v[156:159], v[190:193], v[96:99]
	s_setprio 2
	s_barrier
	v_mfma_f32_16x16x32_bf16 v[84:87], v[148:151], v[198:201], v[84:87]
	v_mfma_f32_16x16x32_bf16 v[80:83], v[156:159], v[198:201], v[80:83]
	v_mfma_f32_16x16x32_bf16 v[68:71], v[148:151], v[206:209], v[68:71]
	v_mfma_f32_16x16x32_bf16 v[64:67], v[156:159], v[206:209], v[64:67]
	s_setprio 0
	s_add_i32 s8, s64, s37
	s_add_u32 s98, s50, s34
	s_addc_u32 s99, s51, s35
	s_mov_b32 m0, s8
	ds_read_b128 v[160:163], v231 offset:16384
	ds_read_b128 v[164:167], v231 offset:17408
	ds_read_b128 v[186:189], v231 offset:18432
	ds_read_b128 v[190:193], v231 offset:19456
	ds_read_b128 v[194:197], v231 offset:20480
	ds_read_b128 v[198:201], v231 offset:21504
	ds_read_b128 v[202:205], v231 offset:22528
	ds_read_b128 v[206:209], v231 offset:23552
	global_load_lds_dwordx4 v170, s[50:51]
	s_add_i32 m0, s8, 0x2000
	s_add_u32 s8, s50, 0xb0000
	s_addc_u32 s9, s51, 0
	s_add_i32 s64, s65, s37
	global_load_lds_dwordx4 v174, s[50:51]
	s_mov_b32 m0, s64
	s_nop 0
	global_load_lds_dwordx4 v170, s[8:9]
	s_add_i32 m0, s64, 0x2000
	s_nop 0
	global_load_lds_dwordx4 v174, s[8:9]
	s_add_u32 s100, s52, s34
	s_addc_u32 s101, s53, s35
	s_mov_b32 m0, s62
	s_nop 0
	global_load_lds_dwordx4 v168, s[52:53]
	s_mov_b32 m0, s63
	s_nop 0
	global_load_lds_dwordx4 v172, s[52:53]
	s_waitcnt vmcnt(8)
	s_waitcnt lgkmcnt(0)
	s_barrier
	s_setprio 1
	v_mfma_f32_16x16x32_bf16 v[60:63], v[128:131], v[160:163], 0
	v_mfma_f32_16x16x32_bf16 v[56:59], v[136:139], v[160:163], 0
	v_mfma_f32_16x16x32_bf16 v[44:47], v[128:131], v[186:189], 0
	v_mfma_f32_16x16x32_bf16 v[40:43], v[136:139], v[186:189], 0
	v_mfma_f32_16x16x32_bf16 v[28:31], v[128:131], v[194:197], 0
	v_mfma_f32_16x16x32_bf16 v[24:27], v[136:139], v[194:197], 0
	v_mfma_f32_16x16x32_bf16 v[12:15], v[128:131], v[202:205], 0
	v_mfma_f32_16x16x32_bf16 v[8:11], v[136:139], v[202:205], 0
	v_mfma_f32_16x16x32_bf16 v[60:63], v[132:135], v[164:167], v[60:63]
	v_mfma_f32_16x16x32_bf16 v[56:59], v[140:143], v[164:167], v[56:59]
	v_mfma_f32_16x16x32_bf16 v[44:47], v[132:135], v[190:193], v[44:47]
	v_mfma_f32_16x16x32_bf16 v[40:43], v[140:143], v[190:193], v[40:43]
	v_mfma_f32_16x16x32_bf16 v[28:31], v[132:135], v[198:201], v[28:31]
	v_mfma_f32_16x16x32_bf16 v[24:27], v[140:143], v[198:201], v[24:27]
	v_mfma_f32_16x16x32_bf16 v[12:15], v[132:135], v[206:209], v[12:15]
	v_mfma_f32_16x16x32_bf16 v[8:11], v[140:143], v[206:209], v[8:11]
	v_mfma_f32_16x16x32_bf16 v[52:55], v[144:147], v[160:163], 0
	v_mfma_f32_16x16x32_bf16 v[48:51], v[152:155], v[160:163], 0
	v_mfma_f32_16x16x32_bf16 v[36:39], v[144:147], v[186:189], 0
	v_mfma_f32_16x16x32_bf16 v[32:35], v[152:155], v[186:189], 0
	v_mfma_f32_16x16x32_bf16 v[20:23], v[144:147], v[194:197], 0
	v_mfma_f32_16x16x32_bf16 v[16:19], v[152:155], v[194:197], 0
	v_mfma_f32_16x16x32_bf16 v[4:7], v[144:147], v[202:205], 0
	v_mfma_f32_16x16x32_bf16 v[0:3], v[152:155], v[202:205], 0
	v_mfma_f32_16x16x32_bf16 v[52:55], v[148:151], v[164:167], v[52:55]
	v_mfma_f32_16x16x32_bf16 v[48:51], v[156:159], v[164:167], v[48:51]
	v_mfma_f32_16x16x32_bf16 v[36:39], v[148:151], v[190:193], v[36:39]
	v_mfma_f32_16x16x32_bf16 v[32:35], v[156:159], v[190:193], v[32:35]
	s_setprio 2
	s_barrier
	v_mfma_f32_16x16x32_bf16 v[20:23], v[148:151], v[198:201], v[20:23]
	v_mfma_f32_16x16x32_bf16 v[16:19], v[156:159], v[198:201], v[16:19]
	v_mfma_f32_16x16x32_bf16 v[4:7], v[148:151], v[206:209], v[4:7]
	v_mfma_f32_16x16x32_bf16 v[0:3], v[156:159], v[206:209], v[0:3]
	s_setprio 0
	s_add_i32 s64, 0, 0x18000
	s_add_i32 s65, 0, 0x1c000
	v_add_u32_e32 v140, s64, v228
	v_add_u32_e32 v156, s65, v228
	ds_read_b128 v[128:131], v140
	ds_read_b128 v[132:135], v140 offset:1024
	ds_read_b128 v[136:139], v140 offset:2048
	ds_read_b128 v[140:143], v140 offset:3072
	ds_read_b128 v[144:147], v156
	ds_read_b128 v[148:151], v156 offset:1024
	ds_read_b128 v[152:155], v156 offset:2048
	ds_read_b128 v[156:159], v156 offset:3072
	s_add_u32 s8, s52, 0xb0000
	s_addc_u32 s9, s53, 0
	s_mov_b32 m0, s68
	ds_read_b128 v[160:163], v231 offset:32768
	ds_read_b128 v[164:167], v231 offset:33792
	ds_read_b128 v[186:189], v231 offset:34816
	ds_read_b128 v[190:193], v231 offset:35840
	ds_read_b128 v[194:197], v231 offset:36864
	ds_read_b128 v[198:201], v231 offset:37888
	ds_read_b128 v[202:205], v231 offset:38912
	ds_read_b128 v[206:209], v231 offset:39936
	global_load_lds_dwordx4 v168, s[8:9]
	s_mov_b32 m0, s69
	s_nop 0
	global_load_lds_dwordx4 v172, s[8:9]
	s_waitcnt vmcnt(8)
	s_waitcnt lgkmcnt(0)
	s_barrier
	s_setprio 1
	v_mfma_f32_16x16x32_bf16 v[124:127], v[128:131], v[160:163], v[124:127]
	v_mfma_f32_16x16x32_bf16 v[120:123], v[136:139], v[160:163], v[120:123]
	v_mfma_f32_16x16x32_bf16 v[108:111], v[128:131], v[186:189], v[108:111]
	v_mfma_f32_16x16x32_bf16 v[104:107], v[136:139], v[186:189], v[104:107]
	v_mfma_f32_16x16x32_bf16 v[92:95], v[128:131], v[194:197], v[92:95]
	v_mfma_f32_16x16x32_bf16 v[88:91], v[136:139], v[194:197], v[88:91]
	v_mfma_f32_16x16x32_bf16 v[76:79], v[128:131], v[202:205], v[76:79]
	v_mfma_f32_16x16x32_bf16 v[72:75], v[136:139], v[202:205], v[72:75]
	v_mfma_f32_16x16x32_bf16 v[124:127], v[132:135], v[164:167], v[124:127]
	v_mfma_f32_16x16x32_bf16 v[120:123], v[140:143], v[164:167], v[120:123]
	v_mfma_f32_16x16x32_bf16 v[108:111], v[132:135], v[190:193], v[108:111]
	v_mfma_f32_16x16x32_bf16 v[104:107], v[140:143], v[190:193], v[104:107]
	v_mfma_f32_16x16x32_bf16 v[92:95], v[132:135], v[198:201], v[92:95]
	v_mfma_f32_16x16x32_bf16 v[88:91], v[140:143], v[198:201], v[88:91]
	v_mfma_f32_16x16x32_bf16 v[76:79], v[132:135], v[206:209], v[76:79]
	v_mfma_f32_16x16x32_bf16 v[72:75], v[140:143], v[206:209], v[72:75]
	v_mfma_f32_16x16x32_bf16 v[116:119], v[144:147], v[160:163], v[116:119]
	v_mfma_f32_16x16x32_bf16 v[112:115], v[152:155], v[160:163], v[112:115]
	v_mfma_f32_16x16x32_bf16 v[100:103], v[144:147], v[186:189], v[100:103]
	v_mfma_f32_16x16x32_bf16 v[96:99], v[152:155], v[186:189], v[96:99]
	v_mfma_f32_16x16x32_bf16 v[84:87], v[144:147], v[194:197], v[84:87]
	v_mfma_f32_16x16x32_bf16 v[80:83], v[152:155], v[194:197], v[80:83]
	v_mfma_f32_16x16x32_bf16 v[68:71], v[144:147], v[202:205], v[68:71]
	v_mfma_f32_16x16x32_bf16 v[64:67], v[152:155], v[202:205], v[64:67]
	v_mfma_f32_16x16x32_bf16 v[116:119], v[148:151], v[164:167], v[116:119]
	v_mfma_f32_16x16x32_bf16 v[112:115], v[156:159], v[164:167], v[112:115]
	v_mfma_f32_16x16x32_bf16 v[100:103], v[148:151], v[190:193], v[100:103]
	v_mfma_f32_16x16x32_bf16 v[96:99], v[156:159], v[190:193], v[96:99]
	s_setprio 2
	s_barrier
	v_mfma_f32_16x16x32_bf16 v[84:87], v[148:151], v[198:201], v[84:87]
	v_mfma_f32_16x16x32_bf16 v[80:83], v[156:159], v[198:201], v[80:83]
	v_mfma_f32_16x16x32_bf16 v[68:71], v[148:151], v[206:209], v[68:71]
	v_mfma_f32_16x16x32_bf16 v[64:67], v[156:159], v[206:209], v[64:67]
	s_setprio 0
	s_add_i32 s8, s64, s37
	s_mov_b32 m0, s8
	ds_read_b128 v[160:163], v231 offset:49152
	ds_read_b128 v[164:167], v231 offset:50176
	ds_read_b128 v[186:189], v231 offset:51200
	ds_read_b128 v[190:193], v231 offset:52224
	ds_read_b128 v[194:197], v231 offset:53248
	ds_read_b128 v[198:201], v231 offset:54272
	ds_read_b128 v[202:205], v231 offset:55296
	ds_read_b128 v[206:209], v231 offset:56320
	global_load_lds_dwordx4 v170, s[98:99]
	s_add_i32 m0, s8, 0x2000
	s_add_u32 s8, s50, 0xb0080
	s_addc_u32 s9, s51, 0
	s_add_i32 s50, s65, s37
	global_load_lds_dwordx4 v174, s[98:99]
	s_mov_b32 m0, s50
	s_nop 0
	global_load_lds_dwordx4 v170, s[8:9]
	s_add_i32 m0, s50, 0x2000
	s_nop 0
	global_load_lds_dwordx4 v174, s[8:9]
	s_mov_b32 m0, s73
	s_nop 0
	global_load_lds_dwordx4 v168, s[100:101]
	s_mov_b32 m0, s74
	s_nop 0
	global_load_lds_dwordx4 v172, s[100:101]
	s_waitcnt vmcnt(8)
	s_waitcnt lgkmcnt(0)
	s_barrier
	s_setprio 1
	v_mfma_f32_16x16x32_bf16 v[60:63], v[128:131], v[160:163], v[60:63]
	v_mfma_f32_16x16x32_bf16 v[56:59], v[136:139], v[160:163], v[56:59]
	v_mfma_f32_16x16x32_bf16 v[44:47], v[128:131], v[186:189], v[44:47]
	v_mfma_f32_16x16x32_bf16 v[40:43], v[136:139], v[186:189], v[40:43]
	v_mfma_f32_16x16x32_bf16 v[28:31], v[128:131], v[194:197], v[28:31]
	v_mfma_f32_16x16x32_bf16 v[24:27], v[136:139], v[194:197], v[24:27]
	v_mfma_f32_16x16x32_bf16 v[12:15], v[128:131], v[202:205], v[12:15]
	v_mfma_f32_16x16x32_bf16 v[8:11], v[136:139], v[202:205], v[8:11]
	v_mfma_f32_16x16x32_bf16 v[60:63], v[132:135], v[164:167], v[60:63]
	v_mfma_f32_16x16x32_bf16 v[56:59], v[140:143], v[164:167], v[56:59]
	v_mfma_f32_16x16x32_bf16 v[44:47], v[132:135], v[190:193], v[44:47]
	v_mfma_f32_16x16x32_bf16 v[40:43], v[140:143], v[190:193], v[40:43]
	v_mfma_f32_16x16x32_bf16 v[28:31], v[132:135], v[198:201], v[28:31]
	v_mfma_f32_16x16x32_bf16 v[24:27], v[140:143], v[198:201], v[24:27]
	v_mfma_f32_16x16x32_bf16 v[12:15], v[132:135], v[206:209], v[12:15]
	v_mfma_f32_16x16x32_bf16 v[8:11], v[140:143], v[206:209], v[8:11]
	v_mfma_f32_16x16x32_bf16 v[52:55], v[144:147], v[160:163], v[52:55]
	v_mfma_f32_16x16x32_bf16 v[48:51], v[152:155], v[160:163], v[48:51]
	v_mfma_f32_16x16x32_bf16 v[36:39], v[144:147], v[186:189], v[36:39]
	v_mfma_f32_16x16x32_bf16 v[32:35], v[152:155], v[186:189], v[32:35]
	v_mfma_f32_16x16x32_bf16 v[20:23], v[144:147], v[194:197], v[20:23]
	v_mfma_f32_16x16x32_bf16 v[16:19], v[152:155], v[194:197], v[16:19]
	v_mfma_f32_16x16x32_bf16 v[4:7], v[144:147], v[202:205], v[4:7]
	v_mfma_f32_16x16x32_bf16 v[0:3], v[152:155], v[202:205], v[0:3]
	v_mfma_f32_16x16x32_bf16 v[52:55], v[148:151], v[164:167], v[52:55]
	v_mfma_f32_16x16x32_bf16 v[48:51], v[156:159], v[164:167], v[48:51]
	v_mfma_f32_16x16x32_bf16 v[36:39], v[148:151], v[190:193], v[36:39]
	v_mfma_f32_16x16x32_bf16 v[32:35], v[156:159], v[190:193], v[32:35]
	s_setprio 2
	s_barrier
	v_mfma_f32_16x16x32_bf16 v[20:23], v[148:151], v[198:201], v[20:23]
	v_mfma_f32_16x16x32_bf16 v[16:19], v[156:159], v[198:201], v[16:19]
	v_mfma_f32_16x16x32_bf16 v[4:7], v[148:151], v[206:209], v[4:7]
	v_mfma_f32_16x16x32_bf16 v[0:3], v[156:159], v[206:209], v[0:3]
	s_setprio 0
	s_add_i32 s92, s92, 2
	s_add_u32 s44, s44, 0x100
	s_addc_u32 s55, s55, 0
	s_cmp_gt_u32 s92, 41
	s_mov_b64 s[8:9], s[40:41]
	s_cbranch_scc1 .Lpeel_exit_2
.LBB0_769:
	s_add_u32 s40, s8, 0x100
	s_addc_u32 s41, s9, 0
	s_add_i32 s64, 0, 0x10000
	s_cmp_eq_u32 s92, 40
	s_cselect_b32 s53, s1, s41
	s_cselect_b32 s52, s0, s40
	s_cselect_b32 s51, s39, s55
	s_cselect_b32 s50, s38, s44
	s_add_i32 s65, 0, 0x14000
	v_add_u32_e32 v140, s64, v228
	v_add_u32_e32 v156, s65, v228
	ds_read_b128 v[128:131], v140
	ds_read_b128 v[132:135], v140 offset:1024
	ds_read_b128 v[136:139], v140 offset:2048
	ds_read_b128 v[140:143], v140 offset:3072
	ds_read_b128 v[144:147], v156
	ds_read_b128 v[148:151], v156 offset:1024
	ds_read_b128 v[152:155], v156 offset:2048
	ds_read_b128 v[156:159], v156 offset:3072
	s_add_i32 m0, s62, 0xc000
	ds_read_b128 v[160:163], v231
	ds_read_b128 v[164:167], v231 offset:1024
	ds_read_b128 v[186:189], v231 offset:2048
	ds_read_b128 v[190:193], v231 offset:3072
	ds_read_b128 v[194:197], v231 offset:4096
	ds_read_b128 v[198:201], v231 offset:5120
	ds_read_b128 v[202:205], v231 offset:6144
	ds_read_b128 v[206:209], v231 offset:7168
	global_load_lds_dwordx4 v184, s[8:9]
	s_add_i32 m0, s62, 0xe000
	s_nop 0
	global_load_lds_dwordx4 v182, s[8:9]
	s_waitcnt vmcnt(8)
	s_waitcnt lgkmcnt(0)
	s_barrier
	s_setprio 1
	v_mfma_f32_16x16x32_bf16 v[124:127], v[128:131], v[160:163], v[124:127]
	v_mfma_f32_16x16x32_bf16 v[120:123], v[136:139], v[160:163], v[120:123]
	v_mfma_f32_16x16x32_bf16 v[108:111], v[128:131], v[186:189], v[108:111]
	v_mfma_f32_16x16x32_bf16 v[104:107], v[136:139], v[186:189], v[104:107]
	v_mfma_f32_16x16x32_bf16 v[92:95], v[128:131], v[194:197], v[92:95]
	v_mfma_f32_16x16x32_bf16 v[88:91], v[136:139], v[194:197], v[88:91]
	v_mfma_f32_16x16x32_bf16 v[76:79], v[128:131], v[202:205], v[76:79]
	v_mfma_f32_16x16x32_bf16 v[72:75], v[136:139], v[202:205], v[72:75]
	v_mfma_f32_16x16x32_bf16 v[124:127], v[132:135], v[164:167], v[124:127]
	v_mfma_f32_16x16x32_bf16 v[120:123], v[140:143], v[164:167], v[120:123]
	v_mfma_f32_16x16x32_bf16 v[108:111], v[132:135], v[190:193], v[108:111]
	v_mfma_f32_16x16x32_bf16 v[104:107], v[140:143], v[190:193], v[104:107]
	v_mfma_f32_16x16x32_bf16 v[92:95], v[132:135], v[198:201], v[92:95]
	v_mfma_f32_16x16x32_bf16 v[88:91], v[140:143], v[198:201], v[88:91]
	v_mfma_f32_16x16x32_bf16 v[76:79], v[132:135], v[206:209], v[76:79]
	v_mfma_f32_16x16x32_bf16 v[72:75], v[140:143], v[206:209], v[72:75]
	v_mfma_f32_16x16x32_bf16 v[116:119], v[144:147], v[160:163], v[116:119]
	v_mfma_f32_16x16x32_bf16 v[112:115], v[152:155], v[160:163], v[112:115]
	v_mfma_f32_16x16x32_bf16 v[100:103], v[144:147], v[186:189], v[100:103]
	v_mfma_f32_16x16x32_bf16 v[96:99], v[152:155], v[186:189], v[96:99]
	v_mfma_f32_16x16x32_bf16 v[84:87], v[144:147], v[194:197], v[84:87]
	v_mfma_f32_16x16x32_bf16 v[80:83], v[152:155], v[194:197], v[80:83]
	v_mfma_f32_16x16x32_bf16 v[68:71], v[144:147], v[202:205], v[68:71]
	v_mfma_f32_16x16x32_bf16 v[64:67], v[152:155], v[202:205], v[64:67]
	v_mfma_f32_16x16x32_bf16 v[116:119], v[148:151], v[164:167], v[116:119]
	v_mfma_f32_16x16x32_bf16 v[112:115], v[156:159], v[164:167], v[112:115]
	v_mfma_f32_16x16x32_bf16 v[100:103], v[148:151], v[190:193], v[100:103]
	v_mfma_f32_16x16x32_bf16 v[96:99], v[156:159], v[190:193], v[96:99]
	s_setprio 2
	s_barrier
	v_mfma_f32_16x16x32_bf16 v[84:87], v[148:151], v[198:201], v[84:87]
	v_mfma_f32_16x16x32_bf16 v[80:83], v[156:159], v[198:201], v[80:83]
	v_mfma_f32_16x16x32_bf16 v[68:71], v[148:151], v[206:209], v[68:71]
	v_mfma_f32_16x16x32_bf16 v[64:67], v[156:159], v[206:209], v[64:67]
	s_setprio 0
	s_add_i32 s8, s64, s37
	s_add_u32 s98, s50, s34
	s_addc_u32 s99, s51, s35
	s_mov_b32 m0, s8
	ds_read_b128 v[160:163], v231 offset:16384
	ds_read_b128 v[164:167], v231 offset:17408
	ds_read_b128 v[186:189], v231 offset:18432
	ds_read_b128 v[190:193], v231 offset:19456
	ds_read_b128 v[194:197], v231 offset:20480
	ds_read_b128 v[198:201], v231 offset:21504
	ds_read_b128 v[202:205], v231 offset:22528
	ds_read_b128 v[206:209], v231 offset:23552
	global_load_lds_dwordx4 v170, s[50:51]
	s_add_i32 m0, s8, 0x2000
	s_add_u32 s8, s50, 0xb0000
	s_addc_u32 s9, s51, 0
	s_add_i32 s64, s65, s37
	global_load_lds_dwordx4 v174, s[50:51]
	s_mov_b32 m0, s64
	s_nop 0
	global_load_lds_dwordx4 v170, s[8:9]
	s_add_i32 m0, s64, 0x2000
	s_nop 0
	global_load_lds_dwordx4 v174, s[8:9]
	s_add_u32 s100, s52, s34
	s_addc_u32 s101, s53, s35
	s_mov_b32 m0, s62
	s_nop 0
	global_load_lds_dwordx4 v168, s[52:53]
	s_mov_b32 m0, s63
	s_nop 0
	global_load_lds_dwordx4 v172, s[52:53]
	s_waitcnt vmcnt(8)
	s_waitcnt lgkmcnt(0)
	s_barrier
	s_setprio 1
	v_mfma_f32_16x16x32_bf16 v[60:63], v[128:131], v[160:163], v[60:63]
	v_mfma_f32_16x16x32_bf16 v[56:59], v[136:139], v[160:163], v[56:59]
	v_mfma_f32_16x16x32_bf16 v[44:47], v[128:131], v[186:189], v[44:47]
	v_mfma_f32_16x16x32_bf16 v[40:43], v[136:139], v[186:189], v[40:43]
	v_mfma_f32_16x16x32_bf16 v[28:31], v[128:131], v[194:197], v[28:31]
	v_mfma_f32_16x16x32_bf16 v[24:27], v[136:139], v[194:197], v[24:27]
	v_mfma_f32_16x16x32_bf16 v[12:15], v[128:131], v[202:205], v[12:15]
	v_mfma_f32_16x16x32_bf16 v[8:11], v[136:139], v[202:205], v[8:11]
	v_mfma_f32_16x16x32_bf16 v[60:63], v[132:135], v[164:167], v[60:63]
	v_mfma_f32_16x16x32_bf16 v[56:59], v[140:143], v[164:167], v[56:59]
	v_mfma_f32_16x16x32_bf16 v[44:47], v[132:135], v[190:193], v[44:47]
	v_mfma_f32_16x16x32_bf16 v[40:43], v[140:143], v[190:193], v[40:43]
	v_mfma_f32_16x16x32_bf16 v[28:31], v[132:135], v[198:201], v[28:31]
	v_mfma_f32_16x16x32_bf16 v[24:27], v[140:143], v[198:201], v[24:27]
	v_mfma_f32_16x16x32_bf16 v[12:15], v[132:135], v[206:209], v[12:15]
	v_mfma_f32_16x16x32_bf16 v[8:11], v[140:143], v[206:209], v[8:11]
	v_mfma_f32_16x16x32_bf16 v[52:55], v[144:147], v[160:163], v[52:55]
	v_mfma_f32_16x16x32_bf16 v[48:51], v[152:155], v[160:163], v[48:51]
	v_mfma_f32_16x16x32_bf16 v[36:39], v[144:147], v[186:189], v[36:39]
	v_mfma_f32_16x16x32_bf16 v[32:35], v[152:155], v[186:189], v[32:35]
	v_mfma_f32_16x16x32_bf16 v[20:23], v[144:147], v[194:197], v[20:23]
	v_mfma_f32_16x16x32_bf16 v[16:19], v[152:155], v[194:197], v[16:19]
	v_mfma_f32_16x16x32_bf16 v[4:7], v[144:147], v[202:205], v[4:7]
	v_mfma_f32_16x16x32_bf16 v[0:3], v[152:155], v[202:205], v[0:3]
	v_mfma_f32_16x16x32_bf16 v[52:55], v[148:151], v[164:167], v[52:55]
	v_mfma_f32_16x16x32_bf16 v[48:51], v[156:159], v[164:167], v[48:51]
	v_mfma_f32_16x16x32_bf16 v[36:39], v[148:151], v[190:193], v[36:39]
	v_mfma_f32_16x16x32_bf16 v[32:35], v[156:159], v[190:193], v[32:35]
	s_setprio 2
	s_barrier
	v_mfma_f32_16x16x32_bf16 v[20:23], v[148:151], v[198:201], v[20:23]
	v_mfma_f32_16x16x32_bf16 v[16:19], v[156:159], v[198:201], v[16:19]
	v_mfma_f32_16x16x32_bf16 v[4:7], v[148:151], v[206:209], v[4:7]
	v_mfma_f32_16x16x32_bf16 v[0:3], v[156:159], v[206:209], v[0:3]
	s_setprio 0
	s_add_i32 s64, 0, 0x18000
	s_add_i32 s65, 0, 0x1c000
	v_add_u32_e32 v140, s64, v228
	v_add_u32_e32 v156, s65, v228
	ds_read_b128 v[128:131], v140
	ds_read_b128 v[132:135], v140 offset:1024
	ds_read_b128 v[136:139], v140 offset:2048
	ds_read_b128 v[140:143], v140 offset:3072
	ds_read_b128 v[144:147], v156
	ds_read_b128 v[148:151], v156 offset:1024
	ds_read_b128 v[152:155], v156 offset:2048
	ds_read_b128 v[156:159], v156 offset:3072
	s_add_u32 s8, s52, 0xb0000
	s_addc_u32 s9, s53, 0
	s_mov_b32 m0, s68
	ds_read_b128 v[160:163], v231 offset:32768
	ds_read_b128 v[164:167], v231 offset:33792
	ds_read_b128 v[186:189], v231 offset:34816
	ds_read_b128 v[190:193], v231 offset:35840
	ds_read_b128 v[194:197], v231 offset:36864
	ds_read_b128 v[198:201], v231 offset:37888
	ds_read_b128 v[202:205], v231 offset:38912
	ds_read_b128 v[206:209], v231 offset:39936
	global_load_lds_dwordx4 v168, s[8:9]
	s_mov_b32 m0, s69
	s_nop 0
	global_load_lds_dwordx4 v172, s[8:9]
	s_waitcnt vmcnt(8)
	s_waitcnt lgkmcnt(0)
	s_barrier
	s_setprio 1
	v_mfma_f32_16x16x32_bf16 v[124:127], v[128:131], v[160:163], v[124:127]
	v_mfma_f32_16x16x32_bf16 v[120:123], v[136:139], v[160:163], v[120:123]
	v_mfma_f32_16x16x32_bf16 v[108:111], v[128:131], v[186:189], v[108:111]
	v_mfma_f32_16x16x32_bf16 v[104:107], v[136:139], v[186:189], v[104:107]
	v_mfma_f32_16x16x32_bf16 v[92:95], v[128:131], v[194:197], v[92:95]
	v_mfma_f32_16x16x32_bf16 v[88:91], v[136:139], v[194:197], v[88:91]
	v_mfma_f32_16x16x32_bf16 v[76:79], v[128:131], v[202:205], v[76:79]
	v_mfma_f32_16x16x32_bf16 v[72:75], v[136:139], v[202:205], v[72:75]
	v_mfma_f32_16x16x32_bf16 v[124:127], v[132:135], v[164:167], v[124:127]
	v_mfma_f32_16x16x32_bf16 v[120:123], v[140:143], v[164:167], v[120:123]
	v_mfma_f32_16x16x32_bf16 v[108:111], v[132:135], v[190:193], v[108:111]
	v_mfma_f32_16x16x32_bf16 v[104:107], v[140:143], v[190:193], v[104:107]
	v_mfma_f32_16x16x32_bf16 v[92:95], v[132:135], v[198:201], v[92:95]
	v_mfma_f32_16x16x32_bf16 v[88:91], v[140:143], v[198:201], v[88:91]
	v_mfma_f32_16x16x32_bf16 v[76:79], v[132:135], v[206:209], v[76:79]
	v_mfma_f32_16x16x32_bf16 v[72:75], v[140:143], v[206:209], v[72:75]
	v_mfma_f32_16x16x32_bf16 v[116:119], v[144:147], v[160:163], v[116:119]
	v_mfma_f32_16x16x32_bf16 v[112:115], v[152:155], v[160:163], v[112:115]
	v_mfma_f32_16x16x32_bf16 v[100:103], v[144:147], v[186:189], v[100:103]
	v_mfma_f32_16x16x32_bf16 v[96:99], v[152:155], v[186:189], v[96:99]
	v_mfma_f32_16x16x32_bf16 v[84:87], v[144:147], v[194:197], v[84:87]
	v_mfma_f32_16x16x32_bf16 v[80:83], v[152:155], v[194:197], v[80:83]
	v_mfma_f32_16x16x32_bf16 v[68:71], v[144:147], v[202:205], v[68:71]
	v_mfma_f32_16x16x32_bf16 v[64:67], v[152:155], v[202:205], v[64:67]
	v_mfma_f32_16x16x32_bf16 v[116:119], v[148:151], v[164:167], v[116:119]
	v_mfma_f32_16x16x32_bf16 v[112:115], v[156:159], v[164:167], v[112:115]
	v_mfma_f32_16x16x32_bf16 v[100:103], v[148:151], v[190:193], v[100:103]
	v_mfma_f32_16x16x32_bf16 v[96:99], v[156:159], v[190:193], v[96:99]
	s_setprio 2
	s_barrier
	v_mfma_f32_16x16x32_bf16 v[84:87], v[148:151], v[198:201], v[84:87]
	v_mfma_f32_16x16x32_bf16 v[80:83], v[156:159], v[198:201], v[80:83]
	v_mfma_f32_16x16x32_bf16 v[68:71], v[148:151], v[206:209], v[68:71]
	v_mfma_f32_16x16x32_bf16 v[64:67], v[156:159], v[206:209], v[64:67]
	s_setprio 0
	s_add_i32 s8, s64, s37
	s_mov_b32 m0, s8
	ds_read_b128 v[160:163], v231 offset:49152
	ds_read_b128 v[164:167], v231 offset:50176
	ds_read_b128 v[186:189], v231 offset:51200
	ds_read_b128 v[190:193], v231 offset:52224
	ds_read_b128 v[194:197], v231 offset:53248
	ds_read_b128 v[198:201], v231 offset:54272
	ds_read_b128 v[202:205], v231 offset:55296
	ds_read_b128 v[206:209], v231 offset:56320
	global_load_lds_dwordx4 v170, s[98:99]
	s_add_i32 m0, s8, 0x2000
	s_add_u32 s8, s50, 0xb0080
	s_addc_u32 s9, s51, 0
	s_add_i32 s50, s65, s37
	global_load_lds_dwordx4 v174, s[98:99]
	s_mov_b32 m0, s50
	s_nop 0
	global_load_lds_dwordx4 v170, s[8:9]
	s_add_i32 m0, s50, 0x2000
	s_nop 0
	global_load_lds_dwordx4 v174, s[8:9]
	s_mov_b32 m0, s73
	s_nop 0
	global_load_lds_dwordx4 v168, s[100:101]
	s_mov_b32 m0, s74
	s_nop 0
	global_load_lds_dwordx4 v172, s[100:101]
	s_waitcnt vmcnt(8)
	s_waitcnt lgkmcnt(0)
	s_barrier
	s_setprio 1
	v_mfma_f32_16x16x32_bf16 v[60:63], v[128:131], v[160:163], v[60:63]
	v_mfma_f32_16x16x32_bf16 v[56:59], v[136:139], v[160:163], v[56:59]
	v_mfma_f32_16x16x32_bf16 v[44:47], v[128:131], v[186:189], v[44:47]
	v_mfma_f32_16x16x32_bf16 v[40:43], v[136:139], v[186:189], v[40:43]
	v_mfma_f32_16x16x32_bf16 v[28:31], v[128:131], v[194:197], v[28:31]
	v_mfma_f32_16x16x32_bf16 v[24:27], v[136:139], v[194:197], v[24:27]
	v_mfma_f32_16x16x32_bf16 v[12:15], v[128:131], v[202:205], v[12:15]
	v_mfma_f32_16x16x32_bf16 v[8:11], v[136:139], v[202:205], v[8:11]
	v_mfma_f32_16x16x32_bf16 v[60:63], v[132:135], v[164:167], v[60:63]
	v_mfma_f32_16x16x32_bf16 v[56:59], v[140:143], v[164:167], v[56:59]
	v_mfma_f32_16x16x32_bf16 v[44:47], v[132:135], v[190:193], v[44:47]
	v_mfma_f32_16x16x32_bf16 v[40:43], v[140:143], v[190:193], v[40:43]
	v_mfma_f32_16x16x32_bf16 v[28:31], v[132:135], v[198:201], v[28:31]
	v_mfma_f32_16x16x32_bf16 v[24:27], v[140:143], v[198:201], v[24:27]
	v_mfma_f32_16x16x32_bf16 v[12:15], v[132:135], v[206:209], v[12:15]
	v_mfma_f32_16x16x32_bf16 v[8:11], v[140:143], v[206:209], v[8:11]
	v_mfma_f32_16x16x32_bf16 v[52:55], v[144:147], v[160:163], v[52:55]
	v_mfma_f32_16x16x32_bf16 v[48:51], v[152:155], v[160:163], v[48:51]
	v_mfma_f32_16x16x32_bf16 v[36:39], v[144:147], v[186:189], v[36:39]
	v_mfma_f32_16x16x32_bf16 v[32:35], v[152:155], v[186:189], v[32:35]
	v_mfma_f32_16x16x32_bf16 v[20:23], v[144:147], v[194:197], v[20:23]
	v_mfma_f32_16x16x32_bf16 v[16:19], v[152:155], v[194:197], v[16:19]
	v_mfma_f32_16x16x32_bf16 v[4:7], v[144:147], v[202:205], v[4:7]
	v_mfma_f32_16x16x32_bf16 v[0:3], v[152:155], v[202:205], v[0:3]
	v_mfma_f32_16x16x32_bf16 v[52:55], v[148:151], v[164:167], v[52:55]
	v_mfma_f32_16x16x32_bf16 v[48:51], v[156:159], v[164:167], v[48:51]
	v_mfma_f32_16x16x32_bf16 v[36:39], v[148:151], v[190:193], v[36:39]
	v_mfma_f32_16x16x32_bf16 v[32:35], v[156:159], v[190:193], v[32:35]
	s_setprio 2
	s_barrier
	v_mfma_f32_16x16x32_bf16 v[20:23], v[148:151], v[198:201], v[20:23]
	v_mfma_f32_16x16x32_bf16 v[16:19], v[156:159], v[198:201], v[16:19]
	v_mfma_f32_16x16x32_bf16 v[4:7], v[148:151], v[206:209], v[4:7]
	v_mfma_f32_16x16x32_bf16 v[0:3], v[156:159], v[206:209], v[0:3]
	s_setprio 0
	s_add_i32 s92, s92, 2
	s_add_u32 s44, s44, 0x100
	s_addc_u32 s55, s55, 0
	s_cmp_gt_u32 s92, 41
	s_mov_b64 s[8:9], s[40:41]
	s_cbranch_scc0 .LBB0_769

.LBB0_862:
	s_add_i32 s27, s63, -2
	s_add_u32 vcc_lo, s40, 0x100
	s_addc_u32 vcc_hi, s41, 0
	s_mov_b32 s50, 0
	s_add_i32 s64, s50, 2
	s_add_u32 s40, s8, 0x100
	s_addc_u32 s41, s9, 0
	s_add_i32 s65, 0, 0x10000
	s_cmp_eq_u32 s27, s50
	s_cselect_b32 s53, s29, s41
	s_cselect_b32 s52, s28, s40
	s_cselect_b32 s51, s39, vcc_hi
	s_cselect_b32 s50, s38, vcc_lo
	s_add_i32 s66, 0, 0x14000
	v_add_u32_e32 v140, s65, v228
	v_add_u32_e32 v156, s66, v228
	ds_read_b128 v[128:131], v140
	ds_read_b128 v[132:135], v140 offset:1024
	ds_read_b128 v[136:139], v140 offset:2048
	ds_read_b128 v[140:143], v140 offset:3072
	ds_read_b128 v[144:147], v156
	ds_read_b128 v[148:151], v156 offset:1024
	ds_read_b128 v[152:155], v156 offset:2048
	ds_read_b128 v[156:159], v156 offset:3072
	s_add_i32 m0, s74, 0xc000
	ds_read_b128 v[160:163], v232
	ds_read_b128 v[164:167], v232 offset:1024
	ds_read_b128 v[186:189], v232 offset:2048
	ds_read_b128 v[190:193], v232 offset:3072
	ds_read_b128 v[194:197], v232 offset:4096
	ds_read_b128 v[198:201], v232 offset:5120
	ds_read_b128 v[202:205], v232 offset:6144
	ds_read_b128 v[206:209], v232 offset:7168
	global_load_lds_dwordx4 v184, s[8:9]
	s_add_i32 m0, s74, 0xe000
	s_nop 0
	global_load_lds_dwordx4 v182, s[8:9]
	s_waitcnt vmcnt(24)
	s_waitcnt lgkmcnt(0)
	s_barrier
	s_setprio 1
	v_mfma_f32_16x16x32_bf16 v[124:127], v[128:131], v[160:163], 0
	v_mfma_f32_16x16x32_bf16 v[120:123], v[136:139], v[160:163], 0
	v_mfma_f32_16x16x32_bf16 v[108:111], v[128:131], v[186:189], 0
	v_mfma_f32_16x16x32_bf16 v[104:107], v[136:139], v[186:189], 0
	v_mfma_f32_16x16x32_bf16 v[92:95], v[128:131], v[194:197], 0
	v_mfma_f32_16x16x32_bf16 v[88:91], v[136:139], v[194:197], 0
	v_mfma_f32_16x16x32_bf16 v[76:79], v[128:131], v[202:205], 0
	v_mfma_f32_16x16x32_bf16 v[72:75], v[136:139], v[202:205], 0
	v_mfma_f32_16x16x32_bf16 v[124:127], v[132:135], v[164:167], v[124:127]
	v_mfma_f32_16x16x32_bf16 v[120:123], v[140:143], v[164:167], v[120:123]
	v_mfma_f32_16x16x32_bf16 v[108:111], v[132:135], v[190:193], v[108:111]
	v_mfma_f32_16x16x32_bf16 v[104:107], v[140:143], v[190:193], v[104:107]
	v_mfma_f32_16x16x32_bf16 v[92:95], v[132:135], v[198:201], v[92:95]
	v_mfma_f32_16x16x32_bf16 v[88:91], v[140:143], v[198:201], v[88:91]
	v_mfma_f32_16x16x32_bf16 v[76:79], v[132:135], v[206:209], v[76:79]
	v_mfma_f32_16x16x32_bf16 v[72:75], v[140:143], v[206:209], v[72:75]
	v_mfma_f32_16x16x32_bf16 v[116:119], v[144:147], v[160:163], 0
	v_mfma_f32_16x16x32_bf16 v[112:115], v[152:155], v[160:163], 0
	v_mfma_f32_16x16x32_bf16 v[100:103], v[144:147], v[186:189], 0
	v_mfma_f32_16x16x32_bf16 v[96:99], v[152:155], v[186:189], 0
	v_mfma_f32_16x16x32_bf16 v[84:87], v[144:147], v[194:197], 0
	v_mfma_f32_16x16x32_bf16 v[80:83], v[152:155], v[194:197], 0
	v_mfma_f32_16x16x32_bf16 v[68:71], v[144:147], v[202:205], 0
	v_mfma_f32_16x16x32_bf16 v[64:67], v[152:155], v[202:205], 0
	v_mfma_f32_16x16x32_bf16 v[116:119], v[148:151], v[164:167], v[116:119]
	v_mfma_f32_16x16x32_bf16 v[112:115], v[156:159], v[164:167], v[112:115]
	v_mfma_f32_16x16x32_bf16 v[100:103], v[148:151], v[190:193], v[100:103]
	v_mfma_f32_16x16x32_bf16 v[96:99], v[156:159], v[190:193], v[96:99]
	s_setprio 2
	s_barrier
	v_mfma_f32_16x16x32_bf16 v[84:87], v[148:151], v[198:201], v[84:87]
	v_mfma_f32_16x16x32_bf16 v[80:83], v[156:159], v[198:201], v[80:83]
	v_mfma_f32_16x16x32_bf16 v[68:71], v[148:151], v[206:209], v[68:71]
	v_mfma_f32_16x16x32_bf16 v[64:67], v[156:159], v[206:209], v[64:67]
	s_setprio 0
	s_add_i32 s8, s65, s72
	s_add_u32 s98, s50, s34
	s_addc_u32 s99, s51, s35
	s_mov_b32 m0, s8
	ds_read_b128 v[160:163], v232 offset:16384
	ds_read_b128 v[164:167], v232 offset:17408
	ds_read_b128 v[186:189], v232 offset:18432
	ds_read_b128 v[190:193], v232 offset:19456
	ds_read_b128 v[194:197], v232 offset:20480
	ds_read_b128 v[198:201], v232 offset:21504
	ds_read_b128 v[202:205], v232 offset:22528
	ds_read_b128 v[206:209], v232 offset:23552
	global_load_lds_dwordx4 v170, s[50:51]
	s_add_i32 m0, s8, 0x2000
	s_add_u32 s8, s50, 0xb0000
	s_addc_u32 s9, s51, 0
	s_add_i32 s65, s66, s72
	global_load_lds_dwordx4 v174, s[50:51]
	s_mov_b32 m0, s65
	s_nop 0
	global_load_lds_dwordx4 v170, s[8:9]
	s_add_i32 m0, s65, 0x2000
	s_nop 0
	global_load_lds_dwordx4 v174, s[8:9]
	s_add_u32 s100, s52, s34
	s_addc_u32 s101, s53, s35
	s_mov_b32 m0, s74
	s_nop 0
	global_load_lds_dwordx4 v168, s[52:53]
	s_mov_b32 m0, s75
	s_nop 0
	global_load_lds_dwordx4 v172, s[52:53]
	s_waitcnt vmcnt(8)
	s_waitcnt lgkmcnt(0)
	s_barrier
	s_setprio 1
	v_mfma_f32_16x16x32_bf16 v[60:63], v[128:131], v[160:163], 0
	v_mfma_f32_16x16x32_bf16 v[56:59], v[136:139], v[160:163], 0
	v_mfma_f32_16x16x32_bf16 v[44:47], v[128:131], v[186:189], 0
	v_mfma_f32_16x16x32_bf16 v[40:43], v[136:139], v[186:189], 0
	v_mfma_f32_16x16x32_bf16 v[28:31], v[128:131], v[194:197], 0
	v_mfma_f32_16x16x32_bf16 v[24:27], v[136:139], v[194:197], 0
	v_mfma_f32_16x16x32_bf16 v[12:15], v[128:131], v[202:205], 0
	v_mfma_f32_16x16x32_bf16 v[8:11], v[136:139], v[202:205], 0
	v_mfma_f32_16x16x32_bf16 v[60:63], v[132:135], v[164:167], v[60:63]
	v_mfma_f32_16x16x32_bf16 v[56:59], v[140:143], v[164:167], v[56:59]
	v_mfma_f32_16x16x32_bf16 v[44:47], v[132:135], v[190:193], v[44:47]
	v_mfma_f32_16x16x32_bf16 v[40:43], v[140:143], v[190:193], v[40:43]
	v_mfma_f32_16x16x32_bf16 v[28:31], v[132:135], v[198:201], v[28:31]
	v_mfma_f32_16x16x32_bf16 v[24:27], v[140:143], v[198:201], v[24:27]
	v_mfma_f32_16x16x32_bf16 v[12:15], v[132:135], v[206:209], v[12:15]
	v_mfma_f32_16x16x32_bf16 v[8:11], v[140:143], v[206:209], v[8:11]
	v_mfma_f32_16x16x32_bf16 v[52:55], v[144:147], v[160:163], 0
	v_mfma_f32_16x16x32_bf16 v[48:51], v[152:155], v[160:163], 0
	v_mfma_f32_16x16x32_bf16 v[36:39], v[144:147], v[186:189], 0
	v_mfma_f32_16x16x32_bf16 v[32:35], v[152:155], v[186:189], 0
	v_mfma_f32_16x16x32_bf16 v[20:23], v[144:147], v[194:197], 0
	v_mfma_f32_16x16x32_bf16 v[16:19], v[152:155], v[194:197], 0
	v_mfma_f32_16x16x32_bf16 v[4:7], v[144:147], v[202:205], 0
	v_mfma_f32_16x16x32_bf16 v[0:3], v[152:155], v[202:205], 0
	v_mfma_f32_16x16x32_bf16 v[52:55], v[148:151], v[164:167], v[52:55]
	v_mfma_f32_16x16x32_bf16 v[48:51], v[156:159], v[164:167], v[48:51]
	v_mfma_f32_16x16x32_bf16 v[36:39], v[148:151], v[190:193], v[36:39]
	v_mfma_f32_16x16x32_bf16 v[32:35], v[156:159], v[190:193], v[32:35]
	s_setprio 2
	s_barrier
	v_mfma_f32_16x16x32_bf16 v[20:23], v[148:151], v[198:201], v[20:23]
	v_mfma_f32_16x16x32_bf16 v[16:19], v[156:159], v[198:201], v[16:19]
	v_mfma_f32_16x16x32_bf16 v[4:7], v[148:151], v[206:209], v[4:7]
	v_mfma_f32_16x16x32_bf16 v[0:3], v[156:159], v[206:209], v[0:3]
	s_setprio 0
	s_add_i32 s65, 0, 0x18000
	s_add_i32 s66, 0, 0x1c000
	v_add_u32_e32 v140, s65, v228
	v_add_u32_e32 v156, s66, v228
	ds_read_b128 v[128:131], v140
	ds_read_b128 v[132:135], v140 offset:1024
	ds_read_b128 v[136:139], v140 offset:2048
	ds_read_b128 v[140:143], v140 offset:3072
	ds_read_b128 v[144:147], v156
	ds_read_b128 v[148:151], v156 offset:1024
	ds_read_b128 v[152:155], v156 offset:2048
	ds_read_b128 v[156:159], v156 offset:3072
	s_add_u32 s8, s52, 0xb0000
	s_addc_u32 s9, s53, 0
	s_mov_b32 m0, s80
	ds_read_b128 v[160:163], v232 offset:32768
	ds_read_b128 v[164:167], v232 offset:33792
	ds_read_b128 v[186:189], v232 offset:34816
	ds_read_b128 v[190:193], v232 offset:35840
	ds_read_b128 v[194:197], v232 offset:36864
	ds_read_b128 v[198:201], v232 offset:37888
	ds_read_b128 v[202:205], v232 offset:38912
	ds_read_b128 v[206:209], v232 offset:39936
	global_load_lds_dwordx4 v168, s[8:9]
	s_mov_b32 m0, s81
	s_nop 0
	global_load_lds_dwordx4 v172, s[8:9]
	s_waitcnt vmcnt(8)
	s_waitcnt lgkmcnt(0)
	s_barrier
	s_setprio 1
	v_mfma_f32_16x16x32_bf16 v[124:127], v[128:131], v[160:163], v[124:127]
	v_mfma_f32_16x16x32_bf16 v[120:123], v[136:139], v[160:163], v[120:123]
	v_mfma_f32_16x16x32_bf16 v[108:111], v[128:131], v[186:189], v[108:111]
	v_mfma_f32_16x16x32_bf16 v[104:107], v[136:139], v[186:189], v[104:107]
	v_mfma_f32_16x16x32_bf16 v[92:95], v[128:131], v[194:197], v[92:95]
	v_mfma_f32_16x16x32_bf16 v[88:91], v[136:139], v[194:197], v[88:91]
	v_mfma_f32_16x16x32_bf16 v[76:79], v[128:131], v[202:205], v[76:79]
	v_mfma_f32_16x16x32_bf16 v[72:75], v[136:139], v[202:205], v[72:75]
	v_mfma_f32_16x16x32_bf16 v[124:127], v[132:135], v[164:167], v[124:127]
	v_mfma_f32_16x16x32_bf16 v[120:123], v[140:143], v[164:167], v[120:123]
	v_mfma_f32_16x16x32_bf16 v[108:111], v[132:135], v[190:193], v[108:111]
	v_mfma_f32_16x16x32_bf16 v[104:107], v[140:143], v[190:193], v[104:107]
	v_mfma_f32_16x16x32_bf16 v[92:95], v[132:135], v[198:201], v[92:95]
	v_mfma_f32_16x16x32_bf16 v[88:91], v[140:143], v[198:201], v[88:91]
	v_mfma_f32_16x16x32_bf16 v[76:79], v[132:135], v[206:209], v[76:79]
	v_mfma_f32_16x16x32_bf16 v[72:75], v[140:143], v[206:209], v[72:75]
	v_mfma_f32_16x16x32_bf16 v[116:119], v[144:147], v[160:163], v[116:119]
	v_mfma_f32_16x16x32_bf16 v[112:115], v[152:155], v[160:163], v[112:115]
	v_mfma_f32_16x16x32_bf16 v[100:103], v[144:147], v[186:189], v[100:103]
	v_mfma_f32_16x16x32_bf16 v[96:99], v[152:155], v[186:189], v[96:99]
	v_mfma_f32_16x16x32_bf16 v[84:87], v[144:147], v[194:197], v[84:87]
	v_mfma_f32_16x16x32_bf16 v[80:83], v[152:155], v[194:197], v[80:83]
	v_mfma_f32_16x16x32_bf16 v[68:71], v[144:147], v[202:205], v[68:71]
	v_mfma_f32_16x16x32_bf16 v[64:67], v[152:155], v[202:205], v[64:67]
	v_mfma_f32_16x16x32_bf16 v[116:119], v[148:151], v[164:167], v[116:119]
	v_mfma_f32_16x16x32_bf16 v[112:115], v[156:159], v[164:167], v[112:115]
	v_mfma_f32_16x16x32_bf16 v[100:103], v[148:151], v[190:193], v[100:103]
	v_mfma_f32_16x16x32_bf16 v[96:99], v[156:159], v[190:193], v[96:99]
	s_setprio 2
	s_barrier
	v_mfma_f32_16x16x32_bf16 v[84:87], v[148:151], v[198:201], v[84:87]
	v_mfma_f32_16x16x32_bf16 v[80:83], v[156:159], v[198:201], v[80:83]
	v_mfma_f32_16x16x32_bf16 v[68:71], v[148:151], v[206:209], v[68:71]
	v_mfma_f32_16x16x32_bf16 v[64:67], v[156:159], v[206:209], v[64:67]
	s_setprio 0
	s_add_i32 s8, s65, s72
	s_mov_b32 m0, s8
	ds_read_b128 v[160:163], v232 offset:49152
	ds_read_b128 v[164:167], v232 offset:50176
	ds_read_b128 v[186:189], v232 offset:51200
	ds_read_b128 v[190:193], v232 offset:52224
	ds_read_b128 v[194:197], v232 offset:53248
	ds_read_b128 v[198:201], v232 offset:54272
	ds_read_b128 v[202:205], v232 offset:55296
	ds_read_b128 v[206:209], v232 offset:56320
	global_load_lds_dwordx4 v170, s[98:99]
	s_add_i32 m0, s8, 0x2000
	s_add_u32 s8, s50, 0xb0080
	s_addc_u32 s9, s51, 0
	s_add_i32 s50, s66, s72
	global_load_lds_dwordx4 v174, s[98:99]
	s_mov_b32 m0, s50
	s_nop 0
	global_load_lds_dwordx4 v170, s[8:9]
	s_add_i32 m0, s50, 0x2000
	s_nop 0
	global_load_lds_dwordx4 v174, s[8:9]
	s_mov_b32 m0, s83
	s_nop 0
	global_load_lds_dwordx4 v168, s[100:101]
	s_mov_b32 m0, s91
	s_nop 0
	global_load_lds_dwordx4 v172, s[100:101]
	s_waitcnt vmcnt(8)
	s_waitcnt lgkmcnt(0)
	s_barrier
	s_setprio 1
	v_mfma_f32_16x16x32_bf16 v[60:63], v[128:131], v[160:163], v[60:63]
	v_mfma_f32_16x16x32_bf16 v[56:59], v[136:139], v[160:163], v[56:59]
	v_mfma_f32_16x16x32_bf16 v[44:47], v[128:131], v[186:189], v[44:47]
	v_mfma_f32_16x16x32_bf16 v[40:43], v[136:139], v[186:189], v[40:43]
	v_mfma_f32_16x16x32_bf16 v[28:31], v[128:131], v[194:197], v[28:31]
	v_mfma_f32_16x16x32_bf16 v[24:27], v[136:139], v[194:197], v[24:27]
	v_mfma_f32_16x16x32_bf16 v[12:15], v[128:131], v[202:205], v[12:15]
	v_mfma_f32_16x16x32_bf16 v[8:11], v[136:139], v[202:205], v[8:11]
	v_mfma_f32_16x16x32_bf16 v[60:63], v[132:135], v[164:167], v[60:63]
	v_mfma_f32_16x16x32_bf16 v[56:59], v[140:143], v[164:167], v[56:59]
	v_mfma_f32_16x16x32_bf16 v[44:47], v[132:135], v[190:193], v[44:47]
	v_mfma_f32_16x16x32_bf16 v[40:43], v[140:143], v[190:193], v[40:43]
	v_mfma_f32_16x16x32_bf16 v[28:31], v[132:135], v[198:201], v[28:31]
	v_mfma_f32_16x16x32_bf16 v[24:27], v[140:143], v[198:201], v[24:27]
	v_mfma_f32_16x16x32_bf16 v[12:15], v[132:135], v[206:209], v[12:15]
	v_mfma_f32_16x16x32_bf16 v[8:11], v[140:143], v[206:209], v[8:11]
	v_mfma_f32_16x16x32_bf16 v[52:55], v[144:147], v[160:163], v[52:55]
	v_mfma_f32_16x16x32_bf16 v[48:51], v[152:155], v[160:163], v[48:51]
	v_mfma_f32_16x16x32_bf16 v[36:39], v[144:147], v[186:189], v[36:39]
	v_mfma_f32_16x16x32_bf16 v[32:35], v[152:155], v[186:189], v[32:35]
	v_mfma_f32_16x16x32_bf16 v[20:23], v[144:147], v[194:197], v[20:23]
	v_mfma_f32_16x16x32_bf16 v[16:19], v[152:155], v[194:197], v[16:19]
	v_mfma_f32_16x16x32_bf16 v[4:7], v[144:147], v[202:205], v[4:7]
	v_mfma_f32_16x16x32_bf16 v[0:3], v[152:155], v[202:205], v[0:3]
	v_mfma_f32_16x16x32_bf16 v[52:55], v[148:151], v[164:167], v[52:55]
	v_mfma_f32_16x16x32_bf16 v[48:51], v[156:159], v[164:167], v[48:51]
	v_mfma_f32_16x16x32_bf16 v[36:39], v[148:151], v[190:193], v[36:39]
	v_mfma_f32_16x16x32_bf16 v[32:35], v[156:159], v[190:193], v[32:35]
	s_setprio 2
	s_barrier
	v_mfma_f32_16x16x32_bf16 v[20:23], v[148:151], v[198:201], v[20:23]
	v_mfma_f32_16x16x32_bf16 v[16:19], v[156:159], v[198:201], v[16:19]
	v_mfma_f32_16x16x32_bf16 v[4:7], v[148:151], v[206:209], v[4:7]
	v_mfma_f32_16x16x32_bf16 v[0:3], v[156:159], v[206:209], v[0:3]
	s_setprio 0
	s_add_u32 vcc_lo, vcc_lo, 0x100
	s_addc_u32 vcc_hi, vcc_hi, 0
	s_cmp_ge_i32 s64, s63
	s_mov_b64 s[8:9], s[40:41]
	s_mov_b32 s50, s64
	s_cbranch_scc1 .Lpeel_exit_3
.LBB0_863:
	s_add_i32 s64, s50, 2
	s_add_u32 s40, s8, 0x100
	s_addc_u32 s41, s9, 0
	s_add_i32 s65, 0, 0x10000
	s_cmp_eq_u32 s27, s50
	s_cselect_b32 s53, s29, s41
	s_cselect_b32 s52, s28, s40
	s_cselect_b32 s51, s39, vcc_hi
	s_cselect_b32 s50, s38, vcc_lo
	s_add_i32 s66, 0, 0x14000
	v_add_u32_e32 v140, s65, v228
	v_add_u32_e32 v156, s66, v228
	ds_read_b128 v[128:131], v140
	ds_read_b128 v[132:135], v140 offset:1024
	ds_read_b128 v[136:139], v140 offset:2048
	ds_read_b128 v[140:143], v140 offset:3072
	ds_read_b128 v[144:147], v156
	ds_read_b128 v[148:151], v156 offset:1024
	ds_read_b128 v[152:155], v156 offset:2048
	ds_read_b128 v[156:159], v156 offset:3072
	s_add_i32 m0, s74, 0xc000
	ds_read_b128 v[160:163], v232
	ds_read_b128 v[164:167], v232 offset:1024
	ds_read_b128 v[186:189], v232 offset:2048
	ds_read_b128 v[190:193], v232 offset:3072
	ds_read_b128 v[194:197], v232 offset:4096
	ds_read_b128 v[198:201], v232 offset:5120
	ds_read_b128 v[202:205], v232 offset:6144
	ds_read_b128 v[206:209], v232 offset:7168
	global_load_lds_dwordx4 v184, s[8:9]
	s_add_i32 m0, s74, 0xe000
	s_nop 0
	global_load_lds_dwordx4 v182, s[8:9]
	s_waitcnt vmcnt(8)
	s_waitcnt lgkmcnt(0)
	s_barrier
	s_setprio 1
	v_mfma_f32_16x16x32_bf16 v[124:127], v[128:131], v[160:163], v[124:127]
	v_mfma_f32_16x16x32_bf16 v[120:123], v[136:139], v[160:163], v[120:123]
	v_mfma_f32_16x16x32_bf16 v[108:111], v[128:131], v[186:189], v[108:111]
	v_mfma_f32_16x16x32_bf16 v[104:107], v[136:139], v[186:189], v[104:107]
	v_mfma_f32_16x16x32_bf16 v[92:95], v[128:131], v[194:197], v[92:95]
	v_mfma_f32_16x16x32_bf16 v[88:91], v[136:139], v[194:197], v[88:91]
	v_mfma_f32_16x16x32_bf16 v[76:79], v[128:131], v[202:205], v[76:79]
	v_mfma_f32_16x16x32_bf16 v[72:75], v[136:139], v[202:205], v[72:75]
	v_mfma_f32_16x16x32_bf16 v[124:127], v[132:135], v[164:167], v[124:127]
	v_mfma_f32_16x16x32_bf16 v[120:123], v[140:143], v[164:167], v[120:123]
	v_mfma_f32_16x16x32_bf16 v[108:111], v[132:135], v[190:193], v[108:111]
	v_mfma_f32_16x16x32_bf16 v[104:107], v[140:143], v[190:193], v[104:107]
	v_mfma_f32_16x16x32_bf16 v[92:95], v[132:135], v[198:201], v[92:95]
	v_mfma_f32_16x16x32_bf16 v[88:91], v[140:143], v[198:201], v[88:91]
	v_mfma_f32_16x16x32_bf16 v[76:79], v[132:135], v[206:209], v[76:79]
	v_mfma_f32_16x16x32_bf16 v[72:75], v[140:143], v[206:209], v[72:75]
	v_mfma_f32_16x16x32_bf16 v[116:119], v[144:147], v[160:163], v[116:119]
	v_mfma_f32_16x16x32_bf16 v[112:115], v[152:155], v[160:163], v[112:115]
	v_mfma_f32_16x16x32_bf16 v[100:103], v[144:147], v[186:189], v[100:103]
	v_mfma_f32_16x16x32_bf16 v[96:99], v[152:155], v[186:189], v[96:99]
	v_mfma_f32_16x16x32_bf16 v[84:87], v[144:147], v[194:197], v[84:87]
	v_mfma_f32_16x16x32_bf16 v[80:83], v[152:155], v[194:197], v[80:83]
	v_mfma_f32_16x16x32_bf16 v[68:71], v[144:147], v[202:205], v[68:71]
	v_mfma_f32_16x16x32_bf16 v[64:67], v[152:155], v[202:205], v[64:67]
	v_mfma_f32_16x16x32_bf16 v[116:119], v[148:151], v[164:167], v[116:119]
	v_mfma_f32_16x16x32_bf16 v[112:115], v[156:159], v[164:167], v[112:115]
	v_mfma_f32_16x16x32_bf16 v[100:103], v[148:151], v[190:193], v[100:103]
	v_mfma_f32_16x16x32_bf16 v[96:99], v[156:159], v[190:193], v[96:99]
	s_setprio 2
	s_barrier
	v_mfma_f32_16x16x32_bf16 v[84:87], v[148:151], v[198:201], v[84:87]
	v_mfma_f32_16x16x32_bf16 v[80:83], v[156:159], v[198:201], v[80:83]
	v_mfma_f32_16x16x32_bf16 v[68:71], v[148:151], v[206:209], v[68:71]
	v_mfma_f32_16x16x32_bf16 v[64:67], v[156:159], v[206:209], v[64:67]
	s_setprio 0
	s_add_i32 s8, s65, s72
	s_add_u32 s98, s50, s34
	s_addc_u32 s99, s51, s35
	s_mov_b32 m0, s8
	ds_read_b128 v[160:163], v232 offset:16384
	ds_read_b128 v[164:167], v232 offset:17408
	ds_read_b128 v[186:189], v232 offset:18432
	ds_read_b128 v[190:193], v232 offset:19456
	ds_read_b128 v[194:197], v232 offset:20480
	ds_read_b128 v[198:201], v232 offset:21504
	ds_read_b128 v[202:205], v232 offset:22528
	ds_read_b128 v[206:209], v232 offset:23552
	global_load_lds_dwordx4 v170, s[50:51]
	s_add_i32 m0, s8, 0x2000
	s_add_u32 s8, s50, 0xb0000
	s_addc_u32 s9, s51, 0
	s_add_i32 s65, s66, s72
	global_load_lds_dwordx4 v174, s[50:51]
	s_mov_b32 m0, s65
	s_nop 0
	global_load_lds_dwordx4 v170, s[8:9]
	s_add_i32 m0, s65, 0x2000
	s_nop 0
	global_load_lds_dwordx4 v174, s[8:9]
	s_add_u32 s100, s52, s34
	s_addc_u32 s101, s53, s35
	s_mov_b32 m0, s74
	s_nop 0
	global_load_lds_dwordx4 v168, s[52:53]
	s_mov_b32 m0, s75
	s_nop 0
	global_load_lds_dwordx4 v172, s[52:53]
	s_waitcnt vmcnt(8)
	s_waitcnt lgkmcnt(0)
	s_barrier
	s_setprio 1
	v_mfma_f32_16x16x32_bf16 v[60:63], v[128:131], v[160:163], v[60:63]
	v_mfma_f32_16x16x32_bf16 v[56:59], v[136:139], v[160:163], v[56:59]
	v_mfma_f32_16x16x32_bf16 v[44:47], v[128:131], v[186:189], v[44:47]
	v_mfma_f32_16x16x32_bf16 v[40:43], v[136:139], v[186:189], v[40:43]
	v_mfma_f32_16x16x32_bf16 v[28:31], v[128:131], v[194:197], v[28:31]
	v_mfma_f32_16x16x32_bf16 v[24:27], v[136:139], v[194:197], v[24:27]
	v_mfma_f32_16x16x32_bf16 v[12:15], v[128:131], v[202:205], v[12:15]
	v_mfma_f32_16x16x32_bf16 v[8:11], v[136:139], v[202:205], v[8:11]
	v_mfma_f32_16x16x32_bf16 v[60:63], v[132:135], v[164:167], v[60:63]
	v_mfma_f32_16x16x32_bf16 v[56:59], v[140:143], v[164:167], v[56:59]
	v_mfma_f32_16x16x32_bf16 v[44:47], v[132:135], v[190:193], v[44:47]
	v_mfma_f32_16x16x32_bf16 v[40:43], v[140:143], v[190:193], v[40:43]
	v_mfma_f32_16x16x32_bf16 v[28:31], v[132:135], v[198:201], v[28:31]
	v_mfma_f32_16x16x32_bf16 v[24:27], v[140:143], v[198:201], v[24:27]
	v_mfma_f32_16x16x32_bf16 v[12:15], v[132:135], v[206:209], v[12:15]
	v_mfma_f32_16x16x32_bf16 v[8:11], v[140:143], v[206:209], v[8:11]
	v_mfma_f32_16x16x32_bf16 v[52:55], v[144:147], v[160:163], v[52:55]
	v_mfma_f32_16x16x32_bf16 v[48:51], v[152:155], v[160:163], v[48:51]
	v_mfma_f32_16x16x32_bf16 v[36:39], v[144:147], v[186:189], v[36:39]
	v_mfma_f32_16x16x32_bf16 v[32:35], v[152:155], v[186:189], v[32:35]
	v_mfma_f32_16x16x32_bf16 v[20:23], v[144:147], v[194:197], v[20:23]
	v_mfma_f32_16x16x32_bf16 v[16:19], v[152:155], v[194:197], v[16:19]
	v_mfma_f32_16x16x32_bf16 v[4:7], v[144:147], v[202:205], v[4:7]
	v_mfma_f32_16x16x32_bf16 v[0:3], v[152:155], v[202:205], v[0:3]
	v_mfma_f32_16x16x32_bf16 v[52:55], v[148:151], v[164:167], v[52:55]
	v_mfma_f32_16x16x32_bf16 v[48:51], v[156:159], v[164:167], v[48:51]
	v_mfma_f32_16x16x32_bf16 v[36:39], v[148:151], v[190:193], v[36:39]
	v_mfma_f32_16x16x32_bf16 v[32:35], v[156:159], v[190:193], v[32:35]
	s_setprio 2
	s_barrier
	v_mfma_f32_16x16x32_bf16 v[20:23], v[148:151], v[198:201], v[20:23]
	v_mfma_f32_16x16x32_bf16 v[16:19], v[156:159], v[198:201], v[16:19]
	v_mfma_f32_16x16x32_bf16 v[4:7], v[148:151], v[206:209], v[4:7]
	v_mfma_f32_16x16x32_bf16 v[0:3], v[156:159], v[206:209], v[0:3]
	s_setprio 0
	s_add_i32 s65, 0, 0x18000
	s_add_i32 s66, 0, 0x1c000
	v_add_u32_e32 v140, s65, v228
	v_add_u32_e32 v156, s66, v228
	ds_read_b128 v[128:131], v140
	ds_read_b128 v[132:135], v140 offset:1024
	ds_read_b128 v[136:139], v140 offset:2048
	ds_read_b128 v[140:143], v140 offset:3072
	ds_read_b128 v[144:147], v156
	ds_read_b128 v[148:151], v156 offset:1024
	ds_read_b128 v[152:155], v156 offset:2048
	ds_read_b128 v[156:159], v156 offset:3072
	s_add_u32 s8, s52, 0xb0000
	s_addc_u32 s9, s53, 0
	s_mov_b32 m0, s80
	ds_read_b128 v[160:163], v232 offset:32768
	ds_read_b128 v[164:167], v232 offset:33792
	ds_read_b128 v[186:189], v232 offset:34816
	ds_read_b128 v[190:193], v232 offset:35840
	ds_read_b128 v[194:197], v232 offset:36864
	ds_read_b128 v[198:201], v232 offset:37888
	ds_read_b128 v[202:205], v232 offset:38912
	ds_read_b128 v[206:209], v232 offset:39936
	global_load_lds_dwordx4 v168, s[8:9]
	s_mov_b32 m0, s81
	s_nop 0
	global_load_lds_dwordx4 v172, s[8:9]
	s_waitcnt vmcnt(8)
	s_waitcnt lgkmcnt(0)
	s_barrier
	s_setprio 1
	v_mfma_f32_16x16x32_bf16 v[124:127], v[128:131], v[160:163], v[124:127]
	v_mfma_f32_16x16x32_bf16 v[120:123], v[136:139], v[160:163], v[120:123]
	v_mfma_f32_16x16x32_bf16 v[108:111], v[128:131], v[186:189], v[108:111]
	v_mfma_f32_16x16x32_bf16 v[104:107], v[136:139], v[186:189], v[104:107]
	v_mfma_f32_16x16x32_bf16 v[92:95], v[128:131], v[194:197], v[92:95]
	v_mfma_f32_16x16x32_bf16 v[88:91], v[136:139], v[194:197], v[88:91]
	v_mfma_f32_16x16x32_bf16 v[76:79], v[128:131], v[202:205], v[76:79]
	v_mfma_f32_16x16x32_bf16 v[72:75], v[136:139], v[202:205], v[72:75]
	v_mfma_f32_16x16x32_bf16 v[124:127], v[132:135], v[164:167], v[124:127]
	v_mfma_f32_16x16x32_bf16 v[120:123], v[140:143], v[164:167], v[120:123]
	v_mfma_f32_16x16x32_bf16 v[108:111], v[132:135], v[190:193], v[108:111]
	v_mfma_f32_16x16x32_bf16 v[104:107], v[140:143], v[190:193], v[104:107]
	v_mfma_f32_16x16x32_bf16 v[92:95], v[132:135], v[198:201], v[92:95]
	v_mfma_f32_16x16x32_bf16 v[88:91], v[140:143], v[198:201], v[88:91]
	v_mfma_f32_16x16x32_bf16 v[76:79], v[132:135], v[206:209], v[76:79]
	v_mfma_f32_16x16x32_bf16 v[72:75], v[140:143], v[206:209], v[72:75]
	v_mfma_f32_16x16x32_bf16 v[116:119], v[144:147], v[160:163], v[116:119]
	v_mfma_f32_16x16x32_bf16 v[112:115], v[152:155], v[160:163], v[112:115]
	v_mfma_f32_16x16x32_bf16 v[100:103], v[144:147], v[186:189], v[100:103]
	v_mfma_f32_16x16x32_bf16 v[96:99], v[152:155], v[186:189], v[96:99]
	v_mfma_f32_16x16x32_bf16 v[84:87], v[144:147], v[194:197], v[84:87]
	v_mfma_f32_16x16x32_bf16 v[80:83], v[152:155], v[194:197], v[80:83]
	v_mfma_f32_16x16x32_bf16 v[68:71], v[144:147], v[202:205], v[68:71]
	v_mfma_f32_16x16x32_bf16 v[64:67], v[152:155], v[202:205], v[64:67]
	v_mfma_f32_16x16x32_bf16 v[116:119], v[148:151], v[164:167], v[116:119]
	v_mfma_f32_16x16x32_bf16 v[112:115], v[156:159], v[164:167], v[112:115]
	v_mfma_f32_16x16x32_bf16 v[100:103], v[148:151], v[190:193], v[100:103]
	v_mfma_f32_16x16x32_bf16 v[96:99], v[156:159], v[190:193], v[96:99]
	s_setprio 2
	s_barrier
	v_mfma_f32_16x16x32_bf16 v[84:87], v[148:151], v[198:201], v[84:87]
	v_mfma_f32_16x16x32_bf16 v[80:83], v[156:159], v[198:201], v[80:83]
	v_mfma_f32_16x16x32_bf16 v[68:71], v[148:151], v[206:209], v[68:71]
	v_mfma_f32_16x16x32_bf16 v[64:67], v[156:159], v[206:209], v[64:67]
	s_setprio 0
	s_add_i32 s8, s65, s72
	s_mov_b32 m0, s8
	ds_read_b128 v[160:163], v232 offset:49152
	ds_read_b128 v[164:167], v232 offset:50176
	ds_read_b128 v[186:189], v232 offset:51200
	ds_read_b128 v[190:193], v232 offset:52224
	ds_read_b128 v[194:197], v232 offset:53248
	ds_read_b128 v[198:201], v232 offset:54272
	ds_read_b128 v[202:205], v232 offset:55296
	ds_read_b128 v[206:209], v232 offset:56320
	global_load_lds_dwordx4 v170, s[98:99]
	s_add_i32 m0, s8, 0x2000
	s_add_u32 s8, s50, 0xb0080
	s_addc_u32 s9, s51, 0
	s_add_i32 s50, s66, s72
	global_load_lds_dwordx4 v174, s[98:99]
	s_mov_b32 m0, s50
	s_nop 0
	global_load_lds_dwordx4 v170, s[8:9]
	s_add_i32 m0, s50, 0x2000
	s_nop 0
	global_load_lds_dwordx4 v174, s[8:9]
	s_mov_b32 m0, s83
	s_nop 0
	global_load_lds_dwordx4 v168, s[100:101]
	s_mov_b32 m0, s91
	s_nop 0
	global_load_lds_dwordx4 v172, s[100:101]
	s_waitcnt vmcnt(8)
	s_waitcnt lgkmcnt(0)
	s_barrier
	s_setprio 1
	v_mfma_f32_16x16x32_bf16 v[60:63], v[128:131], v[160:163], v[60:63]
	v_mfma_f32_16x16x32_bf16 v[56:59], v[136:139], v[160:163], v[56:59]
	v_mfma_f32_16x16x32_bf16 v[44:47], v[128:131], v[186:189], v[44:47]
	v_mfma_f32_16x16x32_bf16 v[40:43], v[136:139], v[186:189], v[40:43]
	v_mfma_f32_16x16x32_bf16 v[28:31], v[128:131], v[194:197], v[28:31]
	v_mfma_f32_16x16x32_bf16 v[24:27], v[136:139], v[194:197], v[24:27]
	v_mfma_f32_16x16x32_bf16 v[12:15], v[128:131], v[202:205], v[12:15]
	v_mfma_f32_16x16x32_bf16 v[8:11], v[136:139], v[202:205], v[8:11]
	v_mfma_f32_16x16x32_bf16 v[60:63], v[132:135], v[164:167], v[60:63]
	v_mfma_f32_16x16x32_bf16 v[56:59], v[140:143], v[164:167], v[56:59]
	v_mfma_f32_16x16x32_bf16 v[44:47], v[132:135], v[190:193], v[44:47]
	v_mfma_f32_16x16x32_bf16 v[40:43], v[140:143], v[190:193], v[40:43]
	v_mfma_f32_16x16x32_bf16 v[28:31], v[132:135], v[198:201], v[28:31]
	v_mfma_f32_16x16x32_bf16 v[24:27], v[140:143], v[198:201], v[24:27]
	v_mfma_f32_16x16x32_bf16 v[12:15], v[132:135], v[206:209], v[12:15]
	v_mfma_f32_16x16x32_bf16 v[8:11], v[140:143], v[206:209], v[8:11]
	v_mfma_f32_16x16x32_bf16 v[52:55], v[144:147], v[160:163], v[52:55]
	v_mfma_f32_16x16x32_bf16 v[48:51], v[152:155], v[160:163], v[48:51]
	v_mfma_f32_16x16x32_bf16 v[36:39], v[144:147], v[186:189], v[36:39]
	v_mfma_f32_16x16x32_bf16 v[32:35], v[152:155], v[186:189], v[32:35]
	v_mfma_f32_16x16x32_bf16 v[20:23], v[144:147], v[194:197], v[20:23]
	v_mfma_f32_16x16x32_bf16 v[16:19], v[152:155], v[194:197], v[16:19]
	v_mfma_f32_16x16x32_bf16 v[4:7], v[144:147], v[202:205], v[4:7]
	v_mfma_f32_16x16x32_bf16 v[0:3], v[152:155], v[202:205], v[0:3]
	v_mfma_f32_16x16x32_bf16 v[52:55], v[148:151], v[164:167], v[52:55]
	v_mfma_f32_16x16x32_bf16 v[48:51], v[156:159], v[164:167], v[48:51]
	v_mfma_f32_16x16x32_bf16 v[36:39], v[148:151], v[190:193], v[36:39]
	v_mfma_f32_16x16x32_bf16 v[32:35], v[156:159], v[190:193], v[32:35]
	s_setprio 2
	s_barrier
	v_mfma_f32_16x16x32_bf16 v[20:23], v[148:151], v[198:201], v[20:23]
	v_mfma_f32_16x16x32_bf16 v[16:19], v[156:159], v[198:201], v[16:19]
	v_mfma_f32_16x16x32_bf16 v[4:7], v[148:151], v[206:209], v[4:7]
	v_mfma_f32_16x16x32_bf16 v[0:3], v[156:159], v[206:209], v[0:3]
	s_setprio 0
	s_add_u32 vcc_lo, vcc_lo, 0x100
	s_addc_u32 vcc_hi, vcc_hi, 0
	s_cmp_ge_i32 s64, s63
	s_mov_b64 s[8:9], s[40:41]
	s_mov_b32 s50, s64
	s_cbranch_scc0 .LBB0_863

.LBB0_952:
	s_add_u32 s44, s38, 0x180
	s_addc_u32 s53, s39, 0
	s_mov_b32 s83, -2
	s_add_u32 s38, s8, 0x180
	s_addc_u32 s39, s9, 0
	s_add_i32 s64, 0, 0x10000
	s_cmp_eq_u32 s83, 12
	s_cselect_b32 s51, s1, s39
	s_cselect_b32 s50, s0, s38
	s_cselect_b32 s41, s29, s53
	s_cselect_b32 s40, s28, s44
	s_add_i32 s65, 0, 0x14000
	v_add_u32_e32 v68, s64, v228
	v_add_u32_e32 v156, s65, v228
	ds_read_b128 v[56:59], v68
	ds_read_b128 v[60:63], v68 offset:1024
	ds_read_b128 v[64:67], v68 offset:2048
	ds_read_b128 v[68:71], v68 offset:3072
	ds_read_b128 v[144:147], v156
	ds_read_b128 v[148:151], v156 offset:1024
	ds_read_b128 v[152:155], v156 offset:2048
	ds_read_b128 v[156:159], v156 offset:3072
	s_add_i32 m0, s60, 0xc000
	ds_read_b128 v[160:163], v231
	ds_read_b128 v[164:167], v231 offset:1024
	ds_read_b128 v[168:171], v231 offset:2048
	ds_read_b128 v[172:175], v231 offset:3072
	ds_read_b128 v[194:197], v231 offset:4096
	ds_read_b128 v[198:201], v231 offset:5120
	ds_read_b128 v[202:205], v231 offset:6144
	ds_read_b128 v[206:209], v231 offset:7168
	global_load_lds_dwordx4 v192, s[8:9]
	s_add_i32 m0, s60, 0xe000
	s_nop 0
	global_load_lds_dwordx4 v190, s[8:9]
	s_waitcnt vmcnt(24)
	s_waitcnt lgkmcnt(0)
	s_barrier
	s_setprio 1
	v_mfma_f32_16x16x32_bf16 v[140:143], v[56:59], v[160:163], 0
	v_mfma_f32_16x16x32_bf16 v[136:139], v[64:67], v[160:163], 0
	v_mfma_f32_16x16x32_bf16 v[128:131], v[56:59], v[168:171], 0
	v_mfma_f32_16x16x32_bf16 v[120:123], v[64:67], v[168:171], 0
	v_mfma_f32_16x16x32_bf16 v[108:111], v[56:59], v[194:197], 0
	v_mfma_f32_16x16x32_bf16 v[104:107], v[64:67], v[194:197], 0
	v_mfma_f32_16x16x32_bf16 v[92:95], v[56:59], v[202:205], 0
	v_mfma_f32_16x16x32_bf16 v[88:91], v[64:67], v[202:205], 0
	v_mfma_f32_16x16x32_bf16 v[140:143], v[60:63], v[164:167], v[140:143]
	v_mfma_f32_16x16x32_bf16 v[136:139], v[68:71], v[164:167], v[136:139]
	v_mfma_f32_16x16x32_bf16 v[128:131], v[60:63], v[172:175], v[128:131]
	v_mfma_f32_16x16x32_bf16 v[120:123], v[68:71], v[172:175], v[120:123]
	v_mfma_f32_16x16x32_bf16 v[108:111], v[60:63], v[198:201], v[108:111]
	v_mfma_f32_16x16x32_bf16 v[104:107], v[68:71], v[198:201], v[104:107]
	v_mfma_f32_16x16x32_bf16 v[92:95], v[60:63], v[206:209], v[92:95]
	v_mfma_f32_16x16x32_bf16 v[88:91], v[68:71], v[206:209], v[88:91]
	v_mfma_f32_16x16x32_bf16 v[132:135], v[144:147], v[160:163], 0
	v_mfma_f32_16x16x32_bf16 v[124:127], v[152:155], v[160:163], 0
	v_mfma_f32_16x16x32_bf16 v[116:119], v[144:147], v[168:171], 0
	v_mfma_f32_16x16x32_bf16 v[112:115], v[152:155], v[168:171], 0
	v_mfma_f32_16x16x32_bf16 v[100:103], v[144:147], v[194:197], 0
	v_mfma_f32_16x16x32_bf16 v[96:99], v[152:155], v[194:197], 0
	v_mfma_f32_16x16x32_bf16 v[84:87], v[144:147], v[202:205], 0
	v_mfma_f32_16x16x32_bf16 v[80:83], v[152:155], v[202:205], 0
	v_mfma_f32_16x16x32_bf16 v[132:135], v[148:151], v[164:167], v[132:135]
	v_mfma_f32_16x16x32_bf16 v[124:127], v[156:159], v[164:167], v[124:127]
	v_mfma_f32_16x16x32_bf16 v[116:119], v[148:151], v[172:175], v[116:119]
	v_mfma_f32_16x16x32_bf16 v[112:115], v[156:159], v[172:175], v[112:115]
	s_setprio 2
	s_barrier
	v_mfma_f32_16x16x32_bf16 v[100:103], v[148:151], v[198:201], v[100:103]
	v_mfma_f32_16x16x32_bf16 v[96:99], v[156:159], v[198:201], v[96:99]
	v_mfma_f32_16x16x32_bf16 v[84:87], v[148:151], v[206:209], v[84:87]
	v_mfma_f32_16x16x32_bf16 v[80:83], v[156:159], v[206:209], v[80:83]
	s_setprio 0
	s_add_i32 s8, s64, s37
	s_add_u32 s98, s40, s34
	s_addc_u32 s99, s41, s35
	s_mov_b32 m0, s8
	ds_read_b128 v[160:163], v231 offset:16384
	ds_read_b128 v[164:167], v231 offset:17408
	ds_read_b128 v[168:171], v231 offset:18432
	ds_read_b128 v[172:175], v231 offset:19456
	ds_read_b128 v[194:197], v231 offset:20480
	ds_read_b128 v[198:201], v231 offset:21504
	ds_read_b128 v[202:205], v231 offset:22528
	ds_read_b128 v[206:209], v231 offset:23552
	global_load_lds_dwordx4 v184, s[40:41]
	s_add_i32 m0, s8, 0x2000
	s_add_u32 s8, s40, 0x60000
	s_addc_u32 s9, s41, 0
	s_add_i32 s64, s65, s37
	global_load_lds_dwordx4 v188, s[40:41]
	s_mov_b32 m0, s64
	s_nop 0
	global_load_lds_dwordx4 v184, s[8:9]
	s_add_i32 m0, s64, 0x2000
	s_nop 0
	global_load_lds_dwordx4 v188, s[8:9]
	s_add_u32 s100, s50, s34
	s_addc_u32 s101, s51, s35
	s_mov_b32 m0, s60
	s_nop 0
	global_load_lds_dwordx4 v182, s[50:51]
	s_mov_b32 m0, s61
	s_nop 0
	global_load_lds_dwordx4 v186, s[50:51]
	s_waitcnt vmcnt(8)
	s_waitcnt lgkmcnt(0)
	s_barrier
	s_setprio 1
	v_mfma_f32_16x16x32_bf16 v[76:79], v[56:59], v[160:163], 0
	v_mfma_f32_16x16x32_bf16 v[72:75], v[64:67], v[160:163], 0
	v_mfma_f32_16x16x32_bf16 v[44:47], v[56:59], v[168:171], 0
	v_mfma_f32_16x16x32_bf16 v[40:43], v[64:67], v[168:171], 0
	v_mfma_f32_16x16x32_bf16 v[28:31], v[56:59], v[194:197], 0
	v_mfma_f32_16x16x32_bf16 v[24:27], v[64:67], v[194:197], 0
	v_mfma_f32_16x16x32_bf16 v[12:15], v[56:59], v[202:205], 0
	v_mfma_f32_16x16x32_bf16 v[8:11], v[64:67], v[202:205], 0
	v_mfma_f32_16x16x32_bf16 v[76:79], v[60:63], v[164:167], v[76:79]
	v_mfma_f32_16x16x32_bf16 v[72:75], v[68:71], v[164:167], v[72:75]
	v_mfma_f32_16x16x32_bf16 v[44:47], v[60:63], v[172:175], v[44:47]
	v_mfma_f32_16x16x32_bf16 v[40:43], v[68:71], v[172:175], v[40:43]
	v_mfma_f32_16x16x32_bf16 v[28:31], v[60:63], v[198:201], v[28:31]
	v_mfma_f32_16x16x32_bf16 v[24:27], v[68:71], v[198:201], v[24:27]
	v_mfma_f32_16x16x32_bf16 v[12:15], v[60:63], v[206:209], v[12:15]
	v_mfma_f32_16x16x32_bf16 v[8:11], v[68:71], v[206:209], v[8:11]
	v_mfma_f32_16x16x32_bf16 v[52:55], v[144:147], v[160:163], 0
	v_mfma_f32_16x16x32_bf16 v[48:51], v[152:155], v[160:163], 0
	v_mfma_f32_16x16x32_bf16 v[36:39], v[144:147], v[168:171], 0
	v_mfma_f32_16x16x32_bf16 v[32:35], v[152:155], v[168:171], 0
	v_mfma_f32_16x16x32_bf16 v[20:23], v[144:147], v[194:197], 0
	v_mfma_f32_16x16x32_bf16 v[16:19], v[152:155], v[194:197], 0
	v_mfma_f32_16x16x32_bf16 v[4:7], v[144:147], v[202:205], 0
	v_mfma_f32_16x16x32_bf16 v[0:3], v[152:155], v[202:205], 0
	v_mfma_f32_16x16x32_bf16 v[52:55], v[148:151], v[164:167], v[52:55]
	v_mfma_f32_16x16x32_bf16 v[48:51], v[156:159], v[164:167], v[48:51]
	v_mfma_f32_16x16x32_bf16 v[36:39], v[148:151], v[172:175], v[36:39]
	v_mfma_f32_16x16x32_bf16 v[32:35], v[156:159], v[172:175], v[32:35]
	s_setprio 2
	s_barrier
	v_mfma_f32_16x16x32_bf16 v[20:23], v[148:151], v[198:201], v[20:23]
	v_mfma_f32_16x16x32_bf16 v[16:19], v[156:159], v[198:201], v[16:19]
	v_mfma_f32_16x16x32_bf16 v[4:7], v[148:151], v[206:209], v[4:7]
	v_mfma_f32_16x16x32_bf16 v[0:3], v[156:159], v[206:209], v[0:3]
	s_setprio 0
	s_add_i32 s64, 0, 0x18000
	s_add_i32 s65, 0, 0x1c000
	v_add_u32_e32 v68, s64, v228
	v_add_u32_e32 v156, s65, v228
	ds_read_b128 v[56:59], v68
	ds_read_b128 v[60:63], v68 offset:1024
	ds_read_b128 v[64:67], v68 offset:2048
	ds_read_b128 v[68:71], v68 offset:3072
	ds_read_b128 v[144:147], v156
	ds_read_b128 v[148:151], v156 offset:1024
	ds_read_b128 v[152:155], v156 offset:2048
	ds_read_b128 v[156:159], v156 offset:3072
	s_add_u32 s8, s50, 0x60000
	s_addc_u32 s9, s51, 0
	s_mov_b32 m0, s62
	ds_read_b128 v[160:163], v231 offset:32768
	ds_read_b128 v[164:167], v231 offset:33792
	ds_read_b128 v[168:171], v231 offset:34816
	ds_read_b128 v[172:175], v231 offset:35840
	ds_read_b128 v[194:197], v231 offset:36864
	ds_read_b128 v[198:201], v231 offset:37888
	ds_read_b128 v[202:205], v231 offset:38912
	ds_read_b128 v[206:209], v231 offset:39936
	global_load_lds_dwordx4 v182, s[8:9]
	s_mov_b32 m0, s63
	s_nop 0
	global_load_lds_dwordx4 v186, s[8:9]
	s_waitcnt vmcnt(8)
	s_waitcnt lgkmcnt(0)
	s_barrier
	s_setprio 1
	v_mfma_f32_16x16x32_bf16 v[140:143], v[56:59], v[160:163], v[140:143]
	v_mfma_f32_16x16x32_bf16 v[136:139], v[64:67], v[160:163], v[136:139]
	v_mfma_f32_16x16x32_bf16 v[128:131], v[56:59], v[168:171], v[128:131]
	v_mfma_f32_16x16x32_bf16 v[120:123], v[64:67], v[168:171], v[120:123]
	v_mfma_f32_16x16x32_bf16 v[108:111], v[56:59], v[194:197], v[108:111]
	v_mfma_f32_16x16x32_bf16 v[104:107], v[64:67], v[194:197], v[104:107]
	v_mfma_f32_16x16x32_bf16 v[92:95], v[56:59], v[202:205], v[92:95]
	v_mfma_f32_16x16x32_bf16 v[88:91], v[64:67], v[202:205], v[88:91]
	v_mfma_f32_16x16x32_bf16 v[140:143], v[60:63], v[164:167], v[140:143]
	v_mfma_f32_16x16x32_bf16 v[136:139], v[68:71], v[164:167], v[136:139]
	v_mfma_f32_16x16x32_bf16 v[128:131], v[60:63], v[172:175], v[128:131]
	v_mfma_f32_16x16x32_bf16 v[120:123], v[68:71], v[172:175], v[120:123]
	v_mfma_f32_16x16x32_bf16 v[108:111], v[60:63], v[198:201], v[108:111]
	v_mfma_f32_16x16x32_bf16 v[104:107], v[68:71], v[198:201], v[104:107]
	v_mfma_f32_16x16x32_bf16 v[92:95], v[60:63], v[206:209], v[92:95]
	v_mfma_f32_16x16x32_bf16 v[88:91], v[68:71], v[206:209], v[88:91]
	v_mfma_f32_16x16x32_bf16 v[132:135], v[144:147], v[160:163], v[132:135]
	v_mfma_f32_16x16x32_bf16 v[124:127], v[152:155], v[160:163], v[124:127]
	v_mfma_f32_16x16x32_bf16 v[116:119], v[144:147], v[168:171], v[116:119]
	v_mfma_f32_16x16x32_bf16 v[112:115], v[152:155], v[168:171], v[112:115]
	v_mfma_f32_16x16x32_bf16 v[100:103], v[144:147], v[194:197], v[100:103]
	v_mfma_f32_16x16x32_bf16 v[96:99], v[152:155], v[194:197], v[96:99]
	v_mfma_f32_16x16x32_bf16 v[84:87], v[144:147], v[202:205], v[84:87]
	v_mfma_f32_16x16x32_bf16 v[80:83], v[152:155], v[202:205], v[80:83]
	v_mfma_f32_16x16x32_bf16 v[132:135], v[148:151], v[164:167], v[132:135]
	v_mfma_f32_16x16x32_bf16 v[124:127], v[156:159], v[164:167], v[124:127]
	v_mfma_f32_16x16x32_bf16 v[116:119], v[148:151], v[172:175], v[116:119]
	v_mfma_f32_16x16x32_bf16 v[112:115], v[156:159], v[172:175], v[112:115]
	s_setprio 2
	s_barrier
	v_mfma_f32_16x16x32_bf16 v[100:103], v[148:151], v[198:201], v[100:103]
	v_mfma_f32_16x16x32_bf16 v[96:99], v[156:159], v[198:201], v[96:99]
	v_mfma_f32_16x16x32_bf16 v[84:87], v[148:151], v[206:209], v[84:87]
	v_mfma_f32_16x16x32_bf16 v[80:83], v[156:159], v[206:209], v[80:83]
	s_setprio 0
	s_add_i32 s8, s64, s37
	s_mov_b32 m0, s8
	ds_read_b128 v[160:163], v231 offset:49152
	ds_read_b128 v[164:167], v231 offset:50176
	ds_read_b128 v[168:171], v231 offset:51200
	ds_read_b128 v[172:175], v231 offset:52224
	ds_read_b128 v[194:197], v231 offset:53248
	ds_read_b128 v[198:201], v231 offset:54272
	ds_read_b128 v[202:205], v231 offset:55296
	ds_read_b128 v[206:209], v231 offset:56320
	global_load_lds_dwordx4 v184, s[98:99]
	s_add_i32 m0, s8, 0x2000
	s_add_u32 s8, s40, 0x60080
	s_addc_u32 s9, s41, 0
	s_add_i32 s40, s65, s37
	global_load_lds_dwordx4 v188, s[98:99]
	s_mov_b32 m0, s40
	s_nop 0
	global_load_lds_dwordx4 v184, s[8:9]
	s_add_i32 m0, s40, 0x2000
	s_nop 0
	global_load_lds_dwordx4 v188, s[8:9]
	s_mov_b32 m0, s69
	s_nop 0
	global_load_lds_dwordx4 v182, s[100:101]
	s_mov_b32 m0, s72
	s_nop 0
	global_load_lds_dwordx4 v186, s[100:101]
	s_waitcnt vmcnt(8)
	s_waitcnt lgkmcnt(0)
	s_barrier
	s_setprio 1
	v_mfma_f32_16x16x32_bf16 v[76:79], v[56:59], v[160:163], v[76:79]
	v_mfma_f32_16x16x32_bf16 v[72:75], v[64:67], v[160:163], v[72:75]
	v_mfma_f32_16x16x32_bf16 v[44:47], v[56:59], v[168:171], v[44:47]
	v_mfma_f32_16x16x32_bf16 v[40:43], v[64:67], v[168:171], v[40:43]
	v_mfma_f32_16x16x32_bf16 v[28:31], v[56:59], v[194:197], v[28:31]
	v_mfma_f32_16x16x32_bf16 v[24:27], v[64:67], v[194:197], v[24:27]
	v_mfma_f32_16x16x32_bf16 v[12:15], v[56:59], v[202:205], v[12:15]
	v_mfma_f32_16x16x32_bf16 v[8:11], v[64:67], v[202:205], v[8:11]
	v_mfma_f32_16x16x32_bf16 v[76:79], v[60:63], v[164:167], v[76:79]
	v_mfma_f32_16x16x32_bf16 v[72:75], v[68:71], v[164:167], v[72:75]
	v_mfma_f32_16x16x32_bf16 v[44:47], v[60:63], v[172:175], v[44:47]
	v_mfma_f32_16x16x32_bf16 v[40:43], v[68:71], v[172:175], v[40:43]
	v_mfma_f32_16x16x32_bf16 v[28:31], v[60:63], v[198:201], v[28:31]
	v_mfma_f32_16x16x32_bf16 v[24:27], v[68:71], v[198:201], v[24:27]
	v_mfma_f32_16x16x32_bf16 v[12:15], v[60:63], v[206:209], v[12:15]
	v_mfma_f32_16x16x32_bf16 v[8:11], v[68:71], v[206:209], v[8:11]
	v_mfma_f32_16x16x32_bf16 v[52:55], v[144:147], v[160:163], v[52:55]
	v_mfma_f32_16x16x32_bf16 v[48:51], v[152:155], v[160:163], v[48:51]
	v_mfma_f32_16x16x32_bf16 v[36:39], v[144:147], v[168:171], v[36:39]
	v_mfma_f32_16x16x32_bf16 v[32:35], v[152:155], v[168:171], v[32:35]
	v_mfma_f32_16x16x32_bf16 v[20:23], v[144:147], v[194:197], v[20:23]
	v_mfma_f32_16x16x32_bf16 v[16:19], v[152:155], v[194:197], v[16:19]
	v_mfma_f32_16x16x32_bf16 v[4:7], v[144:147], v[202:205], v[4:7]
	v_mfma_f32_16x16x32_bf16 v[0:3], v[152:155], v[202:205], v[0:3]
	v_mfma_f32_16x16x32_bf16 v[52:55], v[148:151], v[164:167], v[52:55]
	v_mfma_f32_16x16x32_bf16 v[48:51], v[156:159], v[164:167], v[48:51]
	v_mfma_f32_16x16x32_bf16 v[36:39], v[148:151], v[172:175], v[36:39]
	v_mfma_f32_16x16x32_bf16 v[32:35], v[156:159], v[172:175], v[32:35]
	s_setprio 2
	s_barrier
	v_mfma_f32_16x16x32_bf16 v[20:23], v[148:151], v[198:201], v[20:23]
	v_mfma_f32_16x16x32_bf16 v[16:19], v[156:159], v[198:201], v[16:19]
	v_mfma_f32_16x16x32_bf16 v[4:7], v[148:151], v[206:209], v[4:7]
	v_mfma_f32_16x16x32_bf16 v[0:3], v[156:159], v[206:209], v[0:3]
	s_setprio 0
	s_add_i32 s83, s83, 2
	s_add_u32 s44, s44, 0x180
	s_addc_u32 s53, s53, 0
	s_cmp_gt_u32 s83, 13
	s_mov_b64 s[8:9], s[38:39]
	s_cbranch_scc1 .Lpeel_exit_4
.LBB0_953:
	s_add_u32 s38, s8, 0x180
	s_addc_u32 s39, s9, 0
	s_add_i32 s64, 0, 0x10000
	s_cmp_eq_u32 s83, 12
	s_cselect_b32 s51, s1, s39
	s_cselect_b32 s50, s0, s38
	s_cselect_b32 s41, s29, s53
	s_cselect_b32 s40, s28, s44
	s_add_i32 s65, 0, 0x14000
	v_add_u32_e32 v68, s64, v228
	v_add_u32_e32 v156, s65, v228
	ds_read_b128 v[56:59], v68
	ds_read_b128 v[60:63], v68 offset:1024
	ds_read_b128 v[64:67], v68 offset:2048
	ds_read_b128 v[68:71], v68 offset:3072
	ds_read_b128 v[144:147], v156
	ds_read_b128 v[148:151], v156 offset:1024
	ds_read_b128 v[152:155], v156 offset:2048
	ds_read_b128 v[156:159], v156 offset:3072
	s_add_i32 m0, s60, 0xc000
	ds_read_b128 v[160:163], v231
	ds_read_b128 v[164:167], v231 offset:1024
	ds_read_b128 v[168:171], v231 offset:2048
	ds_read_b128 v[172:175], v231 offset:3072
	ds_read_b128 v[194:197], v231 offset:4096
	ds_read_b128 v[198:201], v231 offset:5120
	ds_read_b128 v[202:205], v231 offset:6144
	ds_read_b128 v[206:209], v231 offset:7168
	global_load_lds_dwordx4 v192, s[8:9]
	s_add_i32 m0, s60, 0xe000
	s_nop 0
	global_load_lds_dwordx4 v190, s[8:9]
	s_waitcnt vmcnt(8)
	s_waitcnt lgkmcnt(0)
	s_barrier
	s_setprio 1
	v_mfma_f32_16x16x32_bf16 v[140:143], v[56:59], v[160:163], v[140:143]
	v_mfma_f32_16x16x32_bf16 v[136:139], v[64:67], v[160:163], v[136:139]
	v_mfma_f32_16x16x32_bf16 v[128:131], v[56:59], v[168:171], v[128:131]
	v_mfma_f32_16x16x32_bf16 v[120:123], v[64:67], v[168:171], v[120:123]
	v_mfma_f32_16x16x32_bf16 v[108:111], v[56:59], v[194:197], v[108:111]
	v_mfma_f32_16x16x32_bf16 v[104:107], v[64:67], v[194:197], v[104:107]
	v_mfma_f32_16x16x32_bf16 v[92:95], v[56:59], v[202:205], v[92:95]
	v_mfma_f32_16x16x32_bf16 v[88:91], v[64:67], v[202:205], v[88:91]
	v_mfma_f32_16x16x32_bf16 v[140:143], v[60:63], v[164:167], v[140:143]
	v_mfma_f32_16x16x32_bf16 v[136:139], v[68:71], v[164:167], v[136:139]
	v_mfma_f32_16x16x32_bf16 v[128:131], v[60:63], v[172:175], v[128:131]
	v_mfma_f32_16x16x32_bf16 v[120:123], v[68:71], v[172:175], v[120:123]
	v_mfma_f32_16x16x32_bf16 v[108:111], v[60:63], v[198:201], v[108:111]
	v_mfma_f32_16x16x32_bf16 v[104:107], v[68:71], v[198:201], v[104:107]
	v_mfma_f32_16x16x32_bf16 v[92:95], v[60:63], v[206:209], v[92:95]
	v_mfma_f32_16x16x32_bf16 v[88:91], v[68:71], v[206:209], v[88:91]
	v_mfma_f32_16x16x32_bf16 v[132:135], v[144:147], v[160:163], v[132:135]
	v_mfma_f32_16x16x32_bf16 v[124:127], v[152:155], v[160:163], v[124:127]
	v_mfma_f32_16x16x32_bf16 v[116:119], v[144:147], v[168:171], v[116:119]
	v_mfma_f32_16x16x32_bf16 v[112:115], v[152:155], v[168:171], v[112:115]
	v_mfma_f32_16x16x32_bf16 v[100:103], v[144:147], v[194:197], v[100:103]
	v_mfma_f32_16x16x32_bf16 v[96:99], v[152:155], v[194:197], v[96:99]
	v_mfma_f32_16x16x32_bf16 v[84:87], v[144:147], v[202:205], v[84:87]
	v_mfma_f32_16x16x32_bf16 v[80:83], v[152:155], v[202:205], v[80:83]
	v_mfma_f32_16x16x32_bf16 v[132:135], v[148:151], v[164:167], v[132:135]
	v_mfma_f32_16x16x32_bf16 v[124:127], v[156:159], v[164:167], v[124:127]
	v_mfma_f32_16x16x32_bf16 v[116:119], v[148:151], v[172:175], v[116:119]
	v_mfma_f32_16x16x32_bf16 v[112:115], v[156:159], v[172:175], v[112:115]
	s_setprio 2
	s_barrier
	v_mfma_f32_16x16x32_bf16 v[100:103], v[148:151], v[198:201], v[100:103]
	v_mfma_f32_16x16x32_bf16 v[96:99], v[156:159], v[198:201], v[96:99]
	v_mfma_f32_16x16x32_bf16 v[84:87], v[148:151], v[206:209], v[84:87]
	v_mfma_f32_16x16x32_bf16 v[80:83], v[156:159], v[206:209], v[80:83]
	s_setprio 0
	s_add_i32 s8, s64, s37
	s_add_u32 s98, s40, s34
	s_addc_u32 s99, s41, s35
	s_mov_b32 m0, s8
	ds_read_b128 v[160:163], v231 offset:16384
	ds_read_b128 v[164:167], v231 offset:17408
	ds_read_b128 v[168:171], v231 offset:18432
	ds_read_b128 v[172:175], v231 offset:19456
	ds_read_b128 v[194:197], v231 offset:20480
	ds_read_b128 v[198:201], v231 offset:21504
	ds_read_b128 v[202:205], v231 offset:22528
	ds_read_b128 v[206:209], v231 offset:23552
	global_load_lds_dwordx4 v184, s[40:41]
	s_add_i32 m0, s8, 0x2000
	s_add_u32 s8, s40, 0x60000
	s_addc_u32 s9, s41, 0
	s_add_i32 s64, s65, s37
	global_load_lds_dwordx4 v188, s[40:41]
	s_mov_b32 m0, s64
	s_nop 0
	global_load_lds_dwordx4 v184, s[8:9]
	s_add_i32 m0, s64, 0x2000
	s_nop 0
	global_load_lds_dwordx4 v188, s[8:9]
	s_add_u32 s100, s50, s34
	s_addc_u32 s101, s51, s35
	s_mov_b32 m0, s60
	s_nop 0
	global_load_lds_dwordx4 v182, s[50:51]
	s_mov_b32 m0, s61
	s_nop 0
	global_load_lds_dwordx4 v186, s[50:51]
	s_waitcnt vmcnt(8)
	s_waitcnt lgkmcnt(0)
	s_barrier
	s_setprio 1
	v_mfma_f32_16x16x32_bf16 v[76:79], v[56:59], v[160:163], v[76:79]
	v_mfma_f32_16x16x32_bf16 v[72:75], v[64:67], v[160:163], v[72:75]
	v_mfma_f32_16x16x32_bf16 v[44:47], v[56:59], v[168:171], v[44:47]
	v_mfma_f32_16x16x32_bf16 v[40:43], v[64:67], v[168:171], v[40:43]
	v_mfma_f32_16x16x32_bf16 v[28:31], v[56:59], v[194:197], v[28:31]
	v_mfma_f32_16x16x32_bf16 v[24:27], v[64:67], v[194:197], v[24:27]
	v_mfma_f32_16x16x32_bf16 v[12:15], v[56:59], v[202:205], v[12:15]
	v_mfma_f32_16x16x32_bf16 v[8:11], v[64:67], v[202:205], v[8:11]
	v_mfma_f32_16x16x32_bf16 v[76:79], v[60:63], v[164:167], v[76:79]
	v_mfma_f32_16x16x32_bf16 v[72:75], v[68:71], v[164:167], v[72:75]
	v_mfma_f32_16x16x32_bf16 v[44:47], v[60:63], v[172:175], v[44:47]
	v_mfma_f32_16x16x32_bf16 v[40:43], v[68:71], v[172:175], v[40:43]
	v_mfma_f32_16x16x32_bf16 v[28:31], v[60:63], v[198:201], v[28:31]
	v_mfma_f32_16x16x32_bf16 v[24:27], v[68:71], v[198:201], v[24:27]
	v_mfma_f32_16x16x32_bf16 v[12:15], v[60:63], v[206:209], v[12:15]
	v_mfma_f32_16x16x32_bf16 v[8:11], v[68:71], v[206:209], v[8:11]
	v_mfma_f32_16x16x32_bf16 v[52:55], v[144:147], v[160:163], v[52:55]
	v_mfma_f32_16x16x32_bf16 v[48:51], v[152:155], v[160:163], v[48:51]
	v_mfma_f32_16x16x32_bf16 v[36:39], v[144:147], v[168:171], v[36:39]
	v_mfma_f32_16x16x32_bf16 v[32:35], v[152:155], v[168:171], v[32:35]
	v_mfma_f32_16x16x32_bf16 v[20:23], v[144:147], v[194:197], v[20:23]
	v_mfma_f32_16x16x32_bf16 v[16:19], v[152:155], v[194:197], v[16:19]
	v_mfma_f32_16x16x32_bf16 v[4:7], v[144:147], v[202:205], v[4:7]
	v_mfma_f32_16x16x32_bf16 v[0:3], v[152:155], v[202:205], v[0:3]
	v_mfma_f32_16x16x32_bf16 v[52:55], v[148:151], v[164:167], v[52:55]
	v_mfma_f32_16x16x32_bf16 v[48:51], v[156:159], v[164:167], v[48:51]
	v_mfma_f32_16x16x32_bf16 v[36:39], v[148:151], v[172:175], v[36:39]
	v_mfma_f32_16x16x32_bf16 v[32:35], v[156:159], v[172:175], v[32:35]
	s_setprio 2
	s_barrier
	v_mfma_f32_16x16x32_bf16 v[20:23], v[148:151], v[198:201], v[20:23]
	v_mfma_f32_16x16x32_bf16 v[16:19], v[156:159], v[198:201], v[16:19]
	v_mfma_f32_16x16x32_bf16 v[4:7], v[148:151], v[206:209], v[4:7]
	v_mfma_f32_16x16x32_bf16 v[0:3], v[156:159], v[206:209], v[0:3]
	s_setprio 0
	s_add_i32 s64, 0, 0x18000
	s_add_i32 s65, 0, 0x1c000
	v_add_u32_e32 v68, s64, v228
	v_add_u32_e32 v156, s65, v228
	ds_read_b128 v[56:59], v68
	ds_read_b128 v[60:63], v68 offset:1024
	ds_read_b128 v[64:67], v68 offset:2048
	ds_read_b128 v[68:71], v68 offset:3072
	ds_read_b128 v[144:147], v156
	ds_read_b128 v[148:151], v156 offset:1024
	ds_read_b128 v[152:155], v156 offset:2048
	ds_read_b128 v[156:159], v156 offset:3072
	s_add_u32 s8, s50, 0x60000
	s_addc_u32 s9, s51, 0
	s_mov_b32 m0, s62
	ds_read_b128 v[160:163], v231 offset:32768
	ds_read_b128 v[164:167], v231 offset:33792
	ds_read_b128 v[168:171], v231 offset:34816
	ds_read_b128 v[172:175], v231 offset:35840
	ds_read_b128 v[194:197], v231 offset:36864
	ds_read_b128 v[198:201], v231 offset:37888
	ds_read_b128 v[202:205], v231 offset:38912
	ds_read_b128 v[206:209], v231 offset:39936
	global_load_lds_dwordx4 v182, s[8:9]
	s_mov_b32 m0, s63
	s_nop 0
	global_load_lds_dwordx4 v186, s[8:9]
	s_waitcnt vmcnt(8)
	s_waitcnt lgkmcnt(0)
	s_barrier
	s_setprio 1
	v_mfma_f32_16x16x32_bf16 v[140:143], v[56:59], v[160:163], v[140:143]
	v_mfma_f32_16x16x32_bf16 v[136:139], v[64:67], v[160:163], v[136:139]
	v_mfma_f32_16x16x32_bf16 v[128:131], v[56:59], v[168:171], v[128:131]
	v_mfma_f32_16x16x32_bf16 v[120:123], v[64:67], v[168:171], v[120:123]
	v_mfma_f32_16x16x32_bf16 v[108:111], v[56:59], v[194:197], v[108:111]
	v_mfma_f32_16x16x32_bf16 v[104:107], v[64:67], v[194:197], v[104:107]
	v_mfma_f32_16x16x32_bf16 v[92:95], v[56:59], v[202:205], v[92:95]
	v_mfma_f32_16x16x32_bf16 v[88:91], v[64:67], v[202:205], v[88:91]
	v_mfma_f32_16x16x32_bf16 v[140:143], v[60:63], v[164:167], v[140:143]
	v_mfma_f32_16x16x32_bf16 v[136:139], v[68:71], v[164:167], v[136:139]
	v_mfma_f32_16x16x32_bf16 v[128:131], v[60:63], v[172:175], v[128:131]
	v_mfma_f32_16x16x32_bf16 v[120:123], v[68:71], v[172:175], v[120:123]
	v_mfma_f32_16x16x32_bf16 v[108:111], v[60:63], v[198:201], v[108:111]
	v_mfma_f32_16x16x32_bf16 v[104:107], v[68:71], v[198:201], v[104:107]
	v_mfma_f32_16x16x32_bf16 v[92:95], v[60:63], v[206:209], v[92:95]
	v_mfma_f32_16x16x32_bf16 v[88:91], v[68:71], v[206:209], v[88:91]
	v_mfma_f32_16x16x32_bf16 v[132:135], v[144:147], v[160:163], v[132:135]
	v_mfma_f32_16x16x32_bf16 v[124:127], v[152:155], v[160:163], v[124:127]
	v_mfma_f32_16x16x32_bf16 v[116:119], v[144:147], v[168:171], v[116:119]
	v_mfma_f32_16x16x32_bf16 v[112:115], v[152:155], v[168:171], v[112:115]
	v_mfma_f32_16x16x32_bf16 v[100:103], v[144:147], v[194:197], v[100:103]
	v_mfma_f32_16x16x32_bf16 v[96:99], v[152:155], v[194:197], v[96:99]
	v_mfma_f32_16x16x32_bf16 v[84:87], v[144:147], v[202:205], v[84:87]
	v_mfma_f32_16x16x32_bf16 v[80:83], v[152:155], v[202:205], v[80:83]
	v_mfma_f32_16x16x32_bf16 v[132:135], v[148:151], v[164:167], v[132:135]
	v_mfma_f32_16x16x32_bf16 v[124:127], v[156:159], v[164:167], v[124:127]
	v_mfma_f32_16x16x32_bf16 v[116:119], v[148:151], v[172:175], v[116:119]
	v_mfma_f32_16x16x32_bf16 v[112:115], v[156:159], v[172:175], v[112:115]
	s_setprio 2
	s_barrier
	v_mfma_f32_16x16x32_bf16 v[100:103], v[148:151], v[198:201], v[100:103]
	v_mfma_f32_16x16x32_bf16 v[96:99], v[156:159], v[198:201], v[96:99]
	v_mfma_f32_16x16x32_bf16 v[84:87], v[148:151], v[206:209], v[84:87]
	v_mfma_f32_16x16x32_bf16 v[80:83], v[156:159], v[206:209], v[80:83]
	s_setprio 0
	s_add_i32 s8, s64, s37
	s_mov_b32 m0, s8
	ds_read_b128 v[160:163], v231 offset:49152
	ds_read_b128 v[164:167], v231 offset:50176
	ds_read_b128 v[168:171], v231 offset:51200
	ds_read_b128 v[172:175], v231 offset:52224
	ds_read_b128 v[194:197], v231 offset:53248
	ds_read_b128 v[198:201], v231 offset:54272
	ds_read_b128 v[202:205], v231 offset:55296
	ds_read_b128 v[206:209], v231 offset:56320
	global_load_lds_dwordx4 v184, s[98:99]
	s_add_i32 m0, s8, 0x2000
	s_add_u32 s8, s40, 0x60080
	s_addc_u32 s9, s41, 0
	s_add_i32 s40, s65, s37
	global_load_lds_dwordx4 v188, s[98:99]
	s_mov_b32 m0, s40
	s_nop 0
	global_load_lds_dwordx4 v184, s[8:9]
	s_add_i32 m0, s40, 0x2000
	s_nop 0
	global_load_lds_dwordx4 v188, s[8:9]
	s_mov_b32 m0, s69
	s_nop 0
	global_load_lds_dwordx4 v182, s[100:101]
	s_mov_b32 m0, s72
	s_nop 0
	global_load_lds_dwordx4 v186, s[100:101]
	s_waitcnt vmcnt(8)
	s_waitcnt lgkmcnt(0)
	s_barrier
	s_setprio 1
	v_mfma_f32_16x16x32_bf16 v[76:79], v[56:59], v[160:163], v[76:79]
	v_mfma_f32_16x16x32_bf16 v[72:75], v[64:67], v[160:163], v[72:75]
	v_mfma_f32_16x16x32_bf16 v[44:47], v[56:59], v[168:171], v[44:47]
	v_mfma_f32_16x16x32_bf16 v[40:43], v[64:67], v[168:171], v[40:43]
	v_mfma_f32_16x16x32_bf16 v[28:31], v[56:59], v[194:197], v[28:31]
	v_mfma_f32_16x16x32_bf16 v[24:27], v[64:67], v[194:197], v[24:27]
	v_mfma_f32_16x16x32_bf16 v[12:15], v[56:59], v[202:205], v[12:15]
	v_mfma_f32_16x16x32_bf16 v[8:11], v[64:67], v[202:205], v[8:11]
	v_mfma_f32_16x16x32_bf16 v[76:79], v[60:63], v[164:167], v[76:79]
	v_mfma_f32_16x16x32_bf16 v[72:75], v[68:71], v[164:167], v[72:75]
	v_mfma_f32_16x16x32_bf16 v[44:47], v[60:63], v[172:175], v[44:47]
	v_mfma_f32_16x16x32_bf16 v[40:43], v[68:71], v[172:175], v[40:43]
	v_mfma_f32_16x16x32_bf16 v[28:31], v[60:63], v[198:201], v[28:31]
	v_mfma_f32_16x16x32_bf16 v[24:27], v[68:71], v[198:201], v[24:27]
	v_mfma_f32_16x16x32_bf16 v[12:15], v[60:63], v[206:209], v[12:15]
	v_mfma_f32_16x16x32_bf16 v[8:11], v[68:71], v[206:209], v[8:11]
	v_mfma_f32_16x16x32_bf16 v[52:55], v[144:147], v[160:163], v[52:55]
	v_mfma_f32_16x16x32_bf16 v[48:51], v[152:155], v[160:163], v[48:51]
	v_mfma_f32_16x16x32_bf16 v[36:39], v[144:147], v[168:171], v[36:39]
	v_mfma_f32_16x16x32_bf16 v[32:35], v[152:155], v[168:171], v[32:35]
	v_mfma_f32_16x16x32_bf16 v[20:23], v[144:147], v[194:197], v[20:23]
	v_mfma_f32_16x16x32_bf16 v[16:19], v[152:155], v[194:197], v[16:19]
	v_mfma_f32_16x16x32_bf16 v[4:7], v[144:147], v[202:205], v[4:7]
	v_mfma_f32_16x16x32_bf16 v[0:3], v[152:155], v[202:205], v[0:3]
	v_mfma_f32_16x16x32_bf16 v[52:55], v[148:151], v[164:167], v[52:55]
	v_mfma_f32_16x16x32_bf16 v[48:51], v[156:159], v[164:167], v[48:51]
	v_mfma_f32_16x16x32_bf16 v[36:39], v[148:151], v[172:175], v[36:39]
	v_mfma_f32_16x16x32_bf16 v[32:35], v[156:159], v[172:175], v[32:35]
	s_setprio 2
	s_barrier
	v_mfma_f32_16x16x32_bf16 v[20:23], v[148:151], v[198:201], v[20:23]
	v_mfma_f32_16x16x32_bf16 v[16:19], v[156:159], v[198:201], v[16:19]
	v_mfma_f32_16x16x32_bf16 v[4:7], v[148:151], v[206:209], v[4:7]
	v_mfma_f32_16x16x32_bf16 v[0:3], v[156:159], v[206:209], v[0:3]
	s_setprio 0
	s_add_i32 s83, s83, 2
	s_add_u32 s44, s44, 0x180
	s_addc_u32 s53, s53, 0
	s_cmp_gt_u32 s83, 13
	s_mov_b64 s[8:9], s[38:39]
	s_cbranch_scc0 .LBB0_953

.LBB0_1045:
	s_add_i32 s25, s63, -2
	s_add_u32 s93, s38, 0x180
	s_addc_u32 s94, s39, 0
	s_mov_b32 s40, 0
	s_add_i32 s64, s40, 2
	s_add_u32 s38, s8, 0x180
	s_addc_u32 s39, s9, 0
	s_add_i32 s65, 0, 0x10000
	s_cmp_eq_u32 s25, s40
	s_cselect_b32 s51, s27, s39
	s_cselect_b32 s50, s26, s38
	s_cselect_b32 s41, s29, s94
	s_cselect_b32 s40, s28, s93
	s_add_i32 s66, 0, 0x14000
	v_add_u32_e32 v108, s65, v228
	v_add_u32_e32 v156, s66, v228
	ds_read_b128 v[88:91], v108
	ds_read_b128 v[92:95], v108 offset:1024
	ds_read_b128 v[104:107], v108 offset:2048
	ds_read_b128 v[108:111], v108 offset:3072
	ds_read_b128 v[144:147], v156
	ds_read_b128 v[148:151], v156 offset:1024
	ds_read_b128 v[152:155], v156 offset:2048
	ds_read_b128 v[156:159], v156 offset:3072
	s_add_i32 m0, s72, 0xc000
	ds_read_b128 v[160:163], v232
	ds_read_b128 v[164:167], v232 offset:1024
	ds_read_b128 v[168:171], v232 offset:2048
	ds_read_b128 v[172:175], v232 offset:3072
	ds_read_b128 v[194:197], v232 offset:4096
	ds_read_b128 v[198:201], v232 offset:5120
	ds_read_b128 v[202:205], v232 offset:6144
	ds_read_b128 v[206:209], v232 offset:7168
	global_load_lds_dwordx4 v192, s[8:9]
	s_add_i32 m0, s72, 0xe000
	s_nop 0
	global_load_lds_dwordx4 v190, s[8:9]
	s_waitcnt vmcnt(24)
	s_waitcnt lgkmcnt(0)
	s_barrier
	s_setprio 1
	v_mfma_f32_16x16x32_bf16 v[140:143], v[88:91], v[160:163], 0
	v_mfma_f32_16x16x32_bf16 v[136:139], v[104:107], v[160:163], 0
	v_mfma_f32_16x16x32_bf16 v[124:127], v[88:91], v[168:171], 0
	v_mfma_f32_16x16x32_bf16 v[120:123], v[104:107], v[168:171], 0
	v_mfma_f32_16x16x32_bf16 v[100:103], v[88:91], v[194:197], 0
	v_mfma_f32_16x16x32_bf16 v[96:99], v[104:107], v[194:197], 0
	v_mfma_f32_16x16x32_bf16 v[76:79], v[88:91], v[202:205], 0
	v_mfma_f32_16x16x32_bf16 v[72:75], v[104:107], v[202:205], 0
	v_mfma_f32_16x16x32_bf16 v[140:143], v[92:95], v[164:167], v[140:143]
	v_mfma_f32_16x16x32_bf16 v[136:139], v[108:111], v[164:167], v[136:139]
	v_mfma_f32_16x16x32_bf16 v[124:127], v[92:95], v[172:175], v[124:127]
	v_mfma_f32_16x16x32_bf16 v[120:123], v[108:111], v[172:175], v[120:123]
	v_mfma_f32_16x16x32_bf16 v[100:103], v[92:95], v[198:201], v[100:103]
	v_mfma_f32_16x16x32_bf16 v[96:99], v[108:111], v[198:201], v[96:99]
	v_mfma_f32_16x16x32_bf16 v[76:79], v[92:95], v[206:209], v[76:79]
	v_mfma_f32_16x16x32_bf16 v[72:75], v[108:111], v[206:209], v[72:75]
	v_mfma_f32_16x16x32_bf16 v[132:135], v[144:147], v[160:163], 0
	v_mfma_f32_16x16x32_bf16 v[128:131], v[152:155], v[160:163], 0
	v_mfma_f32_16x16x32_bf16 v[116:119], v[144:147], v[168:171], 0
	v_mfma_f32_16x16x32_bf16 v[112:115], v[152:155], v[168:171], 0
	v_mfma_f32_16x16x32_bf16 v[84:87], v[144:147], v[194:197], 0
	v_mfma_f32_16x16x32_bf16 v[80:83], v[152:155], v[194:197], 0
	v_mfma_f32_16x16x32_bf16 v[68:71], v[144:147], v[202:205], 0
	v_mfma_f32_16x16x32_bf16 v[64:67], v[152:155], v[202:205], 0
	v_mfma_f32_16x16x32_bf16 v[132:135], v[148:151], v[164:167], v[132:135]
	v_mfma_f32_16x16x32_bf16 v[128:131], v[156:159], v[164:167], v[128:131]
	v_mfma_f32_16x16x32_bf16 v[116:119], v[148:151], v[172:175], v[116:119]
	v_mfma_f32_16x16x32_bf16 v[112:115], v[156:159], v[172:175], v[112:115]
	s_setprio 2
	s_barrier
	v_mfma_f32_16x16x32_bf16 v[84:87], v[148:151], v[198:201], v[84:87]
	v_mfma_f32_16x16x32_bf16 v[80:83], v[156:159], v[198:201], v[80:83]
	v_mfma_f32_16x16x32_bf16 v[68:71], v[148:151], v[206:209], v[68:71]
	v_mfma_f32_16x16x32_bf16 v[64:67], v[156:159], v[206:209], v[64:67]
	s_setprio 0
	s_add_i32 s8, s65, s68
	s_add_u32 s98, s40, s34
	s_addc_u32 s99, s41, s35
	s_mov_b32 m0, s8
	ds_read_b128 v[160:163], v232 offset:16384
	ds_read_b128 v[164:167], v232 offset:17408
	ds_read_b128 v[168:171], v232 offset:18432
	ds_read_b128 v[172:175], v232 offset:19456
	ds_read_b128 v[194:197], v232 offset:20480
	ds_read_b128 v[198:201], v232 offset:21504
	ds_read_b128 v[202:205], v232 offset:22528
	ds_read_b128 v[206:209], v232 offset:23552
	global_load_lds_dwordx4 v184, s[40:41]
	s_add_i32 m0, s8, 0x2000
	s_add_u32 s8, s40, 0x60000
	s_addc_u32 s9, s41, 0
	s_add_i32 s65, s66, s68
	global_load_lds_dwordx4 v188, s[40:41]
	s_mov_b32 m0, s65
	s_nop 0
	global_load_lds_dwordx4 v184, s[8:9]
	s_add_i32 m0, s65, 0x2000
	s_nop 0
	global_load_lds_dwordx4 v188, s[8:9]
	s_add_u32 s100, s50, s34
	s_addc_u32 s101, s51, s35
	s_mov_b32 m0, s72
	s_nop 0
	global_load_lds_dwordx4 v182, s[50:51]
	s_mov_b32 m0, s73
	s_nop 0
	global_load_lds_dwordx4 v186, s[50:51]
	s_waitcnt vmcnt(8)
	s_waitcnt lgkmcnt(0)
	s_barrier
	s_setprio 1
	v_mfma_f32_16x16x32_bf16 v[60:63], v[88:91], v[160:163], 0
	v_mfma_f32_16x16x32_bf16 v[56:59], v[104:107], v[160:163], 0
	v_mfma_f32_16x16x32_bf16 v[44:47], v[88:91], v[168:171], 0
	v_mfma_f32_16x16x32_bf16 v[40:43], v[104:107], v[168:171], 0
	v_mfma_f32_16x16x32_bf16 v[28:31], v[88:91], v[194:197], 0
	v_mfma_f32_16x16x32_bf16 v[24:27], v[104:107], v[194:197], 0
	v_mfma_f32_16x16x32_bf16 v[12:15], v[88:91], v[202:205], 0
	v_mfma_f32_16x16x32_bf16 v[8:11], v[104:107], v[202:205], 0
	v_mfma_f32_16x16x32_bf16 v[60:63], v[92:95], v[164:167], v[60:63]
	v_mfma_f32_16x16x32_bf16 v[56:59], v[108:111], v[164:167], v[56:59]
	v_mfma_f32_16x16x32_bf16 v[44:47], v[92:95], v[172:175], v[44:47]
	v_mfma_f32_16x16x32_bf16 v[40:43], v[108:111], v[172:175], v[40:43]
	v_mfma_f32_16x16x32_bf16 v[28:31], v[92:95], v[198:201], v[28:31]
	v_mfma_f32_16x16x32_bf16 v[24:27], v[108:111], v[198:201], v[24:27]
	v_mfma_f32_16x16x32_bf16 v[12:15], v[92:95], v[206:209], v[12:15]
	v_mfma_f32_16x16x32_bf16 v[8:11], v[108:111], v[206:209], v[8:11]
	v_mfma_f32_16x16x32_bf16 v[52:55], v[144:147], v[160:163], 0
	v_mfma_f32_16x16x32_bf16 v[48:51], v[152:155], v[160:163], 0
	v_mfma_f32_16x16x32_bf16 v[36:39], v[144:147], v[168:171], 0
	v_mfma_f32_16x16x32_bf16 v[32:35], v[152:155], v[168:171], 0
	v_mfma_f32_16x16x32_bf16 v[20:23], v[144:147], v[194:197], 0
	v_mfma_f32_16x16x32_bf16 v[16:19], v[152:155], v[194:197], 0
	v_mfma_f32_16x16x32_bf16 v[4:7], v[144:147], v[202:205], 0
	v_mfma_f32_16x16x32_bf16 v[0:3], v[152:155], v[202:205], 0
	v_mfma_f32_16x16x32_bf16 v[52:55], v[148:151], v[164:167], v[52:55]
	v_mfma_f32_16x16x32_bf16 v[48:51], v[156:159], v[164:167], v[48:51]
	v_mfma_f32_16x16x32_bf16 v[36:39], v[148:151], v[172:175], v[36:39]
	v_mfma_f32_16x16x32_bf16 v[32:35], v[156:159], v[172:175], v[32:35]
	s_setprio 2
	s_barrier
	v_mfma_f32_16x16x32_bf16 v[20:23], v[148:151], v[198:201], v[20:23]
	v_mfma_f32_16x16x32_bf16 v[16:19], v[156:159], v[198:201], v[16:19]
	v_mfma_f32_16x16x32_bf16 v[4:7], v[148:151], v[206:209], v[4:7]
	v_mfma_f32_16x16x32_bf16 v[0:3], v[156:159], v[206:209], v[0:3]
	s_setprio 0
	s_add_i32 s65, 0, 0x18000
	s_add_i32 s66, 0, 0x1c000
	v_add_u32_e32 v108, s65, v228
	v_add_u32_e32 v156, s66, v228
	ds_read_b128 v[88:91], v108
	ds_read_b128 v[92:95], v108 offset:1024
	ds_read_b128 v[104:107], v108 offset:2048
	ds_read_b128 v[108:111], v108 offset:3072
	ds_read_b128 v[144:147], v156
	ds_read_b128 v[148:151], v156 offset:1024
	ds_read_b128 v[152:155], v156 offset:2048
	ds_read_b128 v[156:159], v156 offset:3072
	s_add_u32 s8, s50, 0x60000
	s_addc_u32 s9, s51, 0
	s_mov_b32 m0, s74
	ds_read_b128 v[160:163], v232 offset:32768
	ds_read_b128 v[164:167], v232 offset:33792
	ds_read_b128 v[168:171], v232 offset:34816
	ds_read_b128 v[172:175], v232 offset:35840
	ds_read_b128 v[194:197], v232 offset:36864
	ds_read_b128 v[198:201], v232 offset:37888
	ds_read_b128 v[202:205], v232 offset:38912
	ds_read_b128 v[206:209], v232 offset:39936
	global_load_lds_dwordx4 v182, s[8:9]
	s_mov_b32 m0, s75
	s_nop 0
	global_load_lds_dwordx4 v186, s[8:9]
	s_waitcnt vmcnt(8)
	s_waitcnt lgkmcnt(0)
	s_barrier
	s_setprio 1
	v_mfma_f32_16x16x32_bf16 v[140:143], v[88:91], v[160:163], v[140:143]
	v_mfma_f32_16x16x32_bf16 v[136:139], v[104:107], v[160:163], v[136:139]
	v_mfma_f32_16x16x32_bf16 v[124:127], v[88:91], v[168:171], v[124:127]
	v_mfma_f32_16x16x32_bf16 v[120:123], v[104:107], v[168:171], v[120:123]
	v_mfma_f32_16x16x32_bf16 v[100:103], v[88:91], v[194:197], v[100:103]
	v_mfma_f32_16x16x32_bf16 v[96:99], v[104:107], v[194:197], v[96:99]
	v_mfma_f32_16x16x32_bf16 v[76:79], v[88:91], v[202:205], v[76:79]
	v_mfma_f32_16x16x32_bf16 v[72:75], v[104:107], v[202:205], v[72:75]
	v_mfma_f32_16x16x32_bf16 v[140:143], v[92:95], v[164:167], v[140:143]
	v_mfma_f32_16x16x32_bf16 v[136:139], v[108:111], v[164:167], v[136:139]
	v_mfma_f32_16x16x32_bf16 v[124:127], v[92:95], v[172:175], v[124:127]
	v_mfma_f32_16x16x32_bf16 v[120:123], v[108:111], v[172:175], v[120:123]
	v_mfma_f32_16x16x32_bf16 v[100:103], v[92:95], v[198:201], v[100:103]
	v_mfma_f32_16x16x32_bf16 v[96:99], v[108:111], v[198:201], v[96:99]
	v_mfma_f32_16x16x32_bf16 v[76:79], v[92:95], v[206:209], v[76:79]
	v_mfma_f32_16x16x32_bf16 v[72:75], v[108:111], v[206:209], v[72:75]
	v_mfma_f32_16x16x32_bf16 v[132:135], v[144:147], v[160:163], v[132:135]
	v_mfma_f32_16x16x32_bf16 v[128:131], v[152:155], v[160:163], v[128:131]
	v_mfma_f32_16x16x32_bf16 v[116:119], v[144:147], v[168:171], v[116:119]
	v_mfma_f32_16x16x32_bf16 v[112:115], v[152:155], v[168:171], v[112:115]
	v_mfma_f32_16x16x32_bf16 v[84:87], v[144:147], v[194:197], v[84:87]
	v_mfma_f32_16x16x32_bf16 v[80:83], v[152:155], v[194:197], v[80:83]
	v_mfma_f32_16x16x32_bf16 v[68:71], v[144:147], v[202:205], v[68:71]
	v_mfma_f32_16x16x32_bf16 v[64:67], v[152:155], v[202:205], v[64:67]
	v_mfma_f32_16x16x32_bf16 v[132:135], v[148:151], v[164:167], v[132:135]
	v_mfma_f32_16x16x32_bf16 v[128:131], v[156:159], v[164:167], v[128:131]
	v_mfma_f32_16x16x32_bf16 v[116:119], v[148:151], v[172:175], v[116:119]
	v_mfma_f32_16x16x32_bf16 v[112:115], v[156:159], v[172:175], v[112:115]
	s_setprio 2
	s_barrier
	v_mfma_f32_16x16x32_bf16 v[84:87], v[148:151], v[198:201], v[84:87]
	v_mfma_f32_16x16x32_bf16 v[80:83], v[156:159], v[198:201], v[80:83]
	v_mfma_f32_16x16x32_bf16 v[68:71], v[148:151], v[206:209], v[68:71]
	v_mfma_f32_16x16x32_bf16 v[64:67], v[156:159], v[206:209], v[64:67]
	s_setprio 0
	s_add_i32 s8, s65, s68
	s_mov_b32 m0, s8
	ds_read_b128 v[160:163], v232 offset:49152
	ds_read_b128 v[164:167], v232 offset:50176
	ds_read_b128 v[168:171], v232 offset:51200
	ds_read_b128 v[172:175], v232 offset:52224
	ds_read_b128 v[194:197], v232 offset:53248
	ds_read_b128 v[198:201], v232 offset:54272
	ds_read_b128 v[202:205], v232 offset:55296
	ds_read_b128 v[206:209], v232 offset:56320
	global_load_lds_dwordx4 v184, s[98:99]
	s_add_i32 m0, s8, 0x2000
	s_add_u32 s8, s40, 0x60080
	s_addc_u32 s9, s41, 0
	s_add_i32 s40, s66, s68
	global_load_lds_dwordx4 v188, s[98:99]
	s_mov_b32 m0, s40
	s_nop 0
	global_load_lds_dwordx4 v184, s[8:9]
	s_add_i32 m0, s40, 0x2000
	s_nop 0
	global_load_lds_dwordx4 v188, s[8:9]
	s_mov_b32 m0, s81
	s_nop 0
	global_load_lds_dwordx4 v182, s[100:101]
	s_mov_b32 m0, s82
	s_nop 0
	global_load_lds_dwordx4 v186, s[100:101]
	s_waitcnt vmcnt(8)
	s_waitcnt lgkmcnt(0)
	s_barrier
	s_setprio 1
	v_mfma_f32_16x16x32_bf16 v[60:63], v[88:91], v[160:163], v[60:63]
	v_mfma_f32_16x16x32_bf16 v[56:59], v[104:107], v[160:163], v[56:59]
	v_mfma_f32_16x16x32_bf16 v[44:47], v[88:91], v[168:171], v[44:47]
	v_mfma_f32_16x16x32_bf16 v[40:43], v[104:107], v[168:171], v[40:43]
	v_mfma_f32_16x16x32_bf16 v[28:31], v[88:91], v[194:197], v[28:31]
	v_mfma_f32_16x16x32_bf16 v[24:27], v[104:107], v[194:197], v[24:27]
	v_mfma_f32_16x16x32_bf16 v[12:15], v[88:91], v[202:205], v[12:15]
	v_mfma_f32_16x16x32_bf16 v[8:11], v[104:107], v[202:205], v[8:11]
	v_mfma_f32_16x16x32_bf16 v[60:63], v[92:95], v[164:167], v[60:63]
	v_mfma_f32_16x16x32_bf16 v[56:59], v[108:111], v[164:167], v[56:59]
	v_mfma_f32_16x16x32_bf16 v[44:47], v[92:95], v[172:175], v[44:47]
	v_mfma_f32_16x16x32_bf16 v[40:43], v[108:111], v[172:175], v[40:43]
	v_mfma_f32_16x16x32_bf16 v[28:31], v[92:95], v[198:201], v[28:31]
	v_mfma_f32_16x16x32_bf16 v[24:27], v[108:111], v[198:201], v[24:27]
	v_mfma_f32_16x16x32_bf16 v[12:15], v[92:95], v[206:209], v[12:15]
	v_mfma_f32_16x16x32_bf16 v[8:11], v[108:111], v[206:209], v[8:11]
	v_mfma_f32_16x16x32_bf16 v[52:55], v[144:147], v[160:163], v[52:55]
	v_mfma_f32_16x16x32_bf16 v[48:51], v[152:155], v[160:163], v[48:51]
	v_mfma_f32_16x16x32_bf16 v[36:39], v[144:147], v[168:171], v[36:39]
	v_mfma_f32_16x16x32_bf16 v[32:35], v[152:155], v[168:171], v[32:35]
	v_mfma_f32_16x16x32_bf16 v[20:23], v[144:147], v[194:197], v[20:23]
	v_mfma_f32_16x16x32_bf16 v[16:19], v[152:155], v[194:197], v[16:19]
	v_mfma_f32_16x16x32_bf16 v[4:7], v[144:147], v[202:205], v[4:7]
	v_mfma_f32_16x16x32_bf16 v[0:3], v[152:155], v[202:205], v[0:3]
	v_mfma_f32_16x16x32_bf16 v[52:55], v[148:151], v[164:167], v[52:55]
	v_mfma_f32_16x16x32_bf16 v[48:51], v[156:159], v[164:167], v[48:51]
	v_mfma_f32_16x16x32_bf16 v[36:39], v[148:151], v[172:175], v[36:39]
	v_mfma_f32_16x16x32_bf16 v[32:35], v[156:159], v[172:175], v[32:35]
	s_setprio 2
	s_barrier
	v_mfma_f32_16x16x32_bf16 v[20:23], v[148:151], v[198:201], v[20:23]
	v_mfma_f32_16x16x32_bf16 v[16:19], v[156:159], v[198:201], v[16:19]
	v_mfma_f32_16x16x32_bf16 v[4:7], v[148:151], v[206:209], v[4:7]
	v_mfma_f32_16x16x32_bf16 v[0:3], v[156:159], v[206:209], v[0:3]
	s_setprio 0
	s_add_u32 s93, s93, 0x180
	s_addc_u32 s94, s94, 0
	s_cmp_ge_i32 s64, s63
	s_mov_b64 s[8:9], s[38:39]
	s_mov_b32 s40, s64
	s_cbranch_scc1 .Lpeel_exit_5
.LBB0_1046:
	s_add_i32 s64, s40, 2
	s_add_u32 s38, s8, 0x180
	s_addc_u32 s39, s9, 0
	s_add_i32 s65, 0, 0x10000
	s_cmp_eq_u32 s25, s40
	s_cselect_b32 s51, s27, s39
	s_cselect_b32 s50, s26, s38
	s_cselect_b32 s41, s29, s94
	s_cselect_b32 s40, s28, s93
	s_add_i32 s66, 0, 0x14000
	v_add_u32_e32 v108, s65, v228
	v_add_u32_e32 v156, s66, v228
	ds_read_b128 v[88:91], v108
	ds_read_b128 v[92:95], v108 offset:1024
	ds_read_b128 v[104:107], v108 offset:2048
	ds_read_b128 v[108:111], v108 offset:3072
	ds_read_b128 v[144:147], v156
	ds_read_b128 v[148:151], v156 offset:1024
	ds_read_b128 v[152:155], v156 offset:2048
	ds_read_b128 v[156:159], v156 offset:3072
	s_add_i32 m0, s72, 0xc000
	ds_read_b128 v[160:163], v232
	ds_read_b128 v[164:167], v232 offset:1024
	ds_read_b128 v[168:171], v232 offset:2048
	ds_read_b128 v[172:175], v232 offset:3072
	ds_read_b128 v[194:197], v232 offset:4096
	ds_read_b128 v[198:201], v232 offset:5120
	ds_read_b128 v[202:205], v232 offset:6144
	ds_read_b128 v[206:209], v232 offset:7168
	global_load_lds_dwordx4 v192, s[8:9]
	s_add_i32 m0, s72, 0xe000
	s_nop 0
	global_load_lds_dwordx4 v190, s[8:9]
	s_waitcnt vmcnt(8)
	s_waitcnt lgkmcnt(0)
	s_barrier
	s_setprio 1
	v_mfma_f32_16x16x32_bf16 v[140:143], v[88:91], v[160:163], v[140:143]
	v_mfma_f32_16x16x32_bf16 v[136:139], v[104:107], v[160:163], v[136:139]
	v_mfma_f32_16x16x32_bf16 v[124:127], v[88:91], v[168:171], v[124:127]
	v_mfma_f32_16x16x32_bf16 v[120:123], v[104:107], v[168:171], v[120:123]
	v_mfma_f32_16x16x32_bf16 v[100:103], v[88:91], v[194:197], v[100:103]
	v_mfma_f32_16x16x32_bf16 v[96:99], v[104:107], v[194:197], v[96:99]
	v_mfma_f32_16x16x32_bf16 v[76:79], v[88:91], v[202:205], v[76:79]
	v_mfma_f32_16x16x32_bf16 v[72:75], v[104:107], v[202:205], v[72:75]
	v_mfma_f32_16x16x32_bf16 v[140:143], v[92:95], v[164:167], v[140:143]
	v_mfma_f32_16x16x32_bf16 v[136:139], v[108:111], v[164:167], v[136:139]
	v_mfma_f32_16x16x32_bf16 v[124:127], v[92:95], v[172:175], v[124:127]
	v_mfma_f32_16x16x32_bf16 v[120:123], v[108:111], v[172:175], v[120:123]
	v_mfma_f32_16x16x32_bf16 v[100:103], v[92:95], v[198:201], v[100:103]
	v_mfma_f32_16x16x32_bf16 v[96:99], v[108:111], v[198:201], v[96:99]
	v_mfma_f32_16x16x32_bf16 v[76:79], v[92:95], v[206:209], v[76:79]
	v_mfma_f32_16x16x32_bf16 v[72:75], v[108:111], v[206:209], v[72:75]
	v_mfma_f32_16x16x32_bf16 v[132:135], v[144:147], v[160:163], v[132:135]
	v_mfma_f32_16x16x32_bf16 v[128:131], v[152:155], v[160:163], v[128:131]
	v_mfma_f32_16x16x32_bf16 v[116:119], v[144:147], v[168:171], v[116:119]
	v_mfma_f32_16x16x32_bf16 v[112:115], v[152:155], v[168:171], v[112:115]
	v_mfma_f32_16x16x32_bf16 v[84:87], v[144:147], v[194:197], v[84:87]
	v_mfma_f32_16x16x32_bf16 v[80:83], v[152:155], v[194:197], v[80:83]
	v_mfma_f32_16x16x32_bf16 v[68:71], v[144:147], v[202:205], v[68:71]
	v_mfma_f32_16x16x32_bf16 v[64:67], v[152:155], v[202:205], v[64:67]
	v_mfma_f32_16x16x32_bf16 v[132:135], v[148:151], v[164:167], v[132:135]
	v_mfma_f32_16x16x32_bf16 v[128:131], v[156:159], v[164:167], v[128:131]
	v_mfma_f32_16x16x32_bf16 v[116:119], v[148:151], v[172:175], v[116:119]
	v_mfma_f32_16x16x32_bf16 v[112:115], v[156:159], v[172:175], v[112:115]
	s_setprio 2
	s_barrier
	v_mfma_f32_16x16x32_bf16 v[84:87], v[148:151], v[198:201], v[84:87]
	v_mfma_f32_16x16x32_bf16 v[80:83], v[156:159], v[198:201], v[80:83]
	v_mfma_f32_16x16x32_bf16 v[68:71], v[148:151], v[206:209], v[68:71]
	v_mfma_f32_16x16x32_bf16 v[64:67], v[156:159], v[206:209], v[64:67]
	s_setprio 0
	s_add_i32 s8, s65, s68
	s_add_u32 s98, s40, s34
	s_addc_u32 s99, s41, s35
	s_mov_b32 m0, s8
	ds_read_b128 v[160:163], v232 offset:16384
	ds_read_b128 v[164:167], v232 offset:17408
	ds_read_b128 v[168:171], v232 offset:18432
	ds_read_b128 v[172:175], v232 offset:19456
	ds_read_b128 v[194:197], v232 offset:20480
	ds_read_b128 v[198:201], v232 offset:21504
	ds_read_b128 v[202:205], v232 offset:22528
	ds_read_b128 v[206:209], v232 offset:23552
	global_load_lds_dwordx4 v184, s[40:41]
	s_add_i32 m0, s8, 0x2000
	s_add_u32 s8, s40, 0x60000
	s_addc_u32 s9, s41, 0
	s_add_i32 s65, s66, s68
	global_load_lds_dwordx4 v188, s[40:41]
	s_mov_b32 m0, s65
	s_nop 0
	global_load_lds_dwordx4 v184, s[8:9]
	s_add_i32 m0, s65, 0x2000
	s_nop 0
	global_load_lds_dwordx4 v188, s[8:9]
	s_add_u32 s100, s50, s34
	s_addc_u32 s101, s51, s35
	s_mov_b32 m0, s72
	s_nop 0
	global_load_lds_dwordx4 v182, s[50:51]
	s_mov_b32 m0, s73
	s_nop 0
	global_load_lds_dwordx4 v186, s[50:51]
	s_waitcnt vmcnt(8)
	s_waitcnt lgkmcnt(0)
	s_barrier
	s_setprio 1
	v_mfma_f32_16x16x32_bf16 v[60:63], v[88:91], v[160:163], v[60:63]
	v_mfma_f32_16x16x32_bf16 v[56:59], v[104:107], v[160:163], v[56:59]
	v_mfma_f32_16x16x32_bf16 v[44:47], v[88:91], v[168:171], v[44:47]
	v_mfma_f32_16x16x32_bf16 v[40:43], v[104:107], v[168:171], v[40:43]
	v_mfma_f32_16x16x32_bf16 v[28:31], v[88:91], v[194:197], v[28:31]
	v_mfma_f32_16x16x32_bf16 v[24:27], v[104:107], v[194:197], v[24:27]
	v_mfma_f32_16x16x32_bf16 v[12:15], v[88:91], v[202:205], v[12:15]
	v_mfma_f32_16x16x32_bf16 v[8:11], v[104:107], v[202:205], v[8:11]
	v_mfma_f32_16x16x32_bf16 v[60:63], v[92:95], v[164:167], v[60:63]
	v_mfma_f32_16x16x32_bf16 v[56:59], v[108:111], v[164:167], v[56:59]
	v_mfma_f32_16x16x32_bf16 v[44:47], v[92:95], v[172:175], v[44:47]
	v_mfma_f32_16x16x32_bf16 v[40:43], v[108:111], v[172:175], v[40:43]
	v_mfma_f32_16x16x32_bf16 v[28:31], v[92:95], v[198:201], v[28:31]
	v_mfma_f32_16x16x32_bf16 v[24:27], v[108:111], v[198:201], v[24:27]
	v_mfma_f32_16x16x32_bf16 v[12:15], v[92:95], v[206:209], v[12:15]
	v_mfma_f32_16x16x32_bf16 v[8:11], v[108:111], v[206:209], v[8:11]
	v_mfma_f32_16x16x32_bf16 v[52:55], v[144:147], v[160:163], v[52:55]
	v_mfma_f32_16x16x32_bf16 v[48:51], v[152:155], v[160:163], v[48:51]
	v_mfma_f32_16x16x32_bf16 v[36:39], v[144:147], v[168:171], v[36:39]
	v_mfma_f32_16x16x32_bf16 v[32:35], v[152:155], v[168:171], v[32:35]
	v_mfma_f32_16x16x32_bf16 v[20:23], v[144:147], v[194:197], v[20:23]
	v_mfma_f32_16x16x32_bf16 v[16:19], v[152:155], v[194:197], v[16:19]
	v_mfma_f32_16x16x32_bf16 v[4:7], v[144:147], v[202:205], v[4:7]
	v_mfma_f32_16x16x32_bf16 v[0:3], v[152:155], v[202:205], v[0:3]
	v_mfma_f32_16x16x32_bf16 v[52:55], v[148:151], v[164:167], v[52:55]
	v_mfma_f32_16x16x32_bf16 v[48:51], v[156:159], v[164:167], v[48:51]
	v_mfma_f32_16x16x32_bf16 v[36:39], v[148:151], v[172:175], v[36:39]
	v_mfma_f32_16x16x32_bf16 v[32:35], v[156:159], v[172:175], v[32:35]
	s_setprio 2
	s_barrier
	v_mfma_f32_16x16x32_bf16 v[20:23], v[148:151], v[198:201], v[20:23]
	v_mfma_f32_16x16x32_bf16 v[16:19], v[156:159], v[198:201], v[16:19]
	v_mfma_f32_16x16x32_bf16 v[4:7], v[148:151], v[206:209], v[4:7]
	v_mfma_f32_16x16x32_bf16 v[0:3], v[156:159], v[206:209], v[0:3]
	s_setprio 0
	s_add_i32 s65, 0, 0x18000
	s_add_i32 s66, 0, 0x1c000
	v_add_u32_e32 v108, s65, v228
	v_add_u32_e32 v156, s66, v228
	ds_read_b128 v[88:91], v108
	ds_read_b128 v[92:95], v108 offset:1024
	ds_read_b128 v[104:107], v108 offset:2048
	ds_read_b128 v[108:111], v108 offset:3072
	ds_read_b128 v[144:147], v156
	ds_read_b128 v[148:151], v156 offset:1024
	ds_read_b128 v[152:155], v156 offset:2048
	ds_read_b128 v[156:159], v156 offset:3072
	s_add_u32 s8, s50, 0x60000
	s_addc_u32 s9, s51, 0
	s_mov_b32 m0, s74
	ds_read_b128 v[160:163], v232 offset:32768
	ds_read_b128 v[164:167], v232 offset:33792
	ds_read_b128 v[168:171], v232 offset:34816
	ds_read_b128 v[172:175], v232 offset:35840
	ds_read_b128 v[194:197], v232 offset:36864
	ds_read_b128 v[198:201], v232 offset:37888
	ds_read_b128 v[202:205], v232 offset:38912
	ds_read_b128 v[206:209], v232 offset:39936
	global_load_lds_dwordx4 v182, s[8:9]
	s_mov_b32 m0, s75
	s_nop 0
	global_load_lds_dwordx4 v186, s[8:9]
	s_waitcnt vmcnt(8)
	s_waitcnt lgkmcnt(0)
	s_barrier
	s_setprio 1
	v_mfma_f32_16x16x32_bf16 v[140:143], v[88:91], v[160:163], v[140:143]
	v_mfma_f32_16x16x32_bf16 v[136:139], v[104:107], v[160:163], v[136:139]
	v_mfma_f32_16x16x32_bf16 v[124:127], v[88:91], v[168:171], v[124:127]
	v_mfma_f32_16x16x32_bf16 v[120:123], v[104:107], v[168:171], v[120:123]
	v_mfma_f32_16x16x32_bf16 v[100:103], v[88:91], v[194:197], v[100:103]
	v_mfma_f32_16x16x32_bf16 v[96:99], v[104:107], v[194:197], v[96:99]
	v_mfma_f32_16x16x32_bf16 v[76:79], v[88:91], v[202:205], v[76:79]
	v_mfma_f32_16x16x32_bf16 v[72:75], v[104:107], v[202:205], v[72:75]
	v_mfma_f32_16x16x32_bf16 v[140:143], v[92:95], v[164:167], v[140:143]
	v_mfma_f32_16x16x32_bf16 v[136:139], v[108:111], v[164:167], v[136:139]
	v_mfma_f32_16x16x32_bf16 v[124:127], v[92:95], v[172:175], v[124:127]
	v_mfma_f32_16x16x32_bf16 v[120:123], v[108:111], v[172:175], v[120:123]
	v_mfma_f32_16x16x32_bf16 v[100:103], v[92:95], v[198:201], v[100:103]
	v_mfma_f32_16x16x32_bf16 v[96:99], v[108:111], v[198:201], v[96:99]
	v_mfma_f32_16x16x32_bf16 v[76:79], v[92:95], v[206:209], v[76:79]
	v_mfma_f32_16x16x32_bf16 v[72:75], v[108:111], v[206:209], v[72:75]
	v_mfma_f32_16x16x32_bf16 v[132:135], v[144:147], v[160:163], v[132:135]
	v_mfma_f32_16x16x32_bf16 v[128:131], v[152:155], v[160:163], v[128:131]
	v_mfma_f32_16x16x32_bf16 v[116:119], v[144:147], v[168:171], v[116:119]
	v_mfma_f32_16x16x32_bf16 v[112:115], v[152:155], v[168:171], v[112:115]
	v_mfma_f32_16x16x32_bf16 v[84:87], v[144:147], v[194:197], v[84:87]
	v_mfma_f32_16x16x32_bf16 v[80:83], v[152:155], v[194:197], v[80:83]
	v_mfma_f32_16x16x32_bf16 v[68:71], v[144:147], v[202:205], v[68:71]
	v_mfma_f32_16x16x32_bf16 v[64:67], v[152:155], v[202:205], v[64:67]
	v_mfma_f32_16x16x32_bf16 v[132:135], v[148:151], v[164:167], v[132:135]
	v_mfma_f32_16x16x32_bf16 v[128:131], v[156:159], v[164:167], v[128:131]
	v_mfma_f32_16x16x32_bf16 v[116:119], v[148:151], v[172:175], v[116:119]
	v_mfma_f32_16x16x32_bf16 v[112:115], v[156:159], v[172:175], v[112:115]
	s_setprio 2
	s_barrier
	v_mfma_f32_16x16x32_bf16 v[84:87], v[148:151], v[198:201], v[84:87]
	v_mfma_f32_16x16x32_bf16 v[80:83], v[156:159], v[198:201], v[80:83]
	v_mfma_f32_16x16x32_bf16 v[68:71], v[148:151], v[206:209], v[68:71]
	v_mfma_f32_16x16x32_bf16 v[64:67], v[156:159], v[206:209], v[64:67]
	s_setprio 0
	s_add_i32 s8, s65, s68
	s_mov_b32 m0, s8
	ds_read_b128 v[160:163], v232 offset:49152
	ds_read_b128 v[164:167], v232 offset:50176
	ds_read_b128 v[168:171], v232 offset:51200
	ds_read_b128 v[172:175], v232 offset:52224
	ds_read_b128 v[194:197], v232 offset:53248
	ds_read_b128 v[198:201], v232 offset:54272
	ds_read_b128 v[202:205], v232 offset:55296
	ds_read_b128 v[206:209], v232 offset:56320
	global_load_lds_dwordx4 v184, s[98:99]
	s_add_i32 m0, s8, 0x2000
	s_add_u32 s8, s40, 0x60080
	s_addc_u32 s9, s41, 0
	s_add_i32 s40, s66, s68
	global_load_lds_dwordx4 v188, s[98:99]
	s_mov_b32 m0, s40
	s_nop 0
	global_load_lds_dwordx4 v184, s[8:9]
	s_add_i32 m0, s40, 0x2000
	s_nop 0
	global_load_lds_dwordx4 v188, s[8:9]
	s_mov_b32 m0, s81
	s_nop 0
	global_load_lds_dwordx4 v182, s[100:101]
	s_mov_b32 m0, s82
	s_nop 0
	global_load_lds_dwordx4 v186, s[100:101]
	s_waitcnt vmcnt(8)
	s_waitcnt lgkmcnt(0)
	s_barrier
	s_setprio 1
	v_mfma_f32_16x16x32_bf16 v[60:63], v[88:91], v[160:163], v[60:63]
	v_mfma_f32_16x16x32_bf16 v[56:59], v[104:107], v[160:163], v[56:59]
	v_mfma_f32_16x16x32_bf16 v[44:47], v[88:91], v[168:171], v[44:47]
	v_mfma_f32_16x16x32_bf16 v[40:43], v[104:107], v[168:171], v[40:43]
	v_mfma_f32_16x16x32_bf16 v[28:31], v[88:91], v[194:197], v[28:31]
	v_mfma_f32_16x16x32_bf16 v[24:27], v[104:107], v[194:197], v[24:27]
	v_mfma_f32_16x16x32_bf16 v[12:15], v[88:91], v[202:205], v[12:15]
	v_mfma_f32_16x16x32_bf16 v[8:11], v[104:107], v[202:205], v[8:11]
	v_mfma_f32_16x16x32_bf16 v[60:63], v[92:95], v[164:167], v[60:63]
	v_mfma_f32_16x16x32_bf16 v[56:59], v[108:111], v[164:167], v[56:59]
	v_mfma_f32_16x16x32_bf16 v[44:47], v[92:95], v[172:175], v[44:47]
	v_mfma_f32_16x16x32_bf16 v[40:43], v[108:111], v[172:175], v[40:43]
	v_mfma_f32_16x16x32_bf16 v[28:31], v[92:95], v[198:201], v[28:31]
	v_mfma_f32_16x16x32_bf16 v[24:27], v[108:111], v[198:201], v[24:27]
	v_mfma_f32_16x16x32_bf16 v[12:15], v[92:95], v[206:209], v[12:15]
	v_mfma_f32_16x16x32_bf16 v[8:11], v[108:111], v[206:209], v[8:11]
	v_mfma_f32_16x16x32_bf16 v[52:55], v[144:147], v[160:163], v[52:55]
	v_mfma_f32_16x16x32_bf16 v[48:51], v[152:155], v[160:163], v[48:51]
	v_mfma_f32_16x16x32_bf16 v[36:39], v[144:147], v[168:171], v[36:39]
	v_mfma_f32_16x16x32_bf16 v[32:35], v[152:155], v[168:171], v[32:35]
	v_mfma_f32_16x16x32_bf16 v[20:23], v[144:147], v[194:197], v[20:23]
	v_mfma_f32_16x16x32_bf16 v[16:19], v[152:155], v[194:197], v[16:19]
	v_mfma_f32_16x16x32_bf16 v[4:7], v[144:147], v[202:205], v[4:7]
	v_mfma_f32_16x16x32_bf16 v[0:3], v[152:155], v[202:205], v[0:3]
	v_mfma_f32_16x16x32_bf16 v[52:55], v[148:151], v[164:167], v[52:55]
	v_mfma_f32_16x16x32_bf16 v[48:51], v[156:159], v[164:167], v[48:51]
	v_mfma_f32_16x16x32_bf16 v[36:39], v[148:151], v[172:175], v[36:39]
	v_mfma_f32_16x16x32_bf16 v[32:35], v[156:159], v[172:175], v[32:35]
	s_setprio 2
	s_barrier
	v_mfma_f32_16x16x32_bf16 v[20:23], v[148:151], v[198:201], v[20:23]
	v_mfma_f32_16x16x32_bf16 v[16:19], v[156:159], v[198:201], v[16:19]
	v_mfma_f32_16x16x32_bf16 v[4:7], v[148:151], v[206:209], v[4:7]
	v_mfma_f32_16x16x32_bf16 v[0:3], v[156:159], v[206:209], v[0:3]
	s_setprio 0
	s_add_u32 s93, s93, 0x180
	s_addc_u32 s94, s94, 0
	s_cmp_ge_i32 s64, s63
	s_mov_b64 s[8:9], s[38:39]
	s_mov_b32 s40, s64
	s_cbranch_scc0 .LBB0_1046

.LBB0_1220:
	s_ashr_i32 s21, s20, 31
	s_lshl_b64 s[28:29], s[20:21], 19
	s_add_u32 s21, s54, s28
	s_addc_u32 s23, s55, s29
	s_ashr_i32 s27, s26, 31
	s_lshl_b64 s[38:39], s[26:27], 7
	s_add_u32 s28, s21, s38
	s_addc_u32 s29, s23, s39
	s_ashr_i32 s23, s22, 31
	s_lshl_b64 s[50:51], s[22:23], 19
	s_add_u32 s21, s58, s50
	s_addc_u32 s23, s59, s51
	s_add_u32 s38, s21, s38
	s_addc_u32 s39, s23, s39
	s_cmp_lt_i32 s52, 1
	s_cbranch_scc1 .LBB0_1227
	s_and_b64 s[50:51], s[24:25], exec
	s_cselect_b32 s21, s29, s43
	s_cselect_b32 s23, s28, s42
	s_cselect_b32 s27, s39, s5
	s_cselect_b32 s53, s38, s4
	s_add_i32 s63, s52, -2
	s_add_u32 s95, s4, 0x100
	s_addc_u32 vcc_lo, s5, 0
	s_add_u32 s4, s42, 0x40080
	s_addc_u32 s5, s43, 0
	s_mov_b32 s42, 0
	s_add_i32 vcc_hi, s42, 2
	s_add_u32 s43, s4, 0xfffc0080
	s_addc_u32 s50, s5, -1
	s_add_i32 s64, 0, 0x10000
	s_cmp_eq_u32 s63, s42
	s_cselect_b32 s51, s21, s50
	s_cselect_b32 s50, s23, s43
	s_cselect_b32 s43, s27, vcc_lo
	s_cselect_b32 s42, s53, s95
	s_add_i32 s66, 0, 0x14000
	v_add_u32_e32 v108, s64, v228
	v_add_u32_e32 v156, s66, v228
	ds_read_b128 v[88:91], v108
	ds_read_b128 v[92:95], v108 offset:1024
	ds_read_b128 v[104:107], v108 offset:2048
	ds_read_b128 v[108:111], v108 offset:3072
	ds_read_b128 v[144:147], v156
	ds_read_b128 v[148:151], v156 offset:1024
	ds_read_b128 v[152:155], v156 offset:2048
	ds_read_b128 v[156:159], v156 offset:3072
	s_add_i32 m0, s7, 0xc000
	ds_read_b128 v[160:163], v232
	ds_read_b128 v[164:167], v232 offset:1024
	ds_read_b128 v[168:171], v232 offset:2048
	ds_read_b128 v[172:175], v232 offset:3072
	ds_read_b128 v[194:197], v232 offset:4096
	ds_read_b128 v[198:201], v232 offset:5120
	ds_read_b128 v[202:205], v232 offset:6144
	ds_read_b128 v[206:209], v232 offset:7168
	global_load_lds_dwordx4 v192, s[4:5]
	s_add_i32 m0, s7, 0xe000
	s_nop 0
	global_load_lds_dwordx4 v190, s[4:5]
	s_waitcnt vmcnt(24)
	s_waitcnt lgkmcnt(0)
	s_barrier
	s_setprio 1
	v_mfma_f32_16x16x32_bf16 v[140:143], v[88:91], v[160:163], 0
	v_mfma_f32_16x16x32_bf16 v[136:139], v[104:107], v[160:163], 0
	v_mfma_f32_16x16x32_bf16 v[124:127], v[88:91], v[168:171], 0
	v_mfma_f32_16x16x32_bf16 v[120:123], v[104:107], v[168:171], 0
	v_mfma_f32_16x16x32_bf16 v[100:103], v[88:91], v[194:197], 0
	v_mfma_f32_16x16x32_bf16 v[96:99], v[104:107], v[194:197], 0
	v_mfma_f32_16x16x32_bf16 v[76:79], v[88:91], v[202:205], 0
	v_mfma_f32_16x16x32_bf16 v[72:75], v[104:107], v[202:205], 0
	v_mfma_f32_16x16x32_bf16 v[140:143], v[92:95], v[164:167], v[140:143]
	v_mfma_f32_16x16x32_bf16 v[136:139], v[108:111], v[164:167], v[136:139]
	v_mfma_f32_16x16x32_bf16 v[124:127], v[92:95], v[172:175], v[124:127]
	v_mfma_f32_16x16x32_bf16 v[120:123], v[108:111], v[172:175], v[120:123]
	v_mfma_f32_16x16x32_bf16 v[100:103], v[92:95], v[198:201], v[100:103]
	v_mfma_f32_16x16x32_bf16 v[96:99], v[108:111], v[198:201], v[96:99]
	v_mfma_f32_16x16x32_bf16 v[76:79], v[92:95], v[206:209], v[76:79]
	v_mfma_f32_16x16x32_bf16 v[72:75], v[108:111], v[206:209], v[72:75]
	v_mfma_f32_16x16x32_bf16 v[132:135], v[144:147], v[160:163], 0
	v_mfma_f32_16x16x32_bf16 v[128:131], v[152:155], v[160:163], 0
	v_mfma_f32_16x16x32_bf16 v[116:119], v[144:147], v[168:171], 0
	v_mfma_f32_16x16x32_bf16 v[112:115], v[152:155], v[168:171], 0
	v_mfma_f32_16x16x32_bf16 v[84:87], v[144:147], v[194:197], 0
	v_mfma_f32_16x16x32_bf16 v[80:83], v[152:155], v[194:197], 0
	v_mfma_f32_16x16x32_bf16 v[68:71], v[144:147], v[202:205], 0
	v_mfma_f32_16x16x32_bf16 v[64:67], v[152:155], v[202:205], 0
	v_mfma_f32_16x16x32_bf16 v[132:135], v[148:151], v[164:167], v[132:135]
	v_mfma_f32_16x16x32_bf16 v[128:131], v[156:159], v[164:167], v[128:131]
	v_mfma_f32_16x16x32_bf16 v[116:119], v[148:151], v[172:175], v[116:119]
	v_mfma_f32_16x16x32_bf16 v[112:115], v[156:159], v[172:175], v[112:115]
	s_setprio 2
	s_barrier
	v_mfma_f32_16x16x32_bf16 v[84:87], v[148:151], v[198:201], v[84:87]
	v_mfma_f32_16x16x32_bf16 v[80:83], v[156:159], v[198:201], v[80:83]
	v_mfma_f32_16x16x32_bf16 v[68:71], v[148:151], v[206:209], v[68:71]
	v_mfma_f32_16x16x32_bf16 v[64:67], v[156:159], v[206:209], v[64:67]
	s_setprio 0
	s_add_i32 s64, s64, s72
	s_add_u32 s98, s42, s34
	s_addc_u32 s99, s43, s35
	s_mov_b32 m0, s64
	ds_read_b128 v[160:163], v232 offset:16384
	ds_read_b128 v[164:167], v232 offset:17408
	ds_read_b128 v[168:171], v232 offset:18432
	ds_read_b128 v[172:175], v232 offset:19456
	ds_read_b128 v[194:197], v232 offset:20480
	ds_read_b128 v[198:201], v232 offset:21504
	ds_read_b128 v[202:205], v232 offset:22528
	ds_read_b128 v[206:209], v232 offset:23552
	global_load_lds_dwordx4 v184, s[42:43]
	s_add_i32 m0, s64, 0x2000
	s_add_u32 s64, s42, 0x40000
	s_addc_u32 s65, s43, 0
	s_add_i32 s66, s66, s72
	global_load_lds_dwordx4 v188, s[42:43]
	s_mov_b32 m0, s66
	s_nop 0
	global_load_lds_dwordx4 v184, s[64:65]
	s_add_i32 m0, s66, 0x2000
	s_nop 0
	global_load_lds_dwordx4 v188, s[64:65]
	s_add_u32 s100, s50, s34
	s_addc_u32 s101, s51, s35
	s_mov_b32 m0, s7
	s_nop 0
	global_load_lds_dwordx4 v182, s[50:51]
	s_mov_b32 m0, s73
	s_nop 0
	global_load_lds_dwordx4 v186, s[50:51]
	s_waitcnt vmcnt(8)
	s_waitcnt lgkmcnt(0)
	s_barrier
	s_setprio 1
	v_mfma_f32_16x16x32_bf16 v[60:63], v[88:91], v[160:163], 0
	v_mfma_f32_16x16x32_bf16 v[56:59], v[104:107], v[160:163], 0
	v_mfma_f32_16x16x32_bf16 v[44:47], v[88:91], v[168:171], 0
	v_mfma_f32_16x16x32_bf16 v[40:43], v[104:107], v[168:171], 0
	v_mfma_f32_16x16x32_bf16 v[28:31], v[88:91], v[194:197], 0
	v_mfma_f32_16x16x32_bf16 v[24:27], v[104:107], v[194:197], 0
	v_mfma_f32_16x16x32_bf16 v[12:15], v[88:91], v[202:205], 0
	v_mfma_f32_16x16x32_bf16 v[8:11], v[104:107], v[202:205], 0
	v_mfma_f32_16x16x32_bf16 v[60:63], v[92:95], v[164:167], v[60:63]
	v_mfma_f32_16x16x32_bf16 v[56:59], v[108:111], v[164:167], v[56:59]
	v_mfma_f32_16x16x32_bf16 v[44:47], v[92:95], v[172:175], v[44:47]
	v_mfma_f32_16x16x32_bf16 v[40:43], v[108:111], v[172:175], v[40:43]
	v_mfma_f32_16x16x32_bf16 v[28:31], v[92:95], v[198:201], v[28:31]
	v_mfma_f32_16x16x32_bf16 v[24:27], v[108:111], v[198:201], v[24:27]
	v_mfma_f32_16x16x32_bf16 v[12:15], v[92:95], v[206:209], v[12:15]
	v_mfma_f32_16x16x32_bf16 v[8:11], v[108:111], v[206:209], v[8:11]
	v_mfma_f32_16x16x32_bf16 v[52:55], v[144:147], v[160:163], 0
	v_mfma_f32_16x16x32_bf16 v[48:51], v[152:155], v[160:163], 0
	v_mfma_f32_16x16x32_bf16 v[36:39], v[144:147], v[168:171], 0
	v_mfma_f32_16x16x32_bf16 v[32:35], v[152:155], v[168:171], 0
	v_mfma_f32_16x16x32_bf16 v[20:23], v[144:147], v[194:197], 0
	v_mfma_f32_16x16x32_bf16 v[16:19], v[152:155], v[194:197], 0
	v_mfma_f32_16x16x32_bf16 v[4:7], v[144:147], v[202:205], 0
	v_mfma_f32_16x16x32_bf16 v[0:3], v[152:155], v[202:205], 0
	v_mfma_f32_16x16x32_bf16 v[52:55], v[148:151], v[164:167], v[52:55]
	v_mfma_f32_16x16x32_bf16 v[48:51], v[156:159], v[164:167], v[48:51]
	v_mfma_f32_16x16x32_bf16 v[36:39], v[148:151], v[172:175], v[36:39]
	v_mfma_f32_16x16x32_bf16 v[32:35], v[156:159], v[172:175], v[32:35]
	s_setprio 2
	s_barrier
	v_mfma_f32_16x16x32_bf16 v[20:23], v[148:151], v[198:201], v[20:23]
	v_mfma_f32_16x16x32_bf16 v[16:19], v[156:159], v[198:201], v[16:19]
	v_mfma_f32_16x16x32_bf16 v[4:7], v[148:151], v[206:209], v[4:7]
	v_mfma_f32_16x16x32_bf16 v[0:3], v[156:159], v[206:209], v[0:3]
	s_setprio 0
	s_add_i32 s64, 0, 0x18000
	s_add_i32 s65, 0, 0x1c000
	v_add_u32_e32 v108, s64, v228
	v_add_u32_e32 v156, s65, v228
	ds_read_b128 v[88:91], v108
	ds_read_b128 v[92:95], v108 offset:1024
	ds_read_b128 v[104:107], v108 offset:2048
	ds_read_b128 v[108:111], v108 offset:3072
	ds_read_b128 v[144:147], v156
	ds_read_b128 v[148:151], v156 offset:1024
	ds_read_b128 v[152:155], v156 offset:2048
	ds_read_b128 v[156:159], v156 offset:3072
	s_add_u32 s50, s50, 0x40000
	s_addc_u32 s51, s51, 0
	s_mov_b32 m0, s74
	ds_read_b128 v[160:163], v232 offset:32768
	ds_read_b128 v[164:167], v232 offset:33792
	ds_read_b128 v[168:171], v232 offset:34816
	ds_read_b128 v[172:175], v232 offset:35840
	ds_read_b128 v[194:197], v232 offset:36864
	ds_read_b128 v[198:201], v232 offset:37888
	ds_read_b128 v[202:205], v232 offset:38912
	ds_read_b128 v[206:209], v232 offset:39936
	global_load_lds_dwordx4 v182, s[50:51]
	s_mov_b32 m0, s75
	s_nop 0
	global_load_lds_dwordx4 v186, s[50:51]
	s_waitcnt vmcnt(8)
	s_waitcnt lgkmcnt(0)
	s_barrier
	s_setprio 1
	v_mfma_f32_16x16x32_bf16 v[140:143], v[88:91], v[160:163], v[140:143]
	v_mfma_f32_16x16x32_bf16 v[136:139], v[104:107], v[160:163], v[136:139]
	v_mfma_f32_16x16x32_bf16 v[124:127], v[88:91], v[168:171], v[124:127]
	v_mfma_f32_16x16x32_bf16 v[120:123], v[104:107], v[168:171], v[120:123]
	v_mfma_f32_16x16x32_bf16 v[100:103], v[88:91], v[194:197], v[100:103]
	v_mfma_f32_16x16x32_bf16 v[96:99], v[104:107], v[194:197], v[96:99]
	v_mfma_f32_16x16x32_bf16 v[76:79], v[88:91], v[202:205], v[76:79]
	v_mfma_f32_16x16x32_bf16 v[72:75], v[104:107], v[202:205], v[72:75]
	v_mfma_f32_16x16x32_bf16 v[140:143], v[92:95], v[164:167], v[140:143]
	v_mfma_f32_16x16x32_bf16 v[136:139], v[108:111], v[164:167], v[136:139]
	v_mfma_f32_16x16x32_bf16 v[124:127], v[92:95], v[172:175], v[124:127]
	v_mfma_f32_16x16x32_bf16 v[120:123], v[108:111], v[172:175], v[120:123]
	v_mfma_f32_16x16x32_bf16 v[100:103], v[92:95], v[198:201], v[100:103]
	v_mfma_f32_16x16x32_bf16 v[96:99], v[108:111], v[198:201], v[96:99]
	v_mfma_f32_16x16x32_bf16 v[76:79], v[92:95], v[206:209], v[76:79]
	v_mfma_f32_16x16x32_bf16 v[72:75], v[108:111], v[206:209], v[72:75]
	v_mfma_f32_16x16x32_bf16 v[132:135], v[144:147], v[160:163], v[132:135]
	v_mfma_f32_16x16x32_bf16 v[128:131], v[152:155], v[160:163], v[128:131]
	v_mfma_f32_16x16x32_bf16 v[116:119], v[144:147], v[168:171], v[116:119]
	v_mfma_f32_16x16x32_bf16 v[112:115], v[152:155], v[168:171], v[112:115]
	v_mfma_f32_16x16x32_bf16 v[84:87], v[144:147], v[194:197], v[84:87]
	v_mfma_f32_16x16x32_bf16 v[80:83], v[152:155], v[194:197], v[80:83]
	v_mfma_f32_16x16x32_bf16 v[68:71], v[144:147], v[202:205], v[68:71]
	v_mfma_f32_16x16x32_bf16 v[64:67], v[152:155], v[202:205], v[64:67]
	v_mfma_f32_16x16x32_bf16 v[132:135], v[148:151], v[164:167], v[132:135]
	v_mfma_f32_16x16x32_bf16 v[128:131], v[156:159], v[164:167], v[128:131]
	v_mfma_f32_16x16x32_bf16 v[116:119], v[148:151], v[172:175], v[116:119]
	v_mfma_f32_16x16x32_bf16 v[112:115], v[156:159], v[172:175], v[112:115]
	s_setprio 2
	s_barrier
	v_mfma_f32_16x16x32_bf16 v[84:87], v[148:151], v[198:201], v[84:87]
	v_mfma_f32_16x16x32_bf16 v[80:83], v[156:159], v[198:201], v[80:83]
	v_mfma_f32_16x16x32_bf16 v[68:71], v[148:151], v[206:209], v[68:71]
	v_mfma_f32_16x16x32_bf16 v[64:67], v[156:159], v[206:209], v[64:67]
	s_setprio 0
	s_add_i32 s50, s64, s72
	s_mov_b32 m0, s50
	ds_read_b128 v[160:163], v232 offset:49152
	ds_read_b128 v[164:167], v232 offset:50176
	ds_read_b128 v[168:171], v232 offset:51200
	ds_read_b128 v[172:175], v232 offset:52224
	ds_read_b128 v[194:197], v232 offset:53248
	ds_read_b128 v[198:201], v232 offset:54272
	ds_read_b128 v[202:205], v232 offset:55296
	ds_read_b128 v[206:209], v232 offset:56320
	global_load_lds_dwordx4 v184, s[98:99]
	s_add_i32 m0, s50, 0x2000
	s_add_u32 s42, s42, 0x40080
	s_addc_u32 s43, s43, 0
	s_add_i32 s50, s65, s72
	global_load_lds_dwordx4 v188, s[98:99]
	s_mov_b32 m0, s50
	s_nop 0
	global_load_lds_dwordx4 v184, s[42:43]
	s_add_i32 m0, s50, 0x2000
	s_nop 0
	global_load_lds_dwordx4 v188, s[42:43]
	s_mov_b32 m0, s81
	s_nop 0
	global_load_lds_dwordx4 v182, s[100:101]
	s_mov_b32 m0, s82
	s_nop 0
	global_load_lds_dwordx4 v186, s[100:101]
	s_waitcnt vmcnt(8)
	s_waitcnt lgkmcnt(0)
	s_barrier
	s_setprio 1
	v_mfma_f32_16x16x32_bf16 v[60:63], v[88:91], v[160:163], v[60:63]
	v_mfma_f32_16x16x32_bf16 v[56:59], v[104:107], v[160:163], v[56:59]
	v_mfma_f32_16x16x32_bf16 v[44:47], v[88:91], v[168:171], v[44:47]
	v_mfma_f32_16x16x32_bf16 v[40:43], v[104:107], v[168:171], v[40:43]
	v_mfma_f32_16x16x32_bf16 v[28:31], v[88:91], v[194:197], v[28:31]
	v_mfma_f32_16x16x32_bf16 v[24:27], v[104:107], v[194:197], v[24:27]
	v_mfma_f32_16x16x32_bf16 v[12:15], v[88:91], v[202:205], v[12:15]
	v_mfma_f32_16x16x32_bf16 v[8:11], v[104:107], v[202:205], v[8:11]
	v_mfma_f32_16x16x32_bf16 v[60:63], v[92:95], v[164:167], v[60:63]
	v_mfma_f32_16x16x32_bf16 v[56:59], v[108:111], v[164:167], v[56:59]
	v_mfma_f32_16x16x32_bf16 v[44:47], v[92:95], v[172:175], v[44:47]
	v_mfma_f32_16x16x32_bf16 v[40:43], v[108:111], v[172:175], v[40:43]
	v_mfma_f32_16x16x32_bf16 v[28:31], v[92:95], v[198:201], v[28:31]
	v_mfma_f32_16x16x32_bf16 v[24:27], v[108:111], v[198:201], v[24:27]
	v_mfma_f32_16x16x32_bf16 v[12:15], v[92:95], v[206:209], v[12:15]
	v_mfma_f32_16x16x32_bf16 v[8:11], v[108:111], v[206:209], v[8:11]
	v_mfma_f32_16x16x32_bf16 v[52:55], v[144:147], v[160:163], v[52:55]
	v_mfma_f32_16x16x32_bf16 v[48:51], v[152:155], v[160:163], v[48:51]
	v_mfma_f32_16x16x32_bf16 v[36:39], v[144:147], v[168:171], v[36:39]
	v_mfma_f32_16x16x32_bf16 v[32:35], v[152:155], v[168:171], v[32:35]
	v_mfma_f32_16x16x32_bf16 v[20:23], v[144:147], v[194:197], v[20:23]
	v_mfma_f32_16x16x32_bf16 v[16:19], v[152:155], v[194:197], v[16:19]
	v_mfma_f32_16x16x32_bf16 v[4:7], v[144:147], v[202:205], v[4:7]
	v_mfma_f32_16x16x32_bf16 v[0:3], v[152:155], v[202:205], v[0:3]
	v_mfma_f32_16x16x32_bf16 v[52:55], v[148:151], v[164:167], v[52:55]
	v_mfma_f32_16x16x32_bf16 v[48:51], v[156:159], v[164:167], v[48:51]
	v_mfma_f32_16x16x32_bf16 v[36:39], v[148:151], v[172:175], v[36:39]
	v_mfma_f32_16x16x32_bf16 v[32:35], v[156:159], v[172:175], v[32:35]
	s_setprio 2
	s_barrier
	v_mfma_f32_16x16x32_bf16 v[20:23], v[148:151], v[198:201], v[20:23]
	v_mfma_f32_16x16x32_bf16 v[16:19], v[156:159], v[198:201], v[16:19]
	v_mfma_f32_16x16x32_bf16 v[4:7], v[148:151], v[206:209], v[4:7]
	v_mfma_f32_16x16x32_bf16 v[0:3], v[156:159], v[206:209], v[0:3]
	s_setprio 0
	s_add_u32 s95, s95, 0x100
	s_addc_u32 vcc_lo, vcc_lo, 0
	s_add_u32 s4, s4, 0x100
	s_addc_u32 s5, s5, 0
	s_cmp_ge_i32 vcc_hi, s52
	s_mov_b32 s42, vcc_hi
	s_cbranch_scc1 .Lpeel_exit_6
.LBB0_1222:
	s_add_i32 vcc_hi, s42, 2
	s_add_u32 s43, s4, 0xfffc0080
	s_addc_u32 s50, s5, -1
	s_add_i32 s64, 0, 0x10000
	s_cmp_eq_u32 s63, s42
	s_cselect_b32 s51, s21, s50
	s_cselect_b32 s50, s23, s43
	s_cselect_b32 s43, s27, vcc_lo
	s_cselect_b32 s42, s53, s95
	s_add_i32 s66, 0, 0x14000
	v_add_u32_e32 v108, s64, v228
	v_add_u32_e32 v156, s66, v228
	ds_read_b128 v[88:91], v108
	ds_read_b128 v[92:95], v108 offset:1024
	ds_read_b128 v[104:107], v108 offset:2048
	ds_read_b128 v[108:111], v108 offset:3072
	ds_read_b128 v[144:147], v156
	ds_read_b128 v[148:151], v156 offset:1024
	ds_read_b128 v[152:155], v156 offset:2048
	ds_read_b128 v[156:159], v156 offset:3072
	s_add_i32 m0, s7, 0xc000
	ds_read_b128 v[160:163], v232
	ds_read_b128 v[164:167], v232 offset:1024
	ds_read_b128 v[168:171], v232 offset:2048
	ds_read_b128 v[172:175], v232 offset:3072
	ds_read_b128 v[194:197], v232 offset:4096
	ds_read_b128 v[198:201], v232 offset:5120
	ds_read_b128 v[202:205], v232 offset:6144
	ds_read_b128 v[206:209], v232 offset:7168
	global_load_lds_dwordx4 v192, s[4:5]
	s_add_i32 m0, s7, 0xe000
	s_nop 0
	global_load_lds_dwordx4 v190, s[4:5]
	s_waitcnt vmcnt(8)
	s_waitcnt lgkmcnt(0)
	s_barrier
	s_setprio 1
	v_mfma_f32_16x16x32_bf16 v[140:143], v[88:91], v[160:163], v[140:143]
	v_mfma_f32_16x16x32_bf16 v[136:139], v[104:107], v[160:163], v[136:139]
	v_mfma_f32_16x16x32_bf16 v[124:127], v[88:91], v[168:171], v[124:127]
	v_mfma_f32_16x16x32_bf16 v[120:123], v[104:107], v[168:171], v[120:123]
	v_mfma_f32_16x16x32_bf16 v[100:103], v[88:91], v[194:197], v[100:103]
	v_mfma_f32_16x16x32_bf16 v[96:99], v[104:107], v[194:197], v[96:99]
	v_mfma_f32_16x16x32_bf16 v[76:79], v[88:91], v[202:205], v[76:79]
	v_mfma_f32_16x16x32_bf16 v[72:75], v[104:107], v[202:205], v[72:75]
	v_mfma_f32_16x16x32_bf16 v[140:143], v[92:95], v[164:167], v[140:143]
	v_mfma_f32_16x16x32_bf16 v[136:139], v[108:111], v[164:167], v[136:139]
	v_mfma_f32_16x16x32_bf16 v[124:127], v[92:95], v[172:175], v[124:127]
	v_mfma_f32_16x16x32_bf16 v[120:123], v[108:111], v[172:175], v[120:123]
	v_mfma_f32_16x16x32_bf16 v[100:103], v[92:95], v[198:201], v[100:103]
	v_mfma_f32_16x16x32_bf16 v[96:99], v[108:111], v[198:201], v[96:99]
	v_mfma_f32_16x16x32_bf16 v[76:79], v[92:95], v[206:209], v[76:79]
	v_mfma_f32_16x16x32_bf16 v[72:75], v[108:111], v[206:209], v[72:75]
	v_mfma_f32_16x16x32_bf16 v[132:135], v[144:147], v[160:163], v[132:135]
	v_mfma_f32_16x16x32_bf16 v[128:131], v[152:155], v[160:163], v[128:131]
	v_mfma_f32_16x16x32_bf16 v[116:119], v[144:147], v[168:171], v[116:119]
	v_mfma_f32_16x16x32_bf16 v[112:115], v[152:155], v[168:171], v[112:115]
	v_mfma_f32_16x16x32_bf16 v[84:87], v[144:147], v[194:197], v[84:87]
	v_mfma_f32_16x16x32_bf16 v[80:83], v[152:155], v[194:197], v[80:83]
	v_mfma_f32_16x16x32_bf16 v[68:71], v[144:147], v[202:205], v[68:71]
	v_mfma_f32_16x16x32_bf16 v[64:67], v[152:155], v[202:205], v[64:67]
	v_mfma_f32_16x16x32_bf16 v[132:135], v[148:151], v[164:167], v[132:135]
	v_mfma_f32_16x16x32_bf16 v[128:131], v[156:159], v[164:167], v[128:131]
	v_mfma_f32_16x16x32_bf16 v[116:119], v[148:151], v[172:175], v[116:119]
	v_mfma_f32_16x16x32_bf16 v[112:115], v[156:159], v[172:175], v[112:115]
	s_setprio 2
	s_barrier
	v_mfma_f32_16x16x32_bf16 v[84:87], v[148:151], v[198:201], v[84:87]
	v_mfma_f32_16x16x32_bf16 v[80:83], v[156:159], v[198:201], v[80:83]
	v_mfma_f32_16x16x32_bf16 v[68:71], v[148:151], v[206:209], v[68:71]
	v_mfma_f32_16x16x32_bf16 v[64:67], v[156:159], v[206:209], v[64:67]
	s_setprio 0
	s_add_i32 s64, s64, s72
	s_add_u32 s98, s42, s34
	s_addc_u32 s99, s43, s35
	s_mov_b32 m0, s64
	ds_read_b128 v[160:163], v232 offset:16384
	ds_read_b128 v[164:167], v232 offset:17408
	ds_read_b128 v[168:171], v232 offset:18432
	ds_read_b128 v[172:175], v232 offset:19456
	ds_read_b128 v[194:197], v232 offset:20480
	ds_read_b128 v[198:201], v232 offset:21504
	ds_read_b128 v[202:205], v232 offset:22528
	ds_read_b128 v[206:209], v232 offset:23552
	global_load_lds_dwordx4 v184, s[42:43]
	s_add_i32 m0, s64, 0x2000
	s_add_u32 s64, s42, 0x40000
	s_addc_u32 s65, s43, 0
	s_add_i32 s66, s66, s72
	global_load_lds_dwordx4 v188, s[42:43]
	s_mov_b32 m0, s66
	s_nop 0
	global_load_lds_dwordx4 v184, s[64:65]
	s_add_i32 m0, s66, 0x2000
	s_nop 0
	global_load_lds_dwordx4 v188, s[64:65]
	s_add_u32 s100, s50, s34
	s_addc_u32 s101, s51, s35
	s_mov_b32 m0, s7
	s_nop 0
	global_load_lds_dwordx4 v182, s[50:51]
	s_mov_b32 m0, s73
	s_nop 0
	global_load_lds_dwordx4 v186, s[50:51]
	s_waitcnt vmcnt(8)
	s_waitcnt lgkmcnt(0)
	s_barrier
	s_setprio 1
	v_mfma_f32_16x16x32_bf16 v[60:63], v[88:91], v[160:163], v[60:63]
	v_mfma_f32_16x16x32_bf16 v[56:59], v[104:107], v[160:163], v[56:59]
	v_mfma_f32_16x16x32_bf16 v[44:47], v[88:91], v[168:171], v[44:47]
	v_mfma_f32_16x16x32_bf16 v[40:43], v[104:107], v[168:171], v[40:43]
	v_mfma_f32_16x16x32_bf16 v[28:31], v[88:91], v[194:197], v[28:31]
	v_mfma_f32_16x16x32_bf16 v[24:27], v[104:107], v[194:197], v[24:27]
	v_mfma_f32_16x16x32_bf16 v[12:15], v[88:91], v[202:205], v[12:15]
	v_mfma_f32_16x16x32_bf16 v[8:11], v[104:107], v[202:205], v[8:11]
	v_mfma_f32_16x16x32_bf16 v[60:63], v[92:95], v[164:167], v[60:63]
	v_mfma_f32_16x16x32_bf16 v[56:59], v[108:111], v[164:167], v[56:59]
	v_mfma_f32_16x16x32_bf16 v[44:47], v[92:95], v[172:175], v[44:47]
	v_mfma_f32_16x16x32_bf16 v[40:43], v[108:111], v[172:175], v[40:43]
	v_mfma_f32_16x16x32_bf16 v[28:31], v[92:95], v[198:201], v[28:31]
	v_mfma_f32_16x16x32_bf16 v[24:27], v[108:111], v[198:201], v[24:27]
	v_mfma_f32_16x16x32_bf16 v[12:15], v[92:95], v[206:209], v[12:15]
	v_mfma_f32_16x16x32_bf16 v[8:11], v[108:111], v[206:209], v[8:11]
	v_mfma_f32_16x16x32_bf16 v[52:55], v[144:147], v[160:163], v[52:55]
	v_mfma_f32_16x16x32_bf16 v[48:51], v[152:155], v[160:163], v[48:51]
	v_mfma_f32_16x16x32_bf16 v[36:39], v[144:147], v[168:171], v[36:39]
	v_mfma_f32_16x16x32_bf16 v[32:35], v[152:155], v[168:171], v[32:35]
	v_mfma_f32_16x16x32_bf16 v[20:23], v[144:147], v[194:197], v[20:23]
	v_mfma_f32_16x16x32_bf16 v[16:19], v[152:155], v[194:197], v[16:19]
	v_mfma_f32_16x16x32_bf16 v[4:7], v[144:147], v[202:205], v[4:7]
	v_mfma_f32_16x16x32_bf16 v[0:3], v[152:155], v[202:205], v[0:3]
	v_mfma_f32_16x16x32_bf16 v[52:55], v[148:151], v[164:167], v[52:55]
	v_mfma_f32_16x16x32_bf16 v[48:51], v[156:159], v[164:167], v[48:51]
	v_mfma_f32_16x16x32_bf16 v[36:39], v[148:151], v[172:175], v[36:39]
	v_mfma_f32_16x16x32_bf16 v[32:35], v[156:159], v[172:175], v[32:35]
	s_setprio 2
	s_barrier
	v_mfma_f32_16x16x32_bf16 v[20:23], v[148:151], v[198:201], v[20:23]
	v_mfma_f32_16x16x32_bf16 v[16:19], v[156:159], v[198:201], v[16:19]
	v_mfma_f32_16x16x32_bf16 v[4:7], v[148:151], v[206:209], v[4:7]
	v_mfma_f32_16x16x32_bf16 v[0:3], v[156:159], v[206:209], v[0:3]
	s_setprio 0
	s_add_i32 s64, 0, 0x18000
	s_add_i32 s65, 0, 0x1c000
	v_add_u32_e32 v108, s64, v228
	v_add_u32_e32 v156, s65, v228
	ds_read_b128 v[88:91], v108
	ds_read_b128 v[92:95], v108 offset:1024
	ds_read_b128 v[104:107], v108 offset:2048
	ds_read_b128 v[108:111], v108 offset:3072
	ds_read_b128 v[144:147], v156
	ds_read_b128 v[148:151], v156 offset:1024
	ds_read_b128 v[152:155], v156 offset:2048
	ds_read_b128 v[156:159], v156 offset:3072
	s_add_u32 s50, s50, 0x40000
	s_addc_u32 s51, s51, 0
	s_mov_b32 m0, s74
	ds_read_b128 v[160:163], v232 offset:32768
	ds_read_b128 v[164:167], v232 offset:33792
	ds_read_b128 v[168:171], v232 offset:34816
	ds_read_b128 v[172:175], v232 offset:35840
	ds_read_b128 v[194:197], v232 offset:36864
	ds_read_b128 v[198:201], v232 offset:37888
	ds_read_b128 v[202:205], v232 offset:38912
	ds_read_b128 v[206:209], v232 offset:39936
	global_load_lds_dwordx4 v182, s[50:51]
	s_mov_b32 m0, s75
	s_nop 0
	global_load_lds_dwordx4 v186, s[50:51]
	s_waitcnt vmcnt(8)
	s_waitcnt lgkmcnt(0)
	s_barrier
	s_setprio 1
	v_mfma_f32_16x16x32_bf16 v[140:143], v[88:91], v[160:163], v[140:143]
	v_mfma_f32_16x16x32_bf16 v[136:139], v[104:107], v[160:163], v[136:139]
	v_mfma_f32_16x16x32_bf16 v[124:127], v[88:91], v[168:171], v[124:127]
	v_mfma_f32_16x16x32_bf16 v[120:123], v[104:107], v[168:171], v[120:123]
	v_mfma_f32_16x16x32_bf16 v[100:103], v[88:91], v[194:197], v[100:103]
	v_mfma_f32_16x16x32_bf16 v[96:99], v[104:107], v[194:197], v[96:99]
	v_mfma_f32_16x16x32_bf16 v[76:79], v[88:91], v[202:205], v[76:79]
	v_mfma_f32_16x16x32_bf16 v[72:75], v[104:107], v[202:205], v[72:75]
	v_mfma_f32_16x16x32_bf16 v[140:143], v[92:95], v[164:167], v[140:143]
	v_mfma_f32_16x16x32_bf16 v[136:139], v[108:111], v[164:167], v[136:139]
	v_mfma_f32_16x16x32_bf16 v[124:127], v[92:95], v[172:175], v[124:127]
	v_mfma_f32_16x16x32_bf16 v[120:123], v[108:111], v[172:175], v[120:123]
	v_mfma_f32_16x16x32_bf16 v[100:103], v[92:95], v[198:201], v[100:103]
	v_mfma_f32_16x16x32_bf16 v[96:99], v[108:111], v[198:201], v[96:99]
	v_mfma_f32_16x16x32_bf16 v[76:79], v[92:95], v[206:209], v[76:79]
	v_mfma_f32_16x16x32_bf16 v[72:75], v[108:111], v[206:209], v[72:75]
	v_mfma_f32_16x16x32_bf16 v[132:135], v[144:147], v[160:163], v[132:135]
	v_mfma_f32_16x16x32_bf16 v[128:131], v[152:155], v[160:163], v[128:131]
	v_mfma_f32_16x16x32_bf16 v[116:119], v[144:147], v[168:171], v[116:119]
	v_mfma_f32_16x16x32_bf16 v[112:115], v[152:155], v[168:171], v[112:115]
	v_mfma_f32_16x16x32_bf16 v[84:87], v[144:147], v[194:197], v[84:87]
	v_mfma_f32_16x16x32_bf16 v[80:83], v[152:155], v[194:197], v[80:83]
	v_mfma_f32_16x16x32_bf16 v[68:71], v[144:147], v[202:205], v[68:71]
	v_mfma_f32_16x16x32_bf16 v[64:67], v[152:155], v[202:205], v[64:67]
	v_mfma_f32_16x16x32_bf16 v[132:135], v[148:151], v[164:167], v[132:135]
	v_mfma_f32_16x16x32_bf16 v[128:131], v[156:159], v[164:167], v[128:131]
	v_mfma_f32_16x16x32_bf16 v[116:119], v[148:151], v[172:175], v[116:119]
	v_mfma_f32_16x16x32_bf16 v[112:115], v[156:159], v[172:175], v[112:115]
	s_setprio 2
	s_barrier
	v_mfma_f32_16x16x32_bf16 v[84:87], v[148:151], v[198:201], v[84:87]
	v_mfma_f32_16x16x32_bf16 v[80:83], v[156:159], v[198:201], v[80:83]
	v_mfma_f32_16x16x32_bf16 v[68:71], v[148:151], v[206:209], v[68:71]
	v_mfma_f32_16x16x32_bf16 v[64:67], v[156:159], v[206:209], v[64:67]
	s_setprio 0
	s_add_i32 s50, s64, s72
	s_mov_b32 m0, s50
	ds_read_b128 v[160:163], v232 offset:49152
	ds_read_b128 v[164:167], v232 offset:50176
	ds_read_b128 v[168:171], v232 offset:51200
	ds_read_b128 v[172:175], v232 offset:52224
	ds_read_b128 v[194:197], v232 offset:53248
	ds_read_b128 v[198:201], v232 offset:54272
	ds_read_b128 v[202:205], v232 offset:55296
	ds_read_b128 v[206:209], v232 offset:56320
	global_load_lds_dwordx4 v184, s[98:99]
	s_add_i32 m0, s50, 0x2000
	s_add_u32 s42, s42, 0x40080
	s_addc_u32 s43, s43, 0
	s_add_i32 s50, s65, s72
	global_load_lds_dwordx4 v188, s[98:99]
	s_mov_b32 m0, s50
	s_nop 0
	global_load_lds_dwordx4 v184, s[42:43]
	s_add_i32 m0, s50, 0x2000
	s_nop 0
	global_load_lds_dwordx4 v188, s[42:43]
	s_mov_b32 m0, s81
	s_nop 0
	global_load_lds_dwordx4 v182, s[100:101]
	s_mov_b32 m0, s82
	s_nop 0
	global_load_lds_dwordx4 v186, s[100:101]
	s_waitcnt vmcnt(8)
	s_waitcnt lgkmcnt(0)
	s_barrier
	s_setprio 1
	v_mfma_f32_16x16x32_bf16 v[60:63], v[88:91], v[160:163], v[60:63]
	v_mfma_f32_16x16x32_bf16 v[56:59], v[104:107], v[160:163], v[56:59]
	v_mfma_f32_16x16x32_bf16 v[44:47], v[88:91], v[168:171], v[44:47]
	v_mfma_f32_16x16x32_bf16 v[40:43], v[104:107], v[168:171], v[40:43]
	v_mfma_f32_16x16x32_bf16 v[28:31], v[88:91], v[194:197], v[28:31]
	v_mfma_f32_16x16x32_bf16 v[24:27], v[104:107], v[194:197], v[24:27]
	v_mfma_f32_16x16x32_bf16 v[12:15], v[88:91], v[202:205], v[12:15]
	v_mfma_f32_16x16x32_bf16 v[8:11], v[104:107], v[202:205], v[8:11]
	v_mfma_f32_16x16x32_bf16 v[60:63], v[92:95], v[164:167], v[60:63]
	v_mfma_f32_16x16x32_bf16 v[56:59], v[108:111], v[164:167], v[56:59]
	v_mfma_f32_16x16x32_bf16 v[44:47], v[92:95], v[172:175], v[44:47]
	v_mfma_f32_16x16x32_bf16 v[40:43], v[108:111], v[172:175], v[40:43]
	v_mfma_f32_16x16x32_bf16 v[28:31], v[92:95], v[198:201], v[28:31]
	v_mfma_f32_16x16x32_bf16 v[24:27], v[108:111], v[198:201], v[24:27]
	v_mfma_f32_16x16x32_bf16 v[12:15], v[92:95], v[206:209], v[12:15]
	v_mfma_f32_16x16x32_bf16 v[8:11], v[108:111], v[206:209], v[8:11]
	v_mfma_f32_16x16x32_bf16 v[52:55], v[144:147], v[160:163], v[52:55]
	v_mfma_f32_16x16x32_bf16 v[48:51], v[152:155], v[160:163], v[48:51]
	v_mfma_f32_16x16x32_bf16 v[36:39], v[144:147], v[168:171], v[36:39]
	v_mfma_f32_16x16x32_bf16 v[32:35], v[152:155], v[168:171], v[32:35]
	v_mfma_f32_16x16x32_bf16 v[20:23], v[144:147], v[194:197], v[20:23]
	v_mfma_f32_16x16x32_bf16 v[16:19], v[152:155], v[194:197], v[16:19]
	v_mfma_f32_16x16x32_bf16 v[4:7], v[144:147], v[202:205], v[4:7]
	v_mfma_f32_16x16x32_bf16 v[0:3], v[152:155], v[202:205], v[0:3]
	v_mfma_f32_16x16x32_bf16 v[52:55], v[148:151], v[164:167], v[52:55]
	v_mfma_f32_16x16x32_bf16 v[48:51], v[156:159], v[164:167], v[48:51]
	v_mfma_f32_16x16x32_bf16 v[36:39], v[148:151], v[172:175], v[36:39]
	v_mfma_f32_16x16x32_bf16 v[32:35], v[156:159], v[172:175], v[32:35]
	s_setprio 2
	s_barrier
	v_mfma_f32_16x16x32_bf16 v[20:23], v[148:151], v[198:201], v[20:23]
	v_mfma_f32_16x16x32_bf16 v[16:19], v[156:159], v[198:201], v[16:19]
	v_mfma_f32_16x16x32_bf16 v[4:7], v[148:151], v[206:209], v[4:7]
	v_mfma_f32_16x16x32_bf16 v[0:3], v[156:159], v[206:209], v[0:3]
	s_setprio 0
	s_add_u32 s95, s95, 0x100
	s_addc_u32 vcc_lo, vcc_lo, 0
	s_add_u32 s4, s4, 0x100
	s_addc_u32 s5, s5, 0
	s_cmp_ge_i32 vcc_hi, s52
	s_mov_b32 s42, vcc_hi
	s_cbranch_scc0 .LBB0_1222
